# grid barrier after phases 4,5,8,12,13,16 replaced by a 4-workgroup panel barrier (write-through stores, per-panel device counter, buffer_inv on the consumer); A-operand dependencies on these seams are
# baseline (speedup 1.0000x reference)
.LBB0_33:
	v_rcp_f32_e32 v98, v67
	v_lshlrev_b32_e32 v67, 2, v145
	v_rcp_f32_e32 v94, v69
	v_rcp_f32_e32 v90, v71
	v_rcp_f32_e32 v86, v73
	global_load_dword v69, v67, s[50:51]
	global_load_dword v71, v67, s[50:51] offset:128
	global_load_dword v73, v67, s[50:51] offset:256
	v_readlane_b32 s4, v251, 48
	global_load_dword v67, v67, s[50:51] offset:384
	v_rcp_f32_e32 v88, v72
	v_rcp_f32_e32 v72, v77
	v_rcp_f32_e32 v96, v68
	v_rcp_f32_e32 v68, v79
	v_rcp_f32_e32 v84, v74
	v_rcp_f32_e32 v82, v75
	v_rcp_f32_e32 v100, v66
	v_mov_b32_e32 v106, v34
	v_mov_b32_e32 v107, v18
	s_mov_b32 s10, 0x800000
	v_rcp_f32_e32 v66, v80
	v_ashrrev_i32_e32 v80, 3, v172
	v_rcp_f32_e32 v92, v70
	v_rcp_f32_e32 v70, v78
	v_rcp_f32_e32 v0, v81
	v_and_b32_e32 v81, 0xffffffc, v80
	v_rcp_f32_e32 v76, v76
	s_waitcnt vmcnt(3)
	v_mul_f32_e32 v69, 0x3f24fd5c, v69
	s_waitcnt vmcnt(2)
	v_mul_f32_e32 v71, 0x3f24fd5c, v71
	s_waitcnt vmcnt(1)
	v_mul_f32_e32 v73, 0x3f24fd5c, v73
	s_waitcnt vmcnt(0)
	v_mul_f32_e32 v77, 0x3f24fd5c, v67
	v_mov_b32_e32 v67, s4
	s_nop 0
	v_add_u32_e32 v79, 0, v160
	ds_read2st64_b32 v[74:75], v79 offset1:1
	v_add_u32_e32 v67, 0, v67
	v_lshl_add_u32 v78, v145, 1, v67
	s_waitcnt lgkmcnt(0)
	v_lshlrev_b32_e32 v102, 16, v74
	v_and_b32_e32 v103, 0xffff0000, v74
	v_lshlrev_b32_e32 v105, 16, v75
	v_and_b32_e32 v104, 0xffff0000, v75
	v_mov_b32_e32 v74, v2
	v_mov_b32_e32 v75, v50
	v_pk_mul_f32 v[74:75], v[74:75], v[100:101] op_sel_hi:[1,0]
	v_pk_mul_f32 v[100:101], v[106:107], v[100:101] op_sel_hi:[1,0]
	v_pk_fma_f32 v[102:103], v[142:143], v[74:75], v[102:103] neg_lo:[1,0,0] neg_hi:[1,0,0]
	v_pk_fma_f32 v[100:101], v[142:143], v[100:101], v[104:105] neg_lo:[1,0,0] neg_hi:[1,0,0]
	v_pk_mul_f32 v[74:75], v[102:103], v[102:103]
	v_pk_mul_f32 v[104:105], v[100:101], v[100:101]
	v_add_f32_e32 v2, v74, v75
	v_add_f32_e32 v2, v2, v105
	v_add_f32_e32 v2, v104, v2
	v_mad_u64_u32 v[74:75], s[4:5], v81, s77, v[78:79]
	s_waitcnt lgkmcnt(0)
	s_nop 1
	v_add_f32_dpp v2, v2, v2 quad_perm:[1,0,3,2] row_mask:0xf bank_mask:0xf
	s_waitcnt lgkmcnt(0)
	s_nop 1
	v_add_f32_dpp v2, v2, v2 quad_perm:[2,3,0,1] row_mask:0xf bank_mask:0xf
	s_waitcnt lgkmcnt(0)
	s_nop 1
	v_add_f32_dpp v2, v2, v2 row_half_mirror row_mask:0xf bank_mask:0xf
	s_waitcnt lgkmcnt(0)
	s_nop 1
	v_add_f32_dpp v2, v2, v2 row_mirror row_mask:0xf bank_mask:0xf
	ds_bpermute_b32 v18, v170, v2
	s_waitcnt lgkmcnt(0)
	v_add_f32_e32 v2, v2, v18
	v_fmamk_f32 v2, v2, 0x3c000000, v249
	v_cmp_gt_f32_e32 vcc, s10, v2
	v_mul_f32_e32 v18, 0x4b800000, v2
	s_nop 0
	v_cndmask_b32_e32 v2, v2, v18, vcc
	v_rsq_f32_e32 v2, v2
	s_nop 0
	v_mul_f32_e32 v18, 0x45800000, v2
	v_cndmask_b32_e32 v2, v2, v18, vcc
	v_mul_f32_e32 v18, v102, v2
	v_mul_f32_e32 v18, v69, v18
	v_cvt_pk_bf16_f32 v18, v18, s0
	ds_write_b16 v74, v18
	v_mul_f32_e32 v18, v103, v2
	v_mul_f32_e32 v18, v71, v18
	v_cvt_pk_bf16_f32 v18, v18, s0
	ds_write_b16 v74, v18 offset:64
	v_mul_f32_e32 v18, v101, v2
	v_mul_f32_e32 v2, v100, v2
	v_mul_f32_e32 v18, v73, v18
	v_mul_f32_e32 v2, v77, v2
	v_cvt_pk_bf16_f32 v18, v18, s0
	v_cvt_pk_bf16_f32 v2, v2, s0
	ds_write_b16 v74, v18 offset:128
	ds_write_b16 v74, v2 offset:192
	ds_read2st64_b32 v[100:101], v79 offset0:2 offset1:3
	v_mov_b32_e32 v50, v3
	v_pk_mul_f32 v[50:51], v[50:51], v[98:99] op_sel_hi:[1,0]
	v_mov_b32_e32 v18, v35
	v_pk_mul_f32 v[18:19], v[18:19], v[98:99] op_sel_hi:[1,0]
	s_waitcnt lgkmcnt(0)
	v_lshlrev_b32_e32 v2, 16, v100
	v_and_b32_e32 v3, 0xffff0000, v100
	v_lshlrev_b32_e32 v103, 16, v101
	v_and_b32_e32 v102, 0xffff0000, v101
	v_pk_fma_f32 v[2:3], v[142:143], v[50:51], v[2:3] neg_lo:[1,0,0] neg_hi:[1,0,0]
	v_pk_fma_f32 v[18:19], v[142:143], v[18:19], v[102:103] neg_lo:[1,0,0] neg_hi:[1,0,0]
	v_pk_mul_f32 v[50:51], v[2:3], v[2:3]
	v_pk_mul_f32 v[34:35], v[18:19], v[18:19]
	v_add_f32_e32 v50, v50, v51
	v_add_f32_e32 v35, v50, v35
	v_add_f32_e32 v34, v34, v35
	s_waitcnt lgkmcnt(0)
	s_nop 1
	v_add_f32_dpp v34, v34, v34 quad_perm:[1,0,3,2] row_mask:0xf bank_mask:0xf
	s_waitcnt lgkmcnt(0)
	s_nop 1
	v_add_f32_dpp v34, v34, v34 quad_perm:[2,3,0,1] row_mask:0xf bank_mask:0xf
	s_waitcnt lgkmcnt(0)
	s_nop 1
	v_add_f32_dpp v34, v34, v34 row_half_mirror row_mask:0xf bank_mask:0xf
	s_waitcnt lgkmcnt(0)
	s_nop 1
	v_add_f32_dpp v34, v34, v34 row_mirror row_mask:0xf bank_mask:0xf
	ds_bpermute_b32 v35, v170, v34
	s_waitcnt lgkmcnt(0)
	v_add_f32_e32 v34, v34, v35
	v_fmamk_f32 v34, v34, 0x3c000000, v249
	v_mul_f32_e32 v35, 0x4b800000, v34
	v_cmp_gt_f32_e32 vcc, s10, v34
	s_nop 1
	v_cndmask_b32_e32 v34, v34, v35, vcc
	v_rsq_f32_e32 v34, v34
	s_nop 0
	v_mul_f32_e32 v35, 0x45800000, v34
	v_cndmask_b32_e32 v34, v34, v35, vcc
	v_mul_f32_e32 v2, v2, v34
	v_mul_f32_e32 v3, v3, v34
	v_mul_f32_e32 v19, v19, v34
	v_mul_f32_e32 v18, v18, v34
	v_mul_f32_e32 v2, v69, v2
	v_mul_f32_e32 v3, v71, v3
	v_mul_f32_e32 v19, v73, v19
	v_mul_f32_e32 v18, v77, v18
	v_cvt_pk_bf16_f32 v2, v2, s0
	v_cvt_pk_bf16_f32 v3, v3, s0
	v_cvt_pk_bf16_f32 v19, v19, s0
	v_cvt_pk_bf16_f32 v18, v18, s0
	ds_write_b16 v74, v2 offset:272
	ds_write_b16 v74, v3 offset:336
	ds_write_b16 v74, v19 offset:400
	ds_write_b16 v74, v18 offset:464
	ds_read2st64_b32 v[2:3], v79 offset0:4 offset1:5
	v_mov_b32_e32 v18, v4
	v_mov_b32_e32 v19, v52
	s_waitcnt lgkmcnt(0)
	v_lshlrev_b32_e32 v34, 16, v2
	v_and_b32_e32 v35, 0xffff0000, v2
	v_lshlrev_b32_e32 v51, 16, v3
	v_and_b32_e32 v50, 0xffff0000, v3
	v_pk_mul_f32 v[2:3], v[18:19], v[96:97] op_sel_hi:[1,0]
	s_nop 0
	v_pk_fma_f32 v[2:3], v[142:143], v[2:3], v[34:35] neg_lo:[1,0,0] neg_hi:[1,0,0]
	v_mov_b32_e32 v34, v36
	v_mov_b32_e32 v35, v20
	v_pk_mul_f32 v[34:35], v[34:35], v[96:97] op_sel_hi:[1,0]
	v_pk_mul_f32 v[18:19], v[2:3], v[2:3]
	v_pk_fma_f32 v[34:35], v[142:143], v[34:35], v[50:51] neg_lo:[1,0,0] neg_hi:[1,0,0]
	v_add_f32_e32 v4, v18, v19
	v_pk_mul_f32 v[50:51], v[34:35], v[34:35]
	s_nop 0
	v_add_f32_e32 v4, v4, v51
	v_add_f32_e32 v4, v50, v4
	s_waitcnt lgkmcnt(0)
	s_nop 1
	v_add_f32_dpp v4, v4, v4 quad_perm:[1,0,3,2] row_mask:0xf bank_mask:0xf
	s_waitcnt lgkmcnt(0)
	s_nop 1
	v_add_f32_dpp v4, v4, v4 quad_perm:[2,3,0,1] row_mask:0xf bank_mask:0xf
	s_waitcnt lgkmcnt(0)
	s_nop 1
	v_add_f32_dpp v4, v4, v4 row_half_mirror row_mask:0xf bank_mask:0xf
	s_waitcnt lgkmcnt(0)
	s_nop 1
	v_add_f32_dpp v4, v4, v4 row_mirror row_mask:0xf bank_mask:0xf
	ds_bpermute_b32 v18, v170, v4
	s_waitcnt lgkmcnt(0)
	v_add_f32_e32 v4, v4, v18
	v_fmamk_f32 v4, v4, 0x3c000000, v249
	v_mul_f32_e32 v18, 0x4b800000, v4
	v_cmp_gt_f32_e32 vcc, s10, v4
	s_nop 1
	v_cndmask_b32_e32 v4, v4, v18, vcc
	v_rsq_f32_e32 v4, v4
	s_nop 0
	v_mul_f32_e32 v18, 0x45800000, v4
	v_cndmask_b32_e32 v4, v4, v18, vcc
	v_mul_f32_e32 v2, v2, v4
	v_mul_f32_e32 v3, v3, v4
	v_mul_f32_e32 v18, v35, v4
	v_mul_f32_e32 v4, v34, v4
	v_mul_f32_e32 v2, v69, v2
	v_mul_f32_e32 v3, v71, v3
	v_mul_f32_e32 v18, v73, v18
	v_mul_f32_e32 v4, v77, v4
	v_cvt_pk_bf16_f32 v2, v2, s0
	v_cvt_pk_bf16_f32 v3, v3, s0
	v_cvt_pk_bf16_f32 v18, v18, s0
	v_cvt_pk_bf16_f32 v4, v4, s0
	ds_write_b16 v74, v2 offset:544
	ds_write_b16 v74, v3 offset:608
	ds_write_b16 v74, v18 offset:672
	ds_write_b16 v74, v4 offset:736
	ds_read2st64_b32 v[2:3], v79 offset0:6 offset1:7
	v_mov_b32_e32 v52, v5
	v_mov_b32_e32 v20, v37
	s_waitcnt lgkmcnt(0)
	v_lshlrev_b32_e32 v18, 16, v2
	v_and_b32_e32 v19, 0xffff0000, v2
	v_lshlrev_b32_e32 v35, 16, v3
	v_and_b32_e32 v34, 0xffff0000, v3
	v_pk_mul_f32 v[2:3], v[52:53], v[94:95] op_sel_hi:[1,0]
	s_nop 0
	v_pk_fma_f32 v[4:5], v[142:143], v[2:3], v[18:19] neg_lo:[1,0,0] neg_hi:[1,0,0]
	v_pk_mul_f32 v[18:19], v[20:21], v[94:95] op_sel_hi:[1,0]
	v_pk_mul_f32 v[2:3], v[4:5], v[4:5]
	v_pk_fma_f32 v[18:19], v[142:143], v[18:19], v[34:35] neg_lo:[1,0,0] neg_hi:[1,0,0]
	v_add_f32_e32 v2, v2, v3
	v_pk_mul_f32 v[20:21], v[18:19], v[18:19]
	s_nop 0
	v_add_f32_e32 v2, v2, v21
	v_add_f32_e32 v2, v20, v2
	s_waitcnt lgkmcnt(0)
	s_nop 1
	v_add_f32_dpp v2, v2, v2 quad_perm:[1,0,3,2] row_mask:0xf bank_mask:0xf
	s_waitcnt lgkmcnt(0)
	s_nop 1
	v_add_f32_dpp v2, v2, v2 quad_perm:[2,3,0,1] row_mask:0xf bank_mask:0xf
	s_waitcnt lgkmcnt(0)
	s_nop 1
	v_add_f32_dpp v2, v2, v2 row_half_mirror row_mask:0xf bank_mask:0xf
	s_waitcnt lgkmcnt(0)
	s_nop 1
	v_add_f32_dpp v2, v2, v2 row_mirror row_mask:0xf bank_mask:0xf
	ds_bpermute_b32 v3, v170, v2
	s_waitcnt lgkmcnt(0)
	v_add_f32_e32 v2, v2, v3
	v_fmamk_f32 v2, v2, 0x3c000000, v249
	v_cmp_gt_f32_e32 vcc, s10, v2
	v_mul_f32_e32 v3, 0x4b800000, v2
	s_nop 0
	v_cndmask_b32_e32 v2, v2, v3, vcc
	v_rsq_f32_e32 v2, v2
	s_nop 0
	v_mul_f32_e32 v3, 0x45800000, v2
	v_cndmask_b32_e32 v20, v2, v3, vcc
	v_or_b32_e32 v2, 3, v80
	v_mad_u64_u32 v[2:3], s[4:5], v2, s77, v[78:79]
	v_mul_f32_e32 v3, v4, v20
	v_mul_f32_e32 v3, v69, v3
	v_cvt_pk_bf16_f32 v3, v3, s0
	ds_write_b16 v2, v3
	v_mul_f32_e32 v3, v5, v20
	v_mul_f32_e32 v3, v71, v3
	v_cvt_pk_bf16_f32 v3, v3, s0
	ds_write_b16 v2, v3 offset:64
	v_mul_f32_e32 v3, v19, v20
	v_mul_f32_e32 v3, v73, v3
	v_cvt_pk_bf16_f32 v3, v3, s0
	ds_write_b16 v2, v3 offset:128
	v_mul_f32_e32 v3, v18, v20
	v_mul_f32_e32 v3, v77, v3
	v_cvt_pk_bf16_f32 v3, v3, s0
	ds_write_b16 v2, v3 offset:192
	ds_read2st64_b32 v[4:5], v79 offset0:8 offset1:9
	v_mov_b32_e32 v18, v6
	v_mov_b32_e32 v19, v54
	s_waitcnt lgkmcnt(0)
	v_lshlrev_b32_e32 v20, 16, v4
	v_and_b32_e32 v21, 0xffff0000, v4
	v_lshlrev_b32_e32 v35, 16, v5
	v_and_b32_e32 v34, 0xffff0000, v5
	v_pk_mul_f32 v[4:5], v[18:19], v[92:93] op_sel_hi:[1,0]
	s_nop 0
	v_pk_fma_f32 v[4:5], v[142:143], v[4:5], v[20:21] neg_lo:[1,0,0] neg_hi:[1,0,0]
	v_mov_b32_e32 v20, v38
	v_mov_b32_e32 v21, v22
	v_pk_mul_f32 v[20:21], v[20:21], v[92:93] op_sel_hi:[1,0]
	v_pk_mul_f32 v[18:19], v[4:5], v[4:5]
	v_pk_fma_f32 v[20:21], v[142:143], v[20:21], v[34:35] neg_lo:[1,0,0] neg_hi:[1,0,0]
	v_add_f32_e32 v3, v18, v19
	v_pk_mul_f32 v[34:35], v[20:21], v[20:21]
	s_nop 0
	v_add_f32_e32 v3, v3, v35
	v_add_f32_e32 v3, v34, v3
	s_waitcnt lgkmcnt(0)
	s_nop 1
	v_add_f32_dpp v3, v3, v3 quad_perm:[1,0,3,2] row_mask:0xf bank_mask:0xf
	s_waitcnt lgkmcnt(0)
	s_nop 1
	v_add_f32_dpp v3, v3, v3 quad_perm:[2,3,0,1] row_mask:0xf bank_mask:0xf
	s_waitcnt lgkmcnt(0)
	s_nop 1
	v_add_f32_dpp v3, v3, v3 row_half_mirror row_mask:0xf bank_mask:0xf
	s_waitcnt lgkmcnt(0)
	s_nop 1
	v_add_f32_dpp v3, v3, v3 row_mirror row_mask:0xf bank_mask:0xf
	ds_bpermute_b32 v6, v170, v3
	s_waitcnt lgkmcnt(0)
	v_add_f32_e32 v3, v3, v6
	v_fmamk_f32 v3, v3, 0x3c000000, v249
	v_mul_f32_e32 v6, 0x4b800000, v3
	v_cmp_gt_f32_e32 vcc, s10, v3
	s_nop 1
	v_cndmask_b32_e32 v3, v3, v6, vcc
	v_rsq_f32_e32 v3, v3
	s_nop 0
	v_mul_f32_e32 v6, 0x45800000, v3
	v_cndmask_b32_e32 v3, v3, v6, vcc
	v_mul_f32_e32 v4, v4, v3
	v_mul_f32_e32 v5, v5, v3
	v_mul_f32_e32 v6, v21, v3
	v_mul_f32_e32 v3, v20, v3
	v_mul_f32_e32 v4, v69, v4
	v_mul_f32_e32 v5, v71, v5
	v_mul_f32_e32 v6, v73, v6
	v_mul_f32_e32 v3, v77, v3
	v_cvt_pk_bf16_f32 v4, v4, s0
	v_cvt_pk_bf16_f32 v5, v5, s0
	v_cvt_pk_bf16_f32 v6, v6, s0
	v_cvt_pk_bf16_f32 v3, v3, s0
	ds_write_b16 v74, v4 offset:2176
	ds_write_b16 v74, v5 offset:2240
	ds_write_b16 v74, v6 offset:2304
	ds_write_b16 v74, v3 offset:2368
	ds_read2st64_b32 v[4:5], v79 offset0:10 offset1:11
	v_mov_b32_e32 v54, v7
	v_mov_b32_e32 v22, v39
	v_pk_mul_f32 v[20:21], v[22:23], v[90:91] op_sel_hi:[1,0]
	s_waitcnt lgkmcnt(0)
	v_lshlrev_b32_e32 v6, 16, v4
	v_and_b32_e32 v7, 0xffff0000, v4
	v_lshlrev_b32_e32 v19, 16, v5
	v_and_b32_e32 v18, 0xffff0000, v5
	v_pk_mul_f32 v[4:5], v[54:55], v[90:91] op_sel_hi:[1,0]
	v_pk_fma_f32 v[18:19], v[142:143], v[20:21], v[18:19] neg_lo:[1,0,0] neg_hi:[1,0,0]
	v_pk_fma_f32 v[4:5], v[142:143], v[4:5], v[6:7] neg_lo:[1,0,0] neg_hi:[1,0,0]
	v_pk_mul_f32 v[20:21], v[18:19], v[18:19]
	v_pk_mul_f32 v[6:7], v[4:5], v[4:5]
	s_nop 0
	v_add_f32_e32 v3, v6, v7
	v_add_f32_e32 v3, v3, v21
	v_add_f32_e32 v3, v20, v3
	s_waitcnt lgkmcnt(0)
	s_nop 1
	v_add_f32_dpp v3, v3, v3 quad_perm:[1,0,3,2] row_mask:0xf bank_mask:0xf
	s_waitcnt lgkmcnt(0)
	s_nop 1
	v_add_f32_dpp v3, v3, v3 quad_perm:[2,3,0,1] row_mask:0xf bank_mask:0xf
	s_waitcnt lgkmcnt(0)
	s_nop 1
	v_add_f32_dpp v3, v3, v3 row_half_mirror row_mask:0xf bank_mask:0xf
	s_waitcnt lgkmcnt(0)
	s_nop 1
	v_add_f32_dpp v3, v3, v3 row_mirror row_mask:0xf bank_mask:0xf
	ds_bpermute_b32 v6, v170, v3
	s_waitcnt lgkmcnt(0)
	v_add_f32_e32 v3, v3, v6
	v_fmamk_f32 v3, v3, 0x3c000000, v249
	v_mul_f32_e32 v6, 0x4b800000, v3
	v_cmp_gt_f32_e32 vcc, s10, v3
	s_nop 1
	v_cndmask_b32_e32 v3, v3, v6, vcc
	v_rsq_f32_e32 v3, v3
	s_nop 0
	v_mul_f32_e32 v6, 0x45800000, v3
	v_cndmask_b32_e32 v3, v3, v6, vcc
	v_mul_f32_e32 v4, v4, v3
	v_mul_f32_e32 v5, v5, v3
	v_mul_f32_e32 v6, v19, v3
	v_mul_f32_e32 v3, v18, v3
	v_mul_f32_e32 v4, v69, v4
	v_mul_f32_e32 v5, v71, v5
	v_mul_f32_e32 v6, v73, v6
	v_mul_f32_e32 v3, v77, v3
	v_cvt_pk_bf16_f32 v4, v4, s0
	v_cvt_pk_bf16_f32 v5, v5, s0
	v_cvt_pk_bf16_f32 v6, v6, s0
	v_cvt_pk_bf16_f32 v3, v3, s0
	ds_write_b16 v74, v4 offset:2448
	ds_write_b16 v74, v5 offset:2512
	ds_write_b16 v74, v6 offset:2576
	ds_write_b16 v74, v3 offset:2640
	ds_read2st64_b32 v[4:5], v79 offset0:12 offset1:13
	v_mov_b32_e32 v6, v8
	v_mov_b32_e32 v7, v56
	s_waitcnt lgkmcnt(0)
	v_lshlrev_b32_e32 v18, 16, v4
	v_and_b32_e32 v19, 0xffff0000, v4
	v_lshlrev_b32_e32 v21, 16, v5
	v_and_b32_e32 v20, 0xffff0000, v5
	v_pk_mul_f32 v[4:5], v[6:7], v[88:89] op_sel_hi:[1,0]
	s_nop 0
	v_pk_fma_f32 v[4:5], v[142:143], v[4:5], v[18:19] neg_lo:[1,0,0] neg_hi:[1,0,0]
	v_mov_b32_e32 v18, v40
	v_mov_b32_e32 v19, v24
	v_pk_mul_f32 v[18:19], v[18:19], v[88:89] op_sel_hi:[1,0]
	v_pk_mul_f32 v[6:7], v[4:5], v[4:5]
	v_pk_fma_f32 v[18:19], v[142:143], v[18:19], v[20:21] neg_lo:[1,0,0] neg_hi:[1,0,0]
	v_add_f32_e32 v3, v6, v7
	v_pk_mul_f32 v[20:21], v[18:19], v[18:19]
	s_nop 0
	v_add_f32_e32 v3, v3, v21
	v_add_f32_e32 v3, v20, v3
	s_waitcnt lgkmcnt(0)
	s_nop 1
	v_add_f32_dpp v3, v3, v3 quad_perm:[1,0,3,2] row_mask:0xf bank_mask:0xf
	s_waitcnt lgkmcnt(0)
	s_nop 1
	v_add_f32_dpp v3, v3, v3 quad_perm:[2,3,0,1] row_mask:0xf bank_mask:0xf
	s_waitcnt lgkmcnt(0)
	s_nop 1
	v_add_f32_dpp v3, v3, v3 row_half_mirror row_mask:0xf bank_mask:0xf
	s_waitcnt lgkmcnt(0)
	s_nop 1
	v_add_f32_dpp v3, v3, v3 row_mirror row_mask:0xf bank_mask:0xf
	ds_bpermute_b32 v6, v170, v3
	s_waitcnt lgkmcnt(0)
	v_add_f32_e32 v3, v3, v6
	v_fmamk_f32 v3, v3, 0x3c000000, v249
	v_mul_f32_e32 v6, 0x4b800000, v3
	v_cmp_gt_f32_e32 vcc, s10, v3
	s_nop 1
	v_cndmask_b32_e32 v3, v3, v6, vcc
	v_rsq_f32_e32 v3, v3
	s_nop 0
	v_mul_f32_e32 v6, 0x45800000, v3
	v_cndmask_b32_e32 v3, v3, v6, vcc
	v_mul_f32_e32 v4, v4, v3
	v_mul_f32_e32 v5, v5, v3
	v_mul_f32_e32 v6, v19, v3
	v_mul_f32_e32 v3, v18, v3
	v_mul_f32_e32 v4, v69, v4
	v_mul_f32_e32 v5, v71, v5
	v_mul_f32_e32 v6, v73, v6
	v_mul_f32_e32 v3, v77, v3
	v_cvt_pk_bf16_f32 v4, v4, s0
	v_cvt_pk_bf16_f32 v5, v5, s0
	v_cvt_pk_bf16_f32 v6, v6, s0
	v_cvt_pk_bf16_f32 v3, v3, s0
	ds_write_b16 v74, v4 offset:2720
	ds_write_b16 v74, v5 offset:2784
	ds_write_b16 v74, v6 offset:2848
	ds_write_b16 v74, v3 offset:2912
	ds_read2st64_b32 v[4:5], v79 offset0:14 offset1:15
	v_mov_b32_e32 v56, v9
	v_mov_b32_e32 v24, v41
	v_pk_mul_f32 v[18:19], v[24:25], v[86:87] op_sel_hi:[1,0]
	s_waitcnt lgkmcnt(0)
	v_lshlrev_b32_e32 v6, 16, v4
	v_and_b32_e32 v7, 0xffff0000, v4
	v_lshlrev_b32_e32 v9, 16, v5
	v_and_b32_e32 v8, 0xffff0000, v5
	v_pk_mul_f32 v[4:5], v[56:57], v[86:87] op_sel_hi:[1,0]
	v_pk_fma_f32 v[8:9], v[142:143], v[18:19], v[8:9] neg_lo:[1,0,0] neg_hi:[1,0,0]
	v_pk_fma_f32 v[4:5], v[142:143], v[4:5], v[6:7] neg_lo:[1,0,0] neg_hi:[1,0,0]
	v_pk_mul_f32 v[18:19], v[8:9], v[8:9]
	v_pk_mul_f32 v[6:7], v[4:5], v[4:5]
	s_nop 0
	v_add_f32_e32 v3, v6, v7
	v_add_f32_e32 v3, v3, v19
	v_add_f32_e32 v3, v18, v3
	s_waitcnt lgkmcnt(0)
	s_nop 1
	v_add_f32_dpp v3, v3, v3 quad_perm:[1,0,3,2] row_mask:0xf bank_mask:0xf
	s_waitcnt lgkmcnt(0)
	s_nop 1
	v_add_f32_dpp v3, v3, v3 quad_perm:[2,3,0,1] row_mask:0xf bank_mask:0xf
	s_waitcnt lgkmcnt(0)
	s_nop 1
	v_add_f32_dpp v3, v3, v3 row_half_mirror row_mask:0xf bank_mask:0xf
	s_waitcnt lgkmcnt(0)
	s_nop 1
	v_add_f32_dpp v3, v3, v3 row_mirror row_mask:0xf bank_mask:0xf
	ds_bpermute_b32 v6, v170, v3
	s_waitcnt lgkmcnt(0)
	v_add_f32_e32 v3, v3, v6
	v_fmamk_f32 v3, v3, 0x3c000000, v249
	v_mul_f32_e32 v6, 0x4b800000, v3
	v_cmp_gt_f32_e32 vcc, s10, v3
	s_nop 1
	v_cndmask_b32_e32 v3, v3, v6, vcc
	v_rsq_f32_e32 v3, v3
	s_nop 0
	v_mul_f32_e32 v6, 0x45800000, v3
	v_cndmask_b32_e32 v3, v3, v6, vcc
	v_mul_f32_e32 v4, v4, v3
	v_mul_f32_e32 v5, v5, v3
	v_mul_f32_e32 v6, v9, v3
	v_mul_f32_e32 v3, v8, v3
	v_mul_f32_e32 v4, v69, v4
	v_mul_f32_e32 v5, v71, v5
	v_mul_f32_e32 v6, v73, v6
	v_mul_f32_e32 v3, v77, v3
	v_cvt_pk_bf16_f32 v4, v4, s0
	v_cvt_pk_bf16_f32 v5, v5, s0
	v_cvt_pk_bf16_f32 v6, v6, s0
	v_cvt_pk_bf16_f32 v3, v3, s0
	ds_write_b16 v2, v4 offset:2176
	ds_write_b16 v2, v5 offset:2240
	ds_write_b16 v2, v6 offset:2304
	ds_write_b16 v2, v3 offset:2368
	ds_read2st64_b32 v[4:5], v79 offset0:16 offset1:17
	v_mov_b32_e32 v6, v10
	v_mov_b32_e32 v7, v58
	s_waitcnt lgkmcnt(0)
	v_lshlrev_b32_e32 v8, 16, v4
	v_and_b32_e32 v9, 0xffff0000, v4
	v_lshlrev_b32_e32 v19, 16, v5
	v_and_b32_e32 v18, 0xffff0000, v5
	v_pk_mul_f32 v[4:5], v[6:7], v[84:85] op_sel_hi:[1,0]
	s_nop 0
	v_pk_fma_f32 v[4:5], v[142:143], v[4:5], v[8:9] neg_lo:[1,0,0] neg_hi:[1,0,0]
	v_mov_b32_e32 v8, v42
	v_mov_b32_e32 v9, v26
	v_pk_mul_f32 v[8:9], v[8:9], v[84:85] op_sel_hi:[1,0]
	v_pk_mul_f32 v[6:7], v[4:5], v[4:5]
	v_pk_fma_f32 v[8:9], v[142:143], v[8:9], v[18:19] neg_lo:[1,0,0] neg_hi:[1,0,0]
	v_add_f32_e32 v3, v6, v7
	v_pk_mul_f32 v[18:19], v[8:9], v[8:9]
	s_nop 0
	v_add_f32_e32 v3, v3, v19
	v_add_f32_e32 v3, v18, v3
	s_waitcnt lgkmcnt(0)
	s_nop 1
	v_add_f32_dpp v3, v3, v3 quad_perm:[1,0,3,2] row_mask:0xf bank_mask:0xf
	s_waitcnt lgkmcnt(0)
	s_nop 1
	v_add_f32_dpp v3, v3, v3 quad_perm:[2,3,0,1] row_mask:0xf bank_mask:0xf
	s_waitcnt lgkmcnt(0)
	s_nop 1
	v_add_f32_dpp v3, v3, v3 row_half_mirror row_mask:0xf bank_mask:0xf
	s_waitcnt lgkmcnt(0)
	s_nop 1
	v_add_f32_dpp v3, v3, v3 row_mirror row_mask:0xf bank_mask:0xf
	ds_bpermute_b32 v6, v170, v3
	s_waitcnt lgkmcnt(0)
	v_add_f32_e32 v3, v3, v6
	v_fmamk_f32 v3, v3, 0x3c000000, v249
	v_mul_f32_e32 v6, 0x4b800000, v3
	v_cmp_gt_f32_e32 vcc, s10, v3
	s_nop 1
	v_cndmask_b32_e32 v3, v3, v6, vcc
	v_rsq_f32_e32 v3, v3
	s_nop 0
	v_mul_f32_e32 v6, 0x45800000, v3
	v_cndmask_b32_e32 v3, v3, v6, vcc
	v_mul_f32_e32 v4, v4, v3
	v_mul_f32_e32 v5, v5, v3
	v_mul_f32_e32 v6, v9, v3
	v_mul_f32_e32 v3, v8, v3
	v_mul_f32_e32 v4, v69, v4
	v_mul_f32_e32 v5, v71, v5
	v_mul_f32_e32 v6, v73, v6
	v_mul_f32_e32 v3, v77, v3
	v_cvt_pk_bf16_f32 v4, v4, s0
	v_cvt_pk_bf16_f32 v5, v5, s0
	v_cvt_pk_bf16_f32 v6, v6, s0
	v_cvt_pk_bf16_f32 v3, v3, s0
	ds_write_b16 v74, v4 offset:4352
	ds_write_b16 v74, v5 offset:4416
	ds_write_b16 v74, v6 offset:4480
	ds_write_b16 v74, v3 offset:4544
	ds_read2st64_b32 v[4:5], v79 offset0:18 offset1:19
	v_mov_b32_e32 v58, v11
	v_mov_b32_e32 v26, v43
	v_pk_mul_f32 v[10:11], v[26:27], v[82:83] op_sel_hi:[1,0]
	s_waitcnt lgkmcnt(0)
	v_lshlrev_b32_e32 v6, 16, v4
	v_and_b32_e32 v7, 0xffff0000, v4
	v_lshlrev_b32_e32 v9, 16, v5
	v_and_b32_e32 v8, 0xffff0000, v5
	v_pk_mul_f32 v[4:5], v[58:59], v[82:83] op_sel_hi:[1,0]
	v_pk_fma_f32 v[8:9], v[142:143], v[10:11], v[8:9] neg_lo:[1,0,0] neg_hi:[1,0,0]
	v_pk_fma_f32 v[4:5], v[142:143], v[4:5], v[6:7] neg_lo:[1,0,0] neg_hi:[1,0,0]
	v_pk_mul_f32 v[10:11], v[8:9], v[8:9]
	v_pk_mul_f32 v[6:7], v[4:5], v[4:5]
	s_nop 0
	v_add_f32_e32 v3, v6, v7
	v_add_f32_e32 v3, v3, v11
	v_add_f32_e32 v3, v10, v3
	s_waitcnt lgkmcnt(0)
	s_nop 1
	v_add_f32_dpp v3, v3, v3 quad_perm:[1,0,3,2] row_mask:0xf bank_mask:0xf
	s_waitcnt lgkmcnt(0)
	s_nop 1
	v_add_f32_dpp v3, v3, v3 quad_perm:[2,3,0,1] row_mask:0xf bank_mask:0xf
	s_waitcnt lgkmcnt(0)
	s_nop 1
	v_add_f32_dpp v3, v3, v3 row_half_mirror row_mask:0xf bank_mask:0xf
	s_waitcnt lgkmcnt(0)
	s_nop 1
	v_add_f32_dpp v3, v3, v3 row_mirror row_mask:0xf bank_mask:0xf
	ds_bpermute_b32 v6, v170, v3
	s_waitcnt lgkmcnt(0)
	v_add_f32_e32 v3, v3, v6
	v_fmamk_f32 v3, v3, 0x3c000000, v249
	v_mul_f32_e32 v6, 0x4b800000, v3
	v_cmp_gt_f32_e32 vcc, s10, v3
	s_nop 1
	v_cndmask_b32_e32 v3, v3, v6, vcc
	v_rsq_f32_e32 v3, v3
	s_nop 0
	v_mul_f32_e32 v6, 0x45800000, v3
	v_cndmask_b32_e32 v3, v3, v6, vcc
	v_mul_f32_e32 v4, v4, v3
	v_mul_f32_e32 v5, v5, v3
	v_mul_f32_e32 v6, v9, v3
	v_mul_f32_e32 v3, v8, v3
	v_mul_f32_e32 v4, v69, v4
	v_mul_f32_e32 v5, v71, v5
	v_mul_f32_e32 v6, v73, v6
	v_mul_f32_e32 v3, v77, v3
	v_cvt_pk_bf16_f32 v4, v4, s0
	v_cvt_pk_bf16_f32 v5, v5, s0
	v_cvt_pk_bf16_f32 v6, v6, s0
	v_cvt_pk_bf16_f32 v3, v3, s0
	ds_write_b16 v74, v4 offset:4624
	ds_write_b16 v74, v5 offset:4688
	ds_write_b16 v74, v6 offset:4752
	ds_write_b16 v74, v3 offset:4816
	ds_read2st64_b32 v[4:5], v79 offset0:20 offset1:21
	v_mov_b32_e32 v6, v12
	v_mov_b32_e32 v7, v60
	s_waitcnt lgkmcnt(0)
	v_lshlrev_b32_e32 v8, 16, v4
	v_and_b32_e32 v9, 0xffff0000, v4
	v_lshlrev_b32_e32 v11, 16, v5
	v_and_b32_e32 v10, 0xffff0000, v5
	v_pk_mul_f32 v[4:5], v[6:7], v[76:77] op_sel_hi:[1,0]
	s_nop 0
	v_pk_fma_f32 v[4:5], v[142:143], v[4:5], v[8:9] neg_lo:[1,0,0] neg_hi:[1,0,0]
	v_mov_b32_e32 v8, v44
	v_mov_b32_e32 v9, v28
	v_pk_mul_f32 v[8:9], v[8:9], v[76:77] op_sel_hi:[1,0]
	v_pk_mul_f32 v[6:7], v[4:5], v[4:5]
	v_pk_fma_f32 v[8:9], v[142:143], v[8:9], v[10:11] neg_lo:[1,0,0] neg_hi:[1,0,0]
	v_add_f32_e32 v3, v6, v7
	v_pk_mul_f32 v[10:11], v[8:9], v[8:9]
	s_nop 0
	v_add_f32_e32 v3, v3, v11
	v_add_f32_e32 v3, v10, v3
	s_waitcnt lgkmcnt(0)
	s_nop 1
	v_add_f32_dpp v3, v3, v3 quad_perm:[1,0,3,2] row_mask:0xf bank_mask:0xf
	s_waitcnt lgkmcnt(0)
	s_nop 1
	v_add_f32_dpp v3, v3, v3 quad_perm:[2,3,0,1] row_mask:0xf bank_mask:0xf
	s_waitcnt lgkmcnt(0)
	s_nop 1
	v_add_f32_dpp v3, v3, v3 row_half_mirror row_mask:0xf bank_mask:0xf
	s_waitcnt lgkmcnt(0)
	s_nop 1
	v_add_f32_dpp v3, v3, v3 row_mirror row_mask:0xf bank_mask:0xf
	ds_bpermute_b32 v6, v170, v3
	s_waitcnt lgkmcnt(0)
	v_add_f32_e32 v3, v3, v6
	v_fmamk_f32 v3, v3, 0x3c000000, v249
	v_mul_f32_e32 v6, 0x4b800000, v3
	v_cmp_gt_f32_e32 vcc, s10, v3
	s_nop 1
	v_cndmask_b32_e32 v3, v3, v6, vcc
	v_rsq_f32_e32 v3, v3
	s_nop 0
	v_mul_f32_e32 v6, 0x45800000, v3
	v_cndmask_b32_e32 v3, v3, v6, vcc
	v_mul_f32_e32 v4, v4, v3
	v_mul_f32_e32 v5, v5, v3
	v_mul_f32_e32 v6, v9, v3
	v_mul_f32_e32 v3, v8, v3
	v_mul_f32_e32 v4, v69, v4
	v_mul_f32_e32 v5, v71, v5
	v_mul_f32_e32 v6, v73, v6
	v_mul_f32_e32 v3, v77, v3
	v_cvt_pk_bf16_f32 v4, v4, s0
	v_cvt_pk_bf16_f32 v5, v5, s0
	v_cvt_pk_bf16_f32 v6, v6, s0
	v_cvt_pk_bf16_f32 v3, v3, s0
	ds_write_b16 v74, v4 offset:4896
	ds_write_b16 v74, v5 offset:4960
	ds_write_b16 v74, v6 offset:5024
	ds_write_b16 v74, v3 offset:5088
	ds_read2st64_b32 v[4:5], v79 offset0:22 offset1:23
	v_mov_b32_e32 v60, v13
	v_mov_b32_e32 v28, v45
	v_pk_mul_f32 v[10:11], v[28:29], v[72:73] op_sel_hi:[1,0]
	s_waitcnt lgkmcnt(0)
	v_lshlrev_b32_e32 v6, 16, v4
	v_and_b32_e32 v7, 0xffff0000, v4
	v_lshlrev_b32_e32 v9, 16, v5
	v_and_b32_e32 v8, 0xffff0000, v5
	v_pk_mul_f32 v[4:5], v[60:61], v[72:73] op_sel_hi:[1,0]
	v_pk_fma_f32 v[8:9], v[142:143], v[10:11], v[8:9] neg_lo:[1,0,0] neg_hi:[1,0,0]
	v_pk_fma_f32 v[4:5], v[142:143], v[4:5], v[6:7] neg_lo:[1,0,0] neg_hi:[1,0,0]
	v_pk_mul_f32 v[10:11], v[8:9], v[8:9]
	v_pk_mul_f32 v[6:7], v[4:5], v[4:5]
	s_nop 0
	v_add_f32_e32 v3, v6, v7
	v_add_f32_e32 v3, v3, v11
	v_add_f32_e32 v3, v10, v3
	s_waitcnt lgkmcnt(0)
	s_nop 1
	v_add_f32_dpp v3, v3, v3 quad_perm:[1,0,3,2] row_mask:0xf bank_mask:0xf
	s_waitcnt lgkmcnt(0)
	s_nop 1
	v_add_f32_dpp v3, v3, v3 quad_perm:[2,3,0,1] row_mask:0xf bank_mask:0xf
	s_waitcnt lgkmcnt(0)
	s_nop 1
	v_add_f32_dpp v3, v3, v3 row_half_mirror row_mask:0xf bank_mask:0xf
	s_waitcnt lgkmcnt(0)
	s_nop 1
	v_add_f32_dpp v3, v3, v3 row_mirror row_mask:0xf bank_mask:0xf
	ds_bpermute_b32 v6, v170, v3
	s_waitcnt lgkmcnt(0)
	v_add_f32_e32 v3, v3, v6
	v_fmamk_f32 v3, v3, 0x3c000000, v249
	v_mul_f32_e32 v6, 0x4b800000, v3
	v_cmp_gt_f32_e32 vcc, s10, v3
	s_nop 1
	v_cndmask_b32_e32 v3, v3, v6, vcc
	v_rsq_f32_e32 v3, v3
	s_nop 0
	v_mul_f32_e32 v6, 0x45800000, v3
	v_cndmask_b32_e32 v3, v3, v6, vcc
	v_mul_f32_e32 v4, v4, v3
	v_mul_f32_e32 v5, v5, v3
	v_mul_f32_e32 v6, v9, v3
	v_mul_f32_e32 v3, v8, v3
	v_mul_f32_e32 v4, v69, v4
	v_mul_f32_e32 v5, v71, v5
	v_mul_f32_e32 v6, v73, v6
	v_mul_f32_e32 v3, v77, v3
	v_cvt_pk_bf16_f32 v4, v4, s0
	v_cvt_pk_bf16_f32 v5, v5, s0
	v_cvt_pk_bf16_f32 v6, v6, s0
	v_cvt_pk_bf16_f32 v3, v3, s0
	ds_write_b16 v2, v4 offset:4352
	ds_write_b16 v2, v5 offset:4416
	ds_write_b16 v2, v6 offset:4480
	ds_write_b16 v2, v3 offset:4544
	ds_read2st64_b32 v[4:5], v79 offset0:24 offset1:25
	v_mov_b32_e32 v6, v14
	v_mov_b32_e32 v7, v62
	s_waitcnt lgkmcnt(0)
	v_lshlrev_b32_e32 v8, 16, v4
	v_and_b32_e32 v9, 0xffff0000, v4
	v_lshlrev_b32_e32 v11, 16, v5
	v_and_b32_e32 v10, 0xffff0000, v5
	v_pk_mul_f32 v[4:5], v[6:7], v[70:71] op_sel_hi:[1,0]
	s_nop 0
	v_pk_fma_f32 v[4:5], v[142:143], v[4:5], v[8:9] neg_lo:[1,0,0] neg_hi:[1,0,0]
	v_mov_b32_e32 v8, v46
	v_mov_b32_e32 v9, v30
	v_pk_mul_f32 v[8:9], v[8:9], v[70:71] op_sel_hi:[1,0]
	v_pk_mul_f32 v[6:7], v[4:5], v[4:5]
	v_pk_fma_f32 v[8:9], v[142:143], v[8:9], v[10:11] neg_lo:[1,0,0] neg_hi:[1,0,0]
	v_add_f32_e32 v3, v6, v7
	v_pk_mul_f32 v[10:11], v[8:9], v[8:9]
	s_nop 0
	v_add_f32_e32 v3, v3, v11
	v_add_f32_e32 v3, v10, v3
	s_waitcnt lgkmcnt(0)
	s_nop 1
	v_add_f32_dpp v3, v3, v3 quad_perm:[1,0,3,2] row_mask:0xf bank_mask:0xf
	s_waitcnt lgkmcnt(0)
	s_nop 1
	v_add_f32_dpp v3, v3, v3 quad_perm:[2,3,0,1] row_mask:0xf bank_mask:0xf
	s_waitcnt lgkmcnt(0)
	s_nop 1
	v_add_f32_dpp v3, v3, v3 row_half_mirror row_mask:0xf bank_mask:0xf
	s_waitcnt lgkmcnt(0)
	s_nop 1
	v_add_f32_dpp v3, v3, v3 row_mirror row_mask:0xf bank_mask:0xf
	ds_bpermute_b32 v6, v170, v3
	s_waitcnt lgkmcnt(0)
	v_add_f32_e32 v3, v3, v6
	v_fmamk_f32 v3, v3, 0x3c000000, v249
	v_mul_f32_e32 v6, 0x4b800000, v3
	v_cmp_gt_f32_e32 vcc, s10, v3
	s_nop 1
	v_cndmask_b32_e32 v3, v3, v6, vcc
	v_rsq_f32_e32 v3, v3
	s_nop 0
	v_mul_f32_e32 v6, 0x45800000, v3
	v_cndmask_b32_e32 v3, v3, v6, vcc
	v_mul_f32_e32 v4, v4, v3
	v_mul_f32_e32 v5, v5, v3
	v_mul_f32_e32 v6, v9, v3
	v_mul_f32_e32 v3, v8, v3
	v_mul_f32_e32 v4, v69, v4
	v_mul_f32_e32 v5, v71, v5
	v_mul_f32_e32 v6, v73, v6
	v_mul_f32_e32 v3, v77, v3
	v_cvt_pk_bf16_f32 v4, v4, s0
	v_cvt_pk_bf16_f32 v5, v5, s0
	v_cvt_pk_bf16_f32 v6, v6, s0
	v_cvt_pk_bf16_f32 v3, v3, s0
	ds_write_b16 v74, v4 offset:6528
	ds_write_b16 v74, v5 offset:6592
	ds_write_b16 v74, v6 offset:6656
	ds_write_b16 v74, v3 offset:6720
	ds_read2st64_b32 v[4:5], v79 offset0:26 offset1:27
	v_mov_b32_e32 v62, v15
	v_mov_b32_e32 v30, v47
	v_pk_mul_f32 v[10:11], v[30:31], v[68:69] op_sel_hi:[1,0]
	s_waitcnt lgkmcnt(0)
	v_lshlrev_b32_e32 v6, 16, v4
	v_and_b32_e32 v7, 0xffff0000, v4
	v_lshlrev_b32_e32 v9, 16, v5
	v_and_b32_e32 v8, 0xffff0000, v5
	v_pk_mul_f32 v[4:5], v[62:63], v[68:69] op_sel_hi:[1,0]
	v_pk_fma_f32 v[8:9], v[142:143], v[10:11], v[8:9] neg_lo:[1,0,0] neg_hi:[1,0,0]
	v_pk_fma_f32 v[4:5], v[142:143], v[4:5], v[6:7] neg_lo:[1,0,0] neg_hi:[1,0,0]
	v_pk_mul_f32 v[10:11], v[8:9], v[8:9]
	v_pk_mul_f32 v[6:7], v[4:5], v[4:5]
	s_nop 0
	v_add_f32_e32 v3, v6, v7
	v_add_f32_e32 v3, v3, v11
	v_add_f32_e32 v3, v10, v3
	s_waitcnt lgkmcnt(0)
	s_nop 1
	v_add_f32_dpp v3, v3, v3 quad_perm:[1,0,3,2] row_mask:0xf bank_mask:0xf
	s_waitcnt lgkmcnt(0)
	s_nop 1
	v_add_f32_dpp v3, v3, v3 quad_perm:[2,3,0,1] row_mask:0xf bank_mask:0xf
	s_waitcnt lgkmcnt(0)
	s_nop 1
	v_add_f32_dpp v3, v3, v3 row_half_mirror row_mask:0xf bank_mask:0xf
	s_waitcnt lgkmcnt(0)
	s_nop 1
	v_add_f32_dpp v3, v3, v3 row_mirror row_mask:0xf bank_mask:0xf
	ds_bpermute_b32 v6, v170, v3
	s_waitcnt lgkmcnt(0)
	v_add_f32_e32 v3, v3, v6
	v_fmamk_f32 v3, v3, 0x3c000000, v249
	v_mul_f32_e32 v6, 0x4b800000, v3
	v_cmp_gt_f32_e32 vcc, s10, v3
	s_nop 1
	v_cndmask_b32_e32 v3, v3, v6, vcc
	v_rsq_f32_e32 v3, v3
	s_nop 0
	v_mul_f32_e32 v6, 0x45800000, v3
	v_cndmask_b32_e32 v3, v3, v6, vcc
	v_mul_f32_e32 v4, v4, v3
	v_mul_f32_e32 v5, v5, v3
	v_mul_f32_e32 v6, v9, v3
	v_mul_f32_e32 v3, v8, v3
	v_mul_f32_e32 v4, v69, v4
	v_mul_f32_e32 v5, v71, v5
	v_mul_f32_e32 v6, v73, v6
	v_mul_f32_e32 v3, v77, v3
	v_cvt_pk_bf16_f32 v4, v4, s0
	v_cvt_pk_bf16_f32 v5, v5, s0
	v_cvt_pk_bf16_f32 v6, v6, s0
	v_cvt_pk_bf16_f32 v3, v3, s0
	ds_write_b16 v74, v4 offset:6800
	ds_write_b16 v74, v5 offset:6864
	ds_write_b16 v74, v6 offset:6928
	ds_write_b16 v74, v3 offset:6992
	ds_read2st64_b32 v[4:5], v79 offset0:28 offset1:29
	v_mov_b32_e32 v6, v16
	v_mov_b32_e32 v7, v64
	s_waitcnt lgkmcnt(0)
	v_lshlrev_b32_e32 v8, 16, v4
	v_and_b32_e32 v9, 0xffff0000, v4
	v_lshlrev_b32_e32 v11, 16, v5
	v_and_b32_e32 v10, 0xffff0000, v5
	v_pk_mul_f32 v[4:5], v[6:7], v[66:67] op_sel_hi:[1,0]
	s_nop 0
	v_pk_fma_f32 v[4:5], v[142:143], v[4:5], v[8:9] neg_lo:[1,0,0] neg_hi:[1,0,0]
	v_mov_b32_e32 v8, v48
	v_mov_b32_e32 v9, v32
	v_pk_mul_f32 v[8:9], v[8:9], v[66:67] op_sel_hi:[1,0]
	v_pk_mul_f32 v[6:7], v[4:5], v[4:5]
	v_pk_fma_f32 v[8:9], v[142:143], v[8:9], v[10:11] neg_lo:[1,0,0] neg_hi:[1,0,0]
	v_add_f32_e32 v3, v6, v7
	v_pk_mul_f32 v[10:11], v[8:9], v[8:9]
	s_nop 0
	v_add_f32_e32 v3, v3, v11
	v_add_f32_e32 v3, v10, v3
	s_waitcnt lgkmcnt(0)
	s_nop 1
	v_add_f32_dpp v3, v3, v3 quad_perm:[1,0,3,2] row_mask:0xf bank_mask:0xf
	s_waitcnt lgkmcnt(0)
	s_nop 1
	v_add_f32_dpp v3, v3, v3 quad_perm:[2,3,0,1] row_mask:0xf bank_mask:0xf
	s_waitcnt lgkmcnt(0)
	s_nop 1
	v_add_f32_dpp v3, v3, v3 row_half_mirror row_mask:0xf bank_mask:0xf
	s_waitcnt lgkmcnt(0)
	s_nop 1
	v_add_f32_dpp v3, v3, v3 row_mirror row_mask:0xf bank_mask:0xf
	ds_bpermute_b32 v6, v170, v3
	s_waitcnt lgkmcnt(0)
	v_add_f32_e32 v3, v3, v6
	v_fmamk_f32 v3, v3, 0x3c000000, v249
	v_mul_f32_e32 v6, 0x4b800000, v3
	v_cmp_gt_f32_e32 vcc, s10, v3
	s_nop 1
	v_cndmask_b32_e32 v3, v3, v6, vcc
	v_rsq_f32_e32 v3, v3
	s_nop 0
	v_mul_f32_e32 v6, 0x45800000, v3
	v_cndmask_b32_e32 v3, v3, v6, vcc
	v_mul_f32_e32 v4, v4, v3
	v_mul_f32_e32 v5, v5, v3
	v_mul_f32_e32 v6, v9, v3
	v_mul_f32_e32 v3, v8, v3
	v_mul_f32_e32 v4, v69, v4
	v_mul_f32_e32 v5, v71, v5
	v_mul_f32_e32 v6, v73, v6
	v_mul_f32_e32 v3, v77, v3
	v_cvt_pk_bf16_f32 v4, v4, s0
	v_cvt_pk_bf16_f32 v5, v5, s0
	v_cvt_pk_bf16_f32 v6, v6, s0
	v_cvt_pk_bf16_f32 v3, v3, s0
	ds_write_b16 v74, v4 offset:7072
	ds_write_b16 v74, v5 offset:7136
	ds_write_b16 v74, v6 offset:7200
	ds_write_b16 v74, v3 offset:7264
	ds_read2st64_b32 v[4:5], v79 offset0:30 offset1:31
	v_mov_b32_e32 v64, v17
	v_mov_b32_e32 v32, v49
	v_pk_mul_f32 v[10:11], v[32:33], v[0:1] op_sel_hi:[1,0]
	s_waitcnt lgkmcnt(0)
	v_lshlrev_b32_e32 v6, 16, v4
	v_and_b32_e32 v7, 0xffff0000, v4
	v_lshlrev_b32_e32 v9, 16, v5
	v_and_b32_e32 v8, 0xffff0000, v5
	v_pk_mul_f32 v[4:5], v[64:65], v[0:1] op_sel_hi:[1,0]
	v_pk_fma_f32 v[8:9], v[142:143], v[10:11], v[8:9] neg_lo:[1,0,0] neg_hi:[1,0,0]
	v_pk_fma_f32 v[4:5], v[142:143], v[4:5], v[6:7] neg_lo:[1,0,0] neg_hi:[1,0,0]
	v_pk_mul_f32 v[10:11], v[8:9], v[8:9]
	v_pk_mul_f32 v[6:7], v[4:5], v[4:5]
	s_nop 0
	v_add_f32_e32 v0, v6, v7
	v_add_f32_e32 v0, v0, v11
	v_add_f32_e32 v0, v10, v0
	s_waitcnt lgkmcnt(0)
	s_nop 1
	v_add_f32_dpp v0, v0, v0 quad_perm:[1,0,3,2] row_mask:0xf bank_mask:0xf
	s_waitcnt lgkmcnt(0)
	s_nop 1
	v_add_f32_dpp v0, v0, v0 quad_perm:[2,3,0,1] row_mask:0xf bank_mask:0xf
	s_waitcnt lgkmcnt(0)
	s_nop 1
	v_add_f32_dpp v0, v0, v0 row_half_mirror row_mask:0xf bank_mask:0xf
	s_waitcnt lgkmcnt(0)
	s_nop 1
	v_add_f32_dpp v0, v0, v0 row_mirror row_mask:0xf bank_mask:0xf
	ds_bpermute_b32 v3, v170, v0
	s_waitcnt lgkmcnt(0)
	v_add_f32_e32 v0, v0, v3
	v_fmamk_f32 v0, v0, 0x3c000000, v249
	v_mul_f32_e32 v3, 0x4b800000, v0
	v_cmp_gt_f32_e32 vcc, s10, v0
	s_nop 1
	v_cndmask_b32_e32 v0, v0, v3, vcc
	v_rsq_f32_e32 v0, v0
	s_nop 0
	v_mul_f32_e32 v3, 0x45800000, v0
	v_cndmask_b32_e32 v0, v0, v3, vcc
	v_mul_f32_e32 v3, v4, v0
	v_mul_f32_e32 v4, v5, v0
	v_mul_f32_e32 v5, v9, v0
	v_mul_f32_e32 v0, v8, v0
	v_mul_f32_e32 v3, v69, v3
	v_mul_f32_e32 v4, v71, v4
	v_mul_f32_e32 v5, v73, v5
	v_mul_f32_e32 v0, v77, v0
	v_cvt_pk_bf16_f32 v3, v3, s0
	v_cvt_pk_bf16_f32 v4, v4, s0
	v_cvt_pk_bf16_f32 v5, v5, s0
	v_cvt_pk_bf16_f32 v0, v0, s0
	ds_write_b16 v2, v3 offset:6528
	ds_write_b16 v2, v4 offset:6592
	ds_write_b16 v2, v5 offset:6656
	ds_write_b16 v2, v0 offset:6720
	s_add_i32 s4, s1, s60
	s_ashr_i32 s5, s4, 31
	s_lshl_b64 s[4:5], s[4:5], 11
	s_add_u32 s1, s41, s4
	s_addc_u32 s5, s66, s5
	s_add_u32 s4, s1, s61
	v_ashrrev_i32_e32 v6, 4, v172
	v_lshlrev_b32_e32 v0, 4, v172
	s_addc_u32 s5, s5, 0
	v_and_b32_e32 v0, 0xf0, v0
	v_mul_lo_u32 v2, v6, s77
	s_waitcnt lgkmcnt(0)
	v_lshl_add_u64 v[8:9], s[4:5], 0, v[0:1]
	v_add3_u32 v0, v67, v0, v2
	ds_read_b128 v[2:5], v0
	v_ashrrev_i32_e32 v7, 31, v6
	v_lshlrev_b64 v[6:7], 11, v[6:7]
	v_lshl_add_u64 v[6:7], v[8:9], 0, v[6:7]
	v_add_co_u32_e32 v8, vcc, s88, v6
	s_waitcnt lgkmcnt(0)
	global_store_dwordx4 v[6:7], v[2:5], off sc1
	ds_read_b128 v[2:5], v0 offset:1088
	v_addc_co_u32_e32 v9, vcc, 0, v7, vcc
	v_readlane_b32 s1, v253, 61
	s_add_i32 s68, s68, s1
	s_waitcnt lgkmcnt(0)
	global_store_dwordx4 v[8:9], v[2:5], off sc1
	ds_read_b128 v[2:5], v0 offset:2176
	v_add_co_u32_e32 v8, vcc, s14, v6
	v_readlane_b32 s1, v253, 63
	s_nop 0
	v_addc_co_u32_e32 v9, vcc, 0, v7, vcc
	s_waitcnt lgkmcnt(0)
	global_store_dwordx4 v[8:9], v[2:5], off sc1
	ds_read_b128 v[2:5], v0 offset:3264
	v_add_co_u32_e32 v8, vcc, s89, v6
	s_add_i32 s69, s69, s90
	s_nop 0
	v_addc_co_u32_e32 v9, vcc, 0, v7, vcc
	s_waitcnt lgkmcnt(0)
	global_store_dwordx4 v[8:9], v[2:5], off sc1
	ds_read_b128 v[2:5], v0 offset:4352
	v_add_co_u32_e32 v8, vcc, s81, v6
	s_add_i32 s67, s67, s1
	s_nop 0
	v_addc_co_u32_e32 v9, vcc, 0, v7, vcc
	s_waitcnt lgkmcnt(0)
	global_store_dwordx4 v[8:9], v[2:5], off sc1
	ds_read_b128 v[2:5], v0 offset:5440
	v_add_co_u32_e32 v8, vcc, s20, v6
	s_cmpk_gt_i32 s69, 0xff
	s_nop 0
	v_addc_co_u32_e32 v9, vcc, 0, v7, vcc
	s_waitcnt lgkmcnt(0)
	global_store_dwordx4 v[8:9], v[2:5], off sc1
	ds_read_b128 v[2:5], v0 offset:6528
	v_add_co_u32_e32 v8, vcc, s18, v6
	s_nop 1
	v_addc_co_u32_e32 v9, vcc, 0, v7, vcc
	s_waitcnt lgkmcnt(0)
	global_store_dwordx4 v[8:9], v[2:5], off sc1
	ds_read_b128 v[2:5], v0 offset:7616
	v_add_co_u32_e32 v6, vcc, 0xe000, v6
	s_nop 1
	v_addc_co_u32_e32 v7, vcc, 0, v7, vcc
	s_waitcnt lgkmcnt(0)
	global_store_dwordx4 v[6:7], v[2:5], off sc1
	s_barrier
	s_cbranch_scc1 .LBB0_94

.LBB0_64:
	v_readlane_b32 s4, v255, 34
	v_readlane_b32 s5, v255, 35
	s_load_dwordx2 s[50:51], s[4:5], 0xb0
	v_rcp_f32_e32 v94, v69
	v_lshlrev_b32_e32 v69, 2, v145
	v_rcp_f32_e32 v98, v67
	v_rcp_f32_e32 v90, v71
	v_rcp_f32_e32 v86, v73
	s_waitcnt lgkmcnt(0)
	global_load_dword v67, v69, s[50:51]
	global_load_dword v71, v69, s[50:51] offset:128
	global_load_dword v73, v69, s[50:51] offset:256
	v_readlane_b32 s4, v251, 48
	global_load_dword v69, v69, s[50:51] offset:384
	v_rcp_f32_e32 v82, v75
	v_rcp_f32_e32 v96, v68
	v_rcp_f32_e32 v68, v79
	v_rcp_f32_e32 v88, v72
	v_rcp_f32_e32 v84, v74
	v_rcp_f32_e32 v74, v76
	v_rcp_f32_e32 v72, v77
	v_rcp_f32_e32 v100, v66
	v_mov_b32_e32 v106, v34
	v_mov_b32_e32 v107, v18
	s_mov_b32 s5, 0x800000
	v_rcp_f32_e32 v66, v80
	v_ashrrev_i32_e32 v80, 3, v162
	v_rcp_f32_e32 v92, v70
	v_rcp_f32_e32 v70, v78
	v_rcp_f32_e32 v0, v81
	v_and_b32_e32 v81, 0xffffffc, v80
	s_and_b32 s10, s67, 0x700
	s_addk_i32 s10, 0x100
	s_waitcnt vmcnt(3)
	v_mul_f32_e32 v67, 0x3f24fd5c, v67
	s_waitcnt vmcnt(2)
	v_mul_f32_e32 v71, 0x3f24fd5c, v71
	s_waitcnt vmcnt(1)
	v_mul_f32_e32 v73, 0x3f24fd5c, v73
	s_waitcnt vmcnt(0)
	v_mul_f32_e32 v75, 0x3f24fd5c, v69
	v_mov_b32_e32 v69, s4
	s_mov_b32 s4, 1
	v_add_u32_e32 v79, 0, v160
	ds_read2st64_b32 v[76:77], v79 offset1:1
	v_add_u32_e32 v69, 0, v69
	v_lshl_add_u32 v78, v145, 1, v69
	s_waitcnt lgkmcnt(0)
	v_lshlrev_b32_e32 v102, 16, v76
	v_and_b32_e32 v103, 0xffff0000, v76
	v_lshlrev_b32_e32 v105, 16, v77
	v_and_b32_e32 v104, 0xffff0000, v77
	v_mov_b32_e32 v76, v2
	v_mov_b32_e32 v77, v50
	v_pk_mul_f32 v[76:77], v[76:77], v[100:101] op_sel_hi:[1,0]
	v_pk_mul_f32 v[100:101], v[106:107], v[100:101] op_sel_hi:[1,0]
	v_pk_fma_f32 v[102:103], v[142:143], v[76:77], v[102:103] neg_lo:[1,0,0] neg_hi:[1,0,0]
	v_pk_fma_f32 v[100:101], v[142:143], v[100:101], v[104:105] neg_lo:[1,0,0] neg_hi:[1,0,0]
	v_pk_mul_f32 v[76:77], v[102:103], v[102:103]
	v_pk_mul_f32 v[104:105], v[100:101], v[100:101]
	v_add_f32_e32 v2, v76, v77
	v_add_f32_e32 v2, v2, v105
	v_add_f32_e32 v2, v104, v2
	v_mad_u64_u32 v[76:77], s[22:23], v81, s77, v[78:79]
	s_waitcnt lgkmcnt(0)
	s_nop 1
	v_add_f32_dpp v2, v2, v2 quad_perm:[1,0,3,2] row_mask:0xf bank_mask:0xf
	s_waitcnt lgkmcnt(0)
	s_nop 1
	v_add_f32_dpp v2, v2, v2 quad_perm:[2,3,0,1] row_mask:0xf bank_mask:0xf
	s_waitcnt lgkmcnt(0)
	s_nop 1
	v_add_f32_dpp v2, v2, v2 row_half_mirror row_mask:0xf bank_mask:0xf
	s_waitcnt lgkmcnt(0)
	s_nop 1
	v_add_f32_dpp v2, v2, v2 row_mirror row_mask:0xf bank_mask:0xf
	ds_bpermute_b32 v18, v170, v2
	s_waitcnt lgkmcnt(0)
	v_add_f32_e32 v2, v2, v18
	v_fmamk_f32 v2, v2, 0x3c000000, v249
	v_cmp_gt_f32_e32 vcc, s5, v2
	v_mul_f32_e32 v18, 0x4b800000, v2
	s_nop 0
	v_cndmask_b32_e32 v2, v2, v18, vcc
	v_rsq_f32_e32 v2, v2
	s_nop 0
	v_mul_f32_e32 v18, 0x45800000, v2
	v_cndmask_b32_e32 v2, v2, v18, vcc
	v_mul_f32_e32 v18, v102, v2
	v_mul_f32_e32 v18, v67, v18
	v_cvt_pk_bf16_f32 v18, v18, s0
	ds_write_b16 v76, v18
	v_mul_f32_e32 v18, v103, v2
	v_mul_f32_e32 v18, v71, v18
	v_cvt_pk_bf16_f32 v18, v18, s0
	ds_write_b16 v76, v18 offset:64
	v_mul_f32_e32 v18, v101, v2
	v_mul_f32_e32 v2, v100, v2
	v_mul_f32_e32 v18, v73, v18
	v_mul_f32_e32 v2, v75, v2
	v_cvt_pk_bf16_f32 v18, v18, s0
	v_cvt_pk_bf16_f32 v2, v2, s0
	ds_write_b16 v76, v18 offset:128
	ds_write_b16 v76, v2 offset:192
	ds_read2st64_b32 v[100:101], v79 offset0:2 offset1:3
	v_mov_b32_e32 v50, v3
	v_pk_mul_f32 v[50:51], v[50:51], v[98:99] op_sel_hi:[1,0]
	v_mov_b32_e32 v18, v35
	v_pk_mul_f32 v[18:19], v[18:19], v[98:99] op_sel_hi:[1,0]
	s_waitcnt lgkmcnt(0)
	v_lshlrev_b32_e32 v2, 16, v100
	v_and_b32_e32 v3, 0xffff0000, v100
	v_lshlrev_b32_e32 v103, 16, v101
	v_and_b32_e32 v102, 0xffff0000, v101
	v_pk_fma_f32 v[2:3], v[142:143], v[50:51], v[2:3] neg_lo:[1,0,0] neg_hi:[1,0,0]
	v_pk_fma_f32 v[18:19], v[142:143], v[18:19], v[102:103] neg_lo:[1,0,0] neg_hi:[1,0,0]
	v_pk_mul_f32 v[50:51], v[2:3], v[2:3]
	v_pk_mul_f32 v[34:35], v[18:19], v[18:19]
	v_add_f32_e32 v50, v50, v51
	v_add_f32_e32 v35, v50, v35
	v_add_f32_e32 v34, v34, v35
	s_waitcnt lgkmcnt(0)
	s_nop 1
	v_add_f32_dpp v34, v34, v34 quad_perm:[1,0,3,2] row_mask:0xf bank_mask:0xf
	s_waitcnt lgkmcnt(0)
	s_nop 1
	v_add_f32_dpp v34, v34, v34 quad_perm:[2,3,0,1] row_mask:0xf bank_mask:0xf
	s_waitcnt lgkmcnt(0)
	s_nop 1
	v_add_f32_dpp v34, v34, v34 row_half_mirror row_mask:0xf bank_mask:0xf
	s_waitcnt lgkmcnt(0)
	s_nop 1
	v_add_f32_dpp v34, v34, v34 row_mirror row_mask:0xf bank_mask:0xf
	ds_bpermute_b32 v35, v170, v34
	s_waitcnt lgkmcnt(0)
	v_add_f32_e32 v34, v34, v35
	v_fmamk_f32 v34, v34, 0x3c000000, v249
	v_mul_f32_e32 v35, 0x4b800000, v34
	v_cmp_gt_f32_e32 vcc, s5, v34
	s_nop 1
	v_cndmask_b32_e32 v34, v34, v35, vcc
	v_rsq_f32_e32 v34, v34
	s_nop 0
	v_mul_f32_e32 v35, 0x45800000, v34
	v_cndmask_b32_e32 v34, v34, v35, vcc
	v_mul_f32_e32 v2, v2, v34
	v_mul_f32_e32 v3, v3, v34
	v_mul_f32_e32 v19, v19, v34
	v_mul_f32_e32 v18, v18, v34
	v_mul_f32_e32 v2, v67, v2
	v_mul_f32_e32 v3, v71, v3
	v_mul_f32_e32 v19, v73, v19
	v_mul_f32_e32 v18, v75, v18
	v_cvt_pk_bf16_f32 v2, v2, s0
	v_cvt_pk_bf16_f32 v3, v3, s0
	v_cvt_pk_bf16_f32 v19, v19, s0
	v_cvt_pk_bf16_f32 v18, v18, s0
	ds_write_b16 v76, v2 offset:272
	ds_write_b16 v76, v3 offset:336
	ds_write_b16 v76, v19 offset:400
	ds_write_b16 v76, v18 offset:464
	ds_read2st64_b32 v[2:3], v79 offset0:4 offset1:5
	v_mov_b32_e32 v18, v4
	v_mov_b32_e32 v19, v52
	s_waitcnt lgkmcnt(0)
	v_lshlrev_b32_e32 v34, 16, v2
	v_and_b32_e32 v35, 0xffff0000, v2
	v_lshlrev_b32_e32 v51, 16, v3
	v_and_b32_e32 v50, 0xffff0000, v3
	v_pk_mul_f32 v[2:3], v[18:19], v[96:97] op_sel_hi:[1,0]
	s_nop 0
	v_pk_fma_f32 v[2:3], v[142:143], v[2:3], v[34:35] neg_lo:[1,0,0] neg_hi:[1,0,0]
	v_mov_b32_e32 v34, v36
	v_mov_b32_e32 v35, v20
	v_pk_mul_f32 v[34:35], v[34:35], v[96:97] op_sel_hi:[1,0]
	v_pk_mul_f32 v[18:19], v[2:3], v[2:3]
	v_pk_fma_f32 v[34:35], v[142:143], v[34:35], v[50:51] neg_lo:[1,0,0] neg_hi:[1,0,0]
	v_add_f32_e32 v4, v18, v19
	v_pk_mul_f32 v[50:51], v[34:35], v[34:35]
	s_nop 0
	v_add_f32_e32 v4, v4, v51
	v_add_f32_e32 v4, v50, v4
	s_waitcnt lgkmcnt(0)
	s_nop 1
	v_add_f32_dpp v4, v4, v4 quad_perm:[1,0,3,2] row_mask:0xf bank_mask:0xf
	s_waitcnt lgkmcnt(0)
	s_nop 1
	v_add_f32_dpp v4, v4, v4 quad_perm:[2,3,0,1] row_mask:0xf bank_mask:0xf
	s_waitcnt lgkmcnt(0)
	s_nop 1
	v_add_f32_dpp v4, v4, v4 row_half_mirror row_mask:0xf bank_mask:0xf
	s_waitcnt lgkmcnt(0)
	s_nop 1
	v_add_f32_dpp v4, v4, v4 row_mirror row_mask:0xf bank_mask:0xf
	ds_bpermute_b32 v18, v170, v4
	s_waitcnt lgkmcnt(0)
	v_add_f32_e32 v4, v4, v18
	v_fmamk_f32 v4, v4, 0x3c000000, v249
	v_mul_f32_e32 v18, 0x4b800000, v4
	v_cmp_gt_f32_e32 vcc, s5, v4
	s_nop 1
	v_cndmask_b32_e32 v4, v4, v18, vcc
	v_rsq_f32_e32 v4, v4
	s_nop 0
	v_mul_f32_e32 v18, 0x45800000, v4
	v_cndmask_b32_e32 v4, v4, v18, vcc
	v_mul_f32_e32 v2, v2, v4
	v_mul_f32_e32 v3, v3, v4
	v_mul_f32_e32 v18, v35, v4
	v_mul_f32_e32 v4, v34, v4
	v_mul_f32_e32 v2, v67, v2
	v_mul_f32_e32 v3, v71, v3
	v_mul_f32_e32 v18, v73, v18
	v_mul_f32_e32 v4, v75, v4
	v_cvt_pk_bf16_f32 v2, v2, s0
	v_cvt_pk_bf16_f32 v3, v3, s0
	v_cvt_pk_bf16_f32 v18, v18, s0
	v_cvt_pk_bf16_f32 v4, v4, s0
	ds_write_b16 v76, v2 offset:544
	ds_write_b16 v76, v3 offset:608
	ds_write_b16 v76, v18 offset:672
	ds_write_b16 v76, v4 offset:736
	ds_read2st64_b32 v[2:3], v79 offset0:6 offset1:7
	v_mov_b32_e32 v52, v5
	v_mov_b32_e32 v20, v37
	s_waitcnt lgkmcnt(0)
	v_lshlrev_b32_e32 v18, 16, v2
	v_and_b32_e32 v19, 0xffff0000, v2
	v_lshlrev_b32_e32 v35, 16, v3
	v_and_b32_e32 v34, 0xffff0000, v3
	v_pk_mul_f32 v[2:3], v[52:53], v[94:95] op_sel_hi:[1,0]
	s_nop 0
	v_pk_fma_f32 v[4:5], v[142:143], v[2:3], v[18:19] neg_lo:[1,0,0] neg_hi:[1,0,0]
	v_pk_mul_f32 v[18:19], v[20:21], v[94:95] op_sel_hi:[1,0]
	v_pk_mul_f32 v[2:3], v[4:5], v[4:5]
	v_pk_fma_f32 v[18:19], v[142:143], v[18:19], v[34:35] neg_lo:[1,0,0] neg_hi:[1,0,0]
	v_add_f32_e32 v2, v2, v3
	v_pk_mul_f32 v[20:21], v[18:19], v[18:19]
	s_nop 0
	v_add_f32_e32 v2, v2, v21
	v_add_f32_e32 v2, v20, v2
	s_waitcnt lgkmcnt(0)
	s_nop 1
	v_add_f32_dpp v2, v2, v2 quad_perm:[1,0,3,2] row_mask:0xf bank_mask:0xf
	s_waitcnt lgkmcnt(0)
	s_nop 1
	v_add_f32_dpp v2, v2, v2 quad_perm:[2,3,0,1] row_mask:0xf bank_mask:0xf
	s_waitcnt lgkmcnt(0)
	s_nop 1
	v_add_f32_dpp v2, v2, v2 row_half_mirror row_mask:0xf bank_mask:0xf
	s_waitcnt lgkmcnt(0)
	s_nop 1
	v_add_f32_dpp v2, v2, v2 row_mirror row_mask:0xf bank_mask:0xf
	ds_bpermute_b32 v3, v170, v2
	s_waitcnt lgkmcnt(0)
	v_add_f32_e32 v2, v2, v3
	v_fmamk_f32 v2, v2, 0x3c000000, v249
	v_cmp_gt_f32_e32 vcc, s5, v2
	v_mul_f32_e32 v3, 0x4b800000, v2
	s_nop 0
	v_cndmask_b32_e32 v2, v2, v3, vcc
	v_rsq_f32_e32 v2, v2
	s_nop 0
	v_mul_f32_e32 v3, 0x45800000, v2
	v_cndmask_b32_e32 v20, v2, v3, vcc
	v_or_b32_e32 v2, 3, v80
	v_mad_u64_u32 v[2:3], s[22:23], v2, s77, v[78:79]
	v_mul_f32_e32 v3, v4, v20
	v_mul_f32_e32 v3, v67, v3
	v_cvt_pk_bf16_f32 v3, v3, s0
	ds_write_b16 v2, v3
	v_mul_f32_e32 v3, v5, v20
	v_mul_f32_e32 v3, v71, v3
	v_cvt_pk_bf16_f32 v3, v3, s0
	ds_write_b16 v2, v3 offset:64
	v_mul_f32_e32 v3, v19, v20
	v_mul_f32_e32 v3, v73, v3
	v_cvt_pk_bf16_f32 v3, v3, s0
	ds_write_b16 v2, v3 offset:128
	v_mul_f32_e32 v3, v18, v20
	v_mul_f32_e32 v3, v75, v3
	v_cvt_pk_bf16_f32 v3, v3, s0
	ds_write_b16 v2, v3 offset:192
	ds_read2st64_b32 v[4:5], v79 offset0:8 offset1:9
	v_mov_b32_e32 v18, v6
	v_mov_b32_e32 v19, v54
	s_waitcnt lgkmcnt(0)
	v_lshlrev_b32_e32 v20, 16, v4
	v_and_b32_e32 v21, 0xffff0000, v4
	v_lshlrev_b32_e32 v35, 16, v5
	v_and_b32_e32 v34, 0xffff0000, v5
	v_pk_mul_f32 v[4:5], v[18:19], v[92:93] op_sel_hi:[1,0]
	s_nop 0
	v_pk_fma_f32 v[4:5], v[142:143], v[4:5], v[20:21] neg_lo:[1,0,0] neg_hi:[1,0,0]
	v_mov_b32_e32 v20, v38
	v_mov_b32_e32 v21, v22
	v_pk_mul_f32 v[20:21], v[20:21], v[92:93] op_sel_hi:[1,0]
	v_pk_mul_f32 v[18:19], v[4:5], v[4:5]
	v_pk_fma_f32 v[20:21], v[142:143], v[20:21], v[34:35] neg_lo:[1,0,0] neg_hi:[1,0,0]
	v_add_f32_e32 v3, v18, v19
	v_pk_mul_f32 v[34:35], v[20:21], v[20:21]
	s_nop 0
	v_add_f32_e32 v3, v3, v35
	v_add_f32_e32 v3, v34, v3
	s_waitcnt lgkmcnt(0)
	s_nop 1
	v_add_f32_dpp v3, v3, v3 quad_perm:[1,0,3,2] row_mask:0xf bank_mask:0xf
	s_waitcnt lgkmcnt(0)
	s_nop 1
	v_add_f32_dpp v3, v3, v3 quad_perm:[2,3,0,1] row_mask:0xf bank_mask:0xf
	s_waitcnt lgkmcnt(0)
	s_nop 1
	v_add_f32_dpp v3, v3, v3 row_half_mirror row_mask:0xf bank_mask:0xf
	s_waitcnt lgkmcnt(0)
	s_nop 1
	v_add_f32_dpp v3, v3, v3 row_mirror row_mask:0xf bank_mask:0xf
	ds_bpermute_b32 v6, v170, v3
	s_waitcnt lgkmcnt(0)
	v_add_f32_e32 v3, v3, v6
	v_fmamk_f32 v3, v3, 0x3c000000, v249
	v_mul_f32_e32 v6, 0x4b800000, v3
	v_cmp_gt_f32_e32 vcc, s5, v3
	s_nop 1
	v_cndmask_b32_e32 v3, v3, v6, vcc
	v_rsq_f32_e32 v3, v3
	s_nop 0
	v_mul_f32_e32 v6, 0x45800000, v3
	v_cndmask_b32_e32 v3, v3, v6, vcc
	v_mul_f32_e32 v4, v4, v3
	v_mul_f32_e32 v5, v5, v3
	v_mul_f32_e32 v6, v21, v3
	v_mul_f32_e32 v3, v20, v3
	v_mul_f32_e32 v4, v67, v4
	v_mul_f32_e32 v5, v71, v5
	v_mul_f32_e32 v6, v73, v6
	v_mul_f32_e32 v3, v75, v3
	v_cvt_pk_bf16_f32 v4, v4, s0
	v_cvt_pk_bf16_f32 v5, v5, s0
	v_cvt_pk_bf16_f32 v6, v6, s0
	v_cvt_pk_bf16_f32 v3, v3, s0
	ds_write_b16 v76, v4 offset:2176
	ds_write_b16 v76, v5 offset:2240
	ds_write_b16 v76, v6 offset:2304
	ds_write_b16 v76, v3 offset:2368
	ds_read2st64_b32 v[4:5], v79 offset0:10 offset1:11
	v_mov_b32_e32 v54, v7
	v_mov_b32_e32 v22, v39
	v_pk_mul_f32 v[20:21], v[22:23], v[90:91] op_sel_hi:[1,0]
	s_waitcnt lgkmcnt(0)
	v_lshlrev_b32_e32 v6, 16, v4
	v_and_b32_e32 v7, 0xffff0000, v4
	v_lshlrev_b32_e32 v19, 16, v5
	v_and_b32_e32 v18, 0xffff0000, v5
	v_pk_mul_f32 v[4:5], v[54:55], v[90:91] op_sel_hi:[1,0]
	v_pk_fma_f32 v[18:19], v[142:143], v[20:21], v[18:19] neg_lo:[1,0,0] neg_hi:[1,0,0]
	v_pk_fma_f32 v[4:5], v[142:143], v[4:5], v[6:7] neg_lo:[1,0,0] neg_hi:[1,0,0]
	v_pk_mul_f32 v[20:21], v[18:19], v[18:19]
	v_pk_mul_f32 v[6:7], v[4:5], v[4:5]
	s_nop 0
	v_add_f32_e32 v3, v6, v7
	v_add_f32_e32 v3, v3, v21
	v_add_f32_e32 v3, v20, v3
	s_waitcnt lgkmcnt(0)
	s_nop 1
	v_add_f32_dpp v3, v3, v3 quad_perm:[1,0,3,2] row_mask:0xf bank_mask:0xf
	s_waitcnt lgkmcnt(0)
	s_nop 1
	v_add_f32_dpp v3, v3, v3 quad_perm:[2,3,0,1] row_mask:0xf bank_mask:0xf
	s_waitcnt lgkmcnt(0)
	s_nop 1
	v_add_f32_dpp v3, v3, v3 row_half_mirror row_mask:0xf bank_mask:0xf
	s_waitcnt lgkmcnt(0)
	s_nop 1
	v_add_f32_dpp v3, v3, v3 row_mirror row_mask:0xf bank_mask:0xf
	ds_bpermute_b32 v6, v170, v3
	s_waitcnt lgkmcnt(0)
	v_add_f32_e32 v3, v3, v6
	v_fmamk_f32 v3, v3, 0x3c000000, v249
	v_mul_f32_e32 v6, 0x4b800000, v3
	v_cmp_gt_f32_e32 vcc, s5, v3
	s_nop 1
	v_cndmask_b32_e32 v3, v3, v6, vcc
	v_rsq_f32_e32 v3, v3
	s_nop 0
	v_mul_f32_e32 v6, 0x45800000, v3
	v_cndmask_b32_e32 v3, v3, v6, vcc
	v_mul_f32_e32 v4, v4, v3
	v_mul_f32_e32 v5, v5, v3
	v_mul_f32_e32 v6, v19, v3
	v_mul_f32_e32 v3, v18, v3
	v_mul_f32_e32 v4, v67, v4
	v_mul_f32_e32 v5, v71, v5
	v_mul_f32_e32 v6, v73, v6
	v_mul_f32_e32 v3, v75, v3
	v_cvt_pk_bf16_f32 v4, v4, s0
	v_cvt_pk_bf16_f32 v5, v5, s0
	v_cvt_pk_bf16_f32 v6, v6, s0
	v_cvt_pk_bf16_f32 v3, v3, s0
	ds_write_b16 v76, v4 offset:2448
	ds_write_b16 v76, v5 offset:2512
	ds_write_b16 v76, v6 offset:2576
	ds_write_b16 v76, v3 offset:2640
	ds_read2st64_b32 v[4:5], v79 offset0:12 offset1:13
	v_mov_b32_e32 v6, v8
	v_mov_b32_e32 v7, v56
	s_waitcnt lgkmcnt(0)
	v_lshlrev_b32_e32 v18, 16, v4
	v_and_b32_e32 v19, 0xffff0000, v4
	v_lshlrev_b32_e32 v21, 16, v5
	v_and_b32_e32 v20, 0xffff0000, v5
	v_pk_mul_f32 v[4:5], v[6:7], v[88:89] op_sel_hi:[1,0]
	s_nop 0
	v_pk_fma_f32 v[4:5], v[142:143], v[4:5], v[18:19] neg_lo:[1,0,0] neg_hi:[1,0,0]
	v_mov_b32_e32 v18, v40
	v_mov_b32_e32 v19, v24
	v_pk_mul_f32 v[18:19], v[18:19], v[88:89] op_sel_hi:[1,0]
	v_pk_mul_f32 v[6:7], v[4:5], v[4:5]
	v_pk_fma_f32 v[18:19], v[142:143], v[18:19], v[20:21] neg_lo:[1,0,0] neg_hi:[1,0,0]
	v_add_f32_e32 v3, v6, v7
	v_pk_mul_f32 v[20:21], v[18:19], v[18:19]
	s_nop 0
	v_add_f32_e32 v3, v3, v21
	v_add_f32_e32 v3, v20, v3
	s_waitcnt lgkmcnt(0)
	s_nop 1
	v_add_f32_dpp v3, v3, v3 quad_perm:[1,0,3,2] row_mask:0xf bank_mask:0xf
	s_waitcnt lgkmcnt(0)
	s_nop 1
	v_add_f32_dpp v3, v3, v3 quad_perm:[2,3,0,1] row_mask:0xf bank_mask:0xf
	s_waitcnt lgkmcnt(0)
	s_nop 1
	v_add_f32_dpp v3, v3, v3 row_half_mirror row_mask:0xf bank_mask:0xf
	s_waitcnt lgkmcnt(0)
	s_nop 1
	v_add_f32_dpp v3, v3, v3 row_mirror row_mask:0xf bank_mask:0xf
	ds_bpermute_b32 v6, v170, v3
	s_waitcnt lgkmcnt(0)
	v_add_f32_e32 v3, v3, v6
	v_fmamk_f32 v3, v3, 0x3c000000, v249
	v_mul_f32_e32 v6, 0x4b800000, v3
	v_cmp_gt_f32_e32 vcc, s5, v3
	s_nop 1
	v_cndmask_b32_e32 v3, v3, v6, vcc
	v_rsq_f32_e32 v3, v3
	s_nop 0
	v_mul_f32_e32 v6, 0x45800000, v3
	v_cndmask_b32_e32 v3, v3, v6, vcc
	v_mul_f32_e32 v4, v4, v3
	v_mul_f32_e32 v5, v5, v3
	v_mul_f32_e32 v6, v19, v3
	v_mul_f32_e32 v3, v18, v3
	v_mul_f32_e32 v4, v67, v4
	v_mul_f32_e32 v5, v71, v5
	v_mul_f32_e32 v6, v73, v6
	v_mul_f32_e32 v3, v75, v3
	v_cvt_pk_bf16_f32 v4, v4, s0
	v_cvt_pk_bf16_f32 v5, v5, s0
	v_cvt_pk_bf16_f32 v6, v6, s0
	v_cvt_pk_bf16_f32 v3, v3, s0
	ds_write_b16 v76, v4 offset:2720
	ds_write_b16 v76, v5 offset:2784
	ds_write_b16 v76, v6 offset:2848
	ds_write_b16 v76, v3 offset:2912
	ds_read2st64_b32 v[4:5], v79 offset0:14 offset1:15
	v_mov_b32_e32 v56, v9
	v_mov_b32_e32 v24, v41
	v_pk_mul_f32 v[18:19], v[24:25], v[86:87] op_sel_hi:[1,0]
	s_waitcnt lgkmcnt(0)
	v_lshlrev_b32_e32 v6, 16, v4
	v_and_b32_e32 v7, 0xffff0000, v4
	v_lshlrev_b32_e32 v9, 16, v5
	v_and_b32_e32 v8, 0xffff0000, v5
	v_pk_mul_f32 v[4:5], v[56:57], v[86:87] op_sel_hi:[1,0]
	v_pk_fma_f32 v[8:9], v[142:143], v[18:19], v[8:9] neg_lo:[1,0,0] neg_hi:[1,0,0]
	v_pk_fma_f32 v[4:5], v[142:143], v[4:5], v[6:7] neg_lo:[1,0,0] neg_hi:[1,0,0]
	v_pk_mul_f32 v[18:19], v[8:9], v[8:9]
	v_pk_mul_f32 v[6:7], v[4:5], v[4:5]
	s_nop 0
	v_add_f32_e32 v3, v6, v7
	v_add_f32_e32 v3, v3, v19
	v_add_f32_e32 v3, v18, v3
	s_waitcnt lgkmcnt(0)
	s_nop 1
	v_add_f32_dpp v3, v3, v3 quad_perm:[1,0,3,2] row_mask:0xf bank_mask:0xf
	s_waitcnt lgkmcnt(0)
	s_nop 1
	v_add_f32_dpp v3, v3, v3 quad_perm:[2,3,0,1] row_mask:0xf bank_mask:0xf
	s_waitcnt lgkmcnt(0)
	s_nop 1
	v_add_f32_dpp v3, v3, v3 row_half_mirror row_mask:0xf bank_mask:0xf
	s_waitcnt lgkmcnt(0)
	s_nop 1
	v_add_f32_dpp v3, v3, v3 row_mirror row_mask:0xf bank_mask:0xf
	ds_bpermute_b32 v6, v170, v3
	s_waitcnt lgkmcnt(0)
	v_add_f32_e32 v3, v3, v6
	v_fmamk_f32 v3, v3, 0x3c000000, v249
	v_mul_f32_e32 v6, 0x4b800000, v3
	v_cmp_gt_f32_e32 vcc, s5, v3
	s_nop 1
	v_cndmask_b32_e32 v3, v3, v6, vcc
	v_rsq_f32_e32 v3, v3
	s_nop 0
	v_mul_f32_e32 v6, 0x45800000, v3
	v_cndmask_b32_e32 v3, v3, v6, vcc
	v_mul_f32_e32 v4, v4, v3
	v_mul_f32_e32 v5, v5, v3
	v_mul_f32_e32 v6, v9, v3
	v_mul_f32_e32 v3, v8, v3
	v_mul_f32_e32 v4, v67, v4
	v_mul_f32_e32 v5, v71, v5
	v_mul_f32_e32 v6, v73, v6
	v_mul_f32_e32 v3, v75, v3
	v_cvt_pk_bf16_f32 v4, v4, s0
	v_cvt_pk_bf16_f32 v5, v5, s0
	v_cvt_pk_bf16_f32 v6, v6, s0
	v_cvt_pk_bf16_f32 v3, v3, s0
	ds_write_b16 v2, v4 offset:2176
	ds_write_b16 v2, v5 offset:2240
	ds_write_b16 v2, v6 offset:2304
	ds_write_b16 v2, v3 offset:2368
	ds_read2st64_b32 v[4:5], v79 offset0:16 offset1:17
	v_mov_b32_e32 v6, v10
	v_mov_b32_e32 v7, v58
	s_waitcnt lgkmcnt(0)
	v_lshlrev_b32_e32 v8, 16, v4
	v_and_b32_e32 v9, 0xffff0000, v4
	v_lshlrev_b32_e32 v19, 16, v5
	v_and_b32_e32 v18, 0xffff0000, v5
	v_pk_mul_f32 v[4:5], v[6:7], v[84:85] op_sel_hi:[1,0]
	s_nop 0
	v_pk_fma_f32 v[4:5], v[142:143], v[4:5], v[8:9] neg_lo:[1,0,0] neg_hi:[1,0,0]
	v_mov_b32_e32 v8, v42
	v_mov_b32_e32 v9, v26
	v_pk_mul_f32 v[8:9], v[8:9], v[84:85] op_sel_hi:[1,0]
	v_pk_mul_f32 v[6:7], v[4:5], v[4:5]
	v_pk_fma_f32 v[8:9], v[142:143], v[8:9], v[18:19] neg_lo:[1,0,0] neg_hi:[1,0,0]
	v_add_f32_e32 v3, v6, v7
	v_pk_mul_f32 v[18:19], v[8:9], v[8:9]
	s_nop 0
	v_add_f32_e32 v3, v3, v19
	v_add_f32_e32 v3, v18, v3
	s_waitcnt lgkmcnt(0)
	s_nop 1
	v_add_f32_dpp v3, v3, v3 quad_perm:[1,0,3,2] row_mask:0xf bank_mask:0xf
	s_waitcnt lgkmcnt(0)
	s_nop 1
	v_add_f32_dpp v3, v3, v3 quad_perm:[2,3,0,1] row_mask:0xf bank_mask:0xf
	s_waitcnt lgkmcnt(0)
	s_nop 1
	v_add_f32_dpp v3, v3, v3 row_half_mirror row_mask:0xf bank_mask:0xf
	s_waitcnt lgkmcnt(0)
	s_nop 1
	v_add_f32_dpp v3, v3, v3 row_mirror row_mask:0xf bank_mask:0xf
	ds_bpermute_b32 v6, v170, v3
	s_waitcnt lgkmcnt(0)
	v_add_f32_e32 v3, v3, v6
	v_fmamk_f32 v3, v3, 0x3c000000, v249
	v_mul_f32_e32 v6, 0x4b800000, v3
	v_cmp_gt_f32_e32 vcc, s5, v3
	s_nop 1
	v_cndmask_b32_e32 v3, v3, v6, vcc
	v_rsq_f32_e32 v3, v3
	s_nop 0
	v_mul_f32_e32 v6, 0x45800000, v3
	v_cndmask_b32_e32 v3, v3, v6, vcc
	v_mul_f32_e32 v4, v4, v3
	v_mul_f32_e32 v5, v5, v3
	v_mul_f32_e32 v6, v9, v3
	v_mul_f32_e32 v3, v8, v3
	v_mul_f32_e32 v4, v67, v4
	v_mul_f32_e32 v5, v71, v5
	v_mul_f32_e32 v6, v73, v6
	v_mul_f32_e32 v3, v75, v3
	v_cvt_pk_bf16_f32 v4, v4, s0
	v_cvt_pk_bf16_f32 v5, v5, s0
	v_cvt_pk_bf16_f32 v6, v6, s0
	v_cvt_pk_bf16_f32 v3, v3, s0
	ds_write_b16 v76, v4 offset:4352
	ds_write_b16 v76, v5 offset:4416
	ds_write_b16 v76, v6 offset:4480
	ds_write_b16 v76, v3 offset:4544
	ds_read2st64_b32 v[4:5], v79 offset0:18 offset1:19
	v_mov_b32_e32 v58, v11
	v_mov_b32_e32 v26, v43
	v_pk_mul_f32 v[10:11], v[26:27], v[82:83] op_sel_hi:[1,0]
	s_waitcnt lgkmcnt(0)
	v_lshlrev_b32_e32 v6, 16, v4
	v_and_b32_e32 v7, 0xffff0000, v4
	v_lshlrev_b32_e32 v9, 16, v5
	v_and_b32_e32 v8, 0xffff0000, v5
	v_pk_mul_f32 v[4:5], v[58:59], v[82:83] op_sel_hi:[1,0]
	v_pk_fma_f32 v[8:9], v[142:143], v[10:11], v[8:9] neg_lo:[1,0,0] neg_hi:[1,0,0]
	v_pk_fma_f32 v[4:5], v[142:143], v[4:5], v[6:7] neg_lo:[1,0,0] neg_hi:[1,0,0]
	v_pk_mul_f32 v[10:11], v[8:9], v[8:9]
	v_pk_mul_f32 v[6:7], v[4:5], v[4:5]
	s_nop 0
	v_add_f32_e32 v3, v6, v7
	v_add_f32_e32 v3, v3, v11
	v_add_f32_e32 v3, v10, v3
	s_waitcnt lgkmcnt(0)
	s_nop 1
	v_add_f32_dpp v3, v3, v3 quad_perm:[1,0,3,2] row_mask:0xf bank_mask:0xf
	s_waitcnt lgkmcnt(0)
	s_nop 1
	v_add_f32_dpp v3, v3, v3 quad_perm:[2,3,0,1] row_mask:0xf bank_mask:0xf
	s_waitcnt lgkmcnt(0)
	s_nop 1
	v_add_f32_dpp v3, v3, v3 row_half_mirror row_mask:0xf bank_mask:0xf
	s_waitcnt lgkmcnt(0)
	s_nop 1
	v_add_f32_dpp v3, v3, v3 row_mirror row_mask:0xf bank_mask:0xf
	ds_bpermute_b32 v6, v170, v3
	s_waitcnt lgkmcnt(0)
	v_add_f32_e32 v3, v3, v6
	v_fmamk_f32 v3, v3, 0x3c000000, v249
	v_mul_f32_e32 v6, 0x4b800000, v3
	v_cmp_gt_f32_e32 vcc, s5, v3
	s_nop 1
	v_cndmask_b32_e32 v3, v3, v6, vcc
	v_rsq_f32_e32 v3, v3
	s_nop 0
	v_mul_f32_e32 v6, 0x45800000, v3
	v_cndmask_b32_e32 v3, v3, v6, vcc
	v_mul_f32_e32 v4, v4, v3
	v_mul_f32_e32 v5, v5, v3
	v_mul_f32_e32 v6, v9, v3
	v_mul_f32_e32 v3, v8, v3
	v_mul_f32_e32 v4, v67, v4
	v_mul_f32_e32 v5, v71, v5
	v_mul_f32_e32 v6, v73, v6
	v_mul_f32_e32 v3, v75, v3
	v_cvt_pk_bf16_f32 v4, v4, s0
	v_cvt_pk_bf16_f32 v5, v5, s0
	v_cvt_pk_bf16_f32 v6, v6, s0
	v_cvt_pk_bf16_f32 v3, v3, s0
	ds_write_b16 v76, v4 offset:4624
	ds_write_b16 v76, v5 offset:4688
	ds_write_b16 v76, v6 offset:4752
	ds_write_b16 v76, v3 offset:4816
	ds_read2st64_b32 v[4:5], v79 offset0:20 offset1:21
	v_mov_b32_e32 v6, v12
	v_mov_b32_e32 v7, v60
	s_waitcnt lgkmcnt(0)
	v_lshlrev_b32_e32 v8, 16, v4
	v_and_b32_e32 v9, 0xffff0000, v4
	v_lshlrev_b32_e32 v11, 16, v5
	v_and_b32_e32 v10, 0xffff0000, v5
	v_pk_mul_f32 v[4:5], v[6:7], v[74:75] op_sel_hi:[1,0]
	s_nop 0
	v_pk_fma_f32 v[4:5], v[142:143], v[4:5], v[8:9] neg_lo:[1,0,0] neg_hi:[1,0,0]
	v_mov_b32_e32 v8, v44
	v_mov_b32_e32 v9, v28
	v_pk_mul_f32 v[8:9], v[8:9], v[74:75] op_sel_hi:[1,0]
	v_pk_mul_f32 v[6:7], v[4:5], v[4:5]
	v_pk_fma_f32 v[8:9], v[142:143], v[8:9], v[10:11] neg_lo:[1,0,0] neg_hi:[1,0,0]
	v_add_f32_e32 v3, v6, v7
	v_pk_mul_f32 v[10:11], v[8:9], v[8:9]
	s_nop 0
	v_add_f32_e32 v3, v3, v11
	v_add_f32_e32 v3, v10, v3
	s_waitcnt lgkmcnt(0)
	s_nop 1
	v_add_f32_dpp v3, v3, v3 quad_perm:[1,0,3,2] row_mask:0xf bank_mask:0xf
	s_waitcnt lgkmcnt(0)
	s_nop 1
	v_add_f32_dpp v3, v3, v3 quad_perm:[2,3,0,1] row_mask:0xf bank_mask:0xf
	s_waitcnt lgkmcnt(0)
	s_nop 1
	v_add_f32_dpp v3, v3, v3 row_half_mirror row_mask:0xf bank_mask:0xf
	s_waitcnt lgkmcnt(0)
	s_nop 1
	v_add_f32_dpp v3, v3, v3 row_mirror row_mask:0xf bank_mask:0xf
	ds_bpermute_b32 v6, v170, v3
	s_waitcnt lgkmcnt(0)
	v_add_f32_e32 v3, v3, v6
	v_fmamk_f32 v3, v3, 0x3c000000, v249
	v_mul_f32_e32 v6, 0x4b800000, v3
	v_cmp_gt_f32_e32 vcc, s5, v3
	s_nop 1
	v_cndmask_b32_e32 v3, v3, v6, vcc
	v_rsq_f32_e32 v3, v3
	s_nop 0
	v_mul_f32_e32 v6, 0x45800000, v3
	v_cndmask_b32_e32 v3, v3, v6, vcc
	v_mul_f32_e32 v4, v4, v3
	v_mul_f32_e32 v5, v5, v3
	v_mul_f32_e32 v6, v9, v3
	v_mul_f32_e32 v3, v8, v3
	v_mul_f32_e32 v4, v67, v4
	v_mul_f32_e32 v5, v71, v5
	v_mul_f32_e32 v6, v73, v6
	v_mul_f32_e32 v3, v75, v3
	v_cvt_pk_bf16_f32 v4, v4, s0
	v_cvt_pk_bf16_f32 v5, v5, s0
	v_cvt_pk_bf16_f32 v6, v6, s0
	v_cvt_pk_bf16_f32 v3, v3, s0
	ds_write_b16 v76, v4 offset:4896
	ds_write_b16 v76, v5 offset:4960
	ds_write_b16 v76, v6 offset:5024
	ds_write_b16 v76, v3 offset:5088
	ds_read2st64_b32 v[4:5], v79 offset0:22 offset1:23
	v_mov_b32_e32 v60, v13
	v_mov_b32_e32 v28, v45
	v_pk_mul_f32 v[10:11], v[28:29], v[72:73] op_sel_hi:[1,0]
	s_waitcnt lgkmcnt(0)
	v_lshlrev_b32_e32 v6, 16, v4
	v_and_b32_e32 v7, 0xffff0000, v4
	v_lshlrev_b32_e32 v9, 16, v5
	v_and_b32_e32 v8, 0xffff0000, v5
	v_pk_mul_f32 v[4:5], v[60:61], v[72:73] op_sel_hi:[1,0]
	v_pk_fma_f32 v[8:9], v[142:143], v[10:11], v[8:9] neg_lo:[1,0,0] neg_hi:[1,0,0]
	v_pk_fma_f32 v[4:5], v[142:143], v[4:5], v[6:7] neg_lo:[1,0,0] neg_hi:[1,0,0]
	v_pk_mul_f32 v[10:11], v[8:9], v[8:9]
	v_pk_mul_f32 v[6:7], v[4:5], v[4:5]
	s_nop 0
	v_add_f32_e32 v3, v6, v7
	v_add_f32_e32 v3, v3, v11
	v_add_f32_e32 v3, v10, v3
	s_waitcnt lgkmcnt(0)
	s_nop 1
	v_add_f32_dpp v3, v3, v3 quad_perm:[1,0,3,2] row_mask:0xf bank_mask:0xf
	s_waitcnt lgkmcnt(0)
	s_nop 1
	v_add_f32_dpp v3, v3, v3 quad_perm:[2,3,0,1] row_mask:0xf bank_mask:0xf
	s_waitcnt lgkmcnt(0)
	s_nop 1
	v_add_f32_dpp v3, v3, v3 row_half_mirror row_mask:0xf bank_mask:0xf
	s_waitcnt lgkmcnt(0)
	s_nop 1
	v_add_f32_dpp v3, v3, v3 row_mirror row_mask:0xf bank_mask:0xf
	ds_bpermute_b32 v6, v170, v3
	s_waitcnt lgkmcnt(0)
	v_add_f32_e32 v3, v3, v6
	v_fmamk_f32 v3, v3, 0x3c000000, v249
	v_mul_f32_e32 v6, 0x4b800000, v3
	v_cmp_gt_f32_e32 vcc, s5, v3
	s_nop 1
	v_cndmask_b32_e32 v3, v3, v6, vcc
	v_rsq_f32_e32 v3, v3
	s_nop 0
	v_mul_f32_e32 v6, 0x45800000, v3
	v_cndmask_b32_e32 v3, v3, v6, vcc
	v_mul_f32_e32 v4, v4, v3
	v_mul_f32_e32 v5, v5, v3
	v_mul_f32_e32 v6, v9, v3
	v_mul_f32_e32 v3, v8, v3
	v_mul_f32_e32 v4, v67, v4
	v_mul_f32_e32 v5, v71, v5
	v_mul_f32_e32 v6, v73, v6
	v_mul_f32_e32 v3, v75, v3
	v_cvt_pk_bf16_f32 v4, v4, s0
	v_cvt_pk_bf16_f32 v5, v5, s0
	v_cvt_pk_bf16_f32 v6, v6, s0
	v_cvt_pk_bf16_f32 v3, v3, s0
	ds_write_b16 v2, v4 offset:4352
	ds_write_b16 v2, v5 offset:4416
	ds_write_b16 v2, v6 offset:4480
	ds_write_b16 v2, v3 offset:4544
	ds_read2st64_b32 v[4:5], v79 offset0:24 offset1:25
	v_mov_b32_e32 v6, v14
	v_mov_b32_e32 v7, v62
	s_waitcnt lgkmcnt(0)
	v_lshlrev_b32_e32 v8, 16, v4
	v_and_b32_e32 v9, 0xffff0000, v4
	v_lshlrev_b32_e32 v11, 16, v5
	v_and_b32_e32 v10, 0xffff0000, v5
	v_pk_mul_f32 v[4:5], v[6:7], v[70:71] op_sel_hi:[1,0]
	s_nop 0
	v_pk_fma_f32 v[4:5], v[142:143], v[4:5], v[8:9] neg_lo:[1,0,0] neg_hi:[1,0,0]
	v_mov_b32_e32 v8, v46
	v_mov_b32_e32 v9, v30
	v_pk_mul_f32 v[8:9], v[8:9], v[70:71] op_sel_hi:[1,0]
	v_pk_mul_f32 v[6:7], v[4:5], v[4:5]
	v_pk_fma_f32 v[8:9], v[142:143], v[8:9], v[10:11] neg_lo:[1,0,0] neg_hi:[1,0,0]
	v_add_f32_e32 v3, v6, v7
	v_pk_mul_f32 v[10:11], v[8:9], v[8:9]
	s_nop 0
	v_add_f32_e32 v3, v3, v11
	v_add_f32_e32 v3, v10, v3
	s_waitcnt lgkmcnt(0)
	s_nop 1
	v_add_f32_dpp v3, v3, v3 quad_perm:[1,0,3,2] row_mask:0xf bank_mask:0xf
	s_waitcnt lgkmcnt(0)
	s_nop 1
	v_add_f32_dpp v3, v3, v3 quad_perm:[2,3,0,1] row_mask:0xf bank_mask:0xf
	s_waitcnt lgkmcnt(0)
	s_nop 1
	v_add_f32_dpp v3, v3, v3 row_half_mirror row_mask:0xf bank_mask:0xf
	s_waitcnt lgkmcnt(0)
	s_nop 1
	v_add_f32_dpp v3, v3, v3 row_mirror row_mask:0xf bank_mask:0xf
	ds_bpermute_b32 v6, v170, v3
	s_waitcnt lgkmcnt(0)
	v_add_f32_e32 v3, v3, v6
	v_fmamk_f32 v3, v3, 0x3c000000, v249
	v_mul_f32_e32 v6, 0x4b800000, v3
	v_cmp_gt_f32_e32 vcc, s5, v3
	s_nop 1
	v_cndmask_b32_e32 v3, v3, v6, vcc
	v_rsq_f32_e32 v3, v3
	s_nop 0
	v_mul_f32_e32 v6, 0x45800000, v3
	v_cndmask_b32_e32 v3, v3, v6, vcc
	v_mul_f32_e32 v4, v4, v3
	v_mul_f32_e32 v5, v5, v3
	v_mul_f32_e32 v6, v9, v3
	v_mul_f32_e32 v3, v8, v3
	v_mul_f32_e32 v4, v67, v4
	v_mul_f32_e32 v5, v71, v5
	v_mul_f32_e32 v6, v73, v6
	v_mul_f32_e32 v3, v75, v3
	v_cvt_pk_bf16_f32 v4, v4, s0
	v_cvt_pk_bf16_f32 v5, v5, s0
	v_cvt_pk_bf16_f32 v6, v6, s0
	v_cvt_pk_bf16_f32 v3, v3, s0
	ds_write_b16 v76, v4 offset:6528
	ds_write_b16 v76, v5 offset:6592
	ds_write_b16 v76, v6 offset:6656
	ds_write_b16 v76, v3 offset:6720
	ds_read2st64_b32 v[4:5], v79 offset0:26 offset1:27
	v_mov_b32_e32 v62, v15
	v_mov_b32_e32 v30, v47
	v_pk_mul_f32 v[10:11], v[30:31], v[68:69] op_sel_hi:[1,0]
	s_waitcnt lgkmcnt(0)
	v_lshlrev_b32_e32 v6, 16, v4
	v_and_b32_e32 v7, 0xffff0000, v4
	v_lshlrev_b32_e32 v9, 16, v5
	v_and_b32_e32 v8, 0xffff0000, v5
	v_pk_mul_f32 v[4:5], v[62:63], v[68:69] op_sel_hi:[1,0]
	v_pk_fma_f32 v[8:9], v[142:143], v[10:11], v[8:9] neg_lo:[1,0,0] neg_hi:[1,0,0]
	v_pk_fma_f32 v[4:5], v[142:143], v[4:5], v[6:7] neg_lo:[1,0,0] neg_hi:[1,0,0]
	v_pk_mul_f32 v[10:11], v[8:9], v[8:9]
	v_pk_mul_f32 v[6:7], v[4:5], v[4:5]
	s_nop 0
	v_add_f32_e32 v3, v6, v7
	v_add_f32_e32 v3, v3, v11
	v_add_f32_e32 v3, v10, v3
	s_waitcnt lgkmcnt(0)
	s_nop 1
	v_add_f32_dpp v3, v3, v3 quad_perm:[1,0,3,2] row_mask:0xf bank_mask:0xf
	s_waitcnt lgkmcnt(0)
	s_nop 1
	v_add_f32_dpp v3, v3, v3 quad_perm:[2,3,0,1] row_mask:0xf bank_mask:0xf
	s_waitcnt lgkmcnt(0)
	s_nop 1
	v_add_f32_dpp v3, v3, v3 row_half_mirror row_mask:0xf bank_mask:0xf
	s_waitcnt lgkmcnt(0)
	s_nop 1
	v_add_f32_dpp v3, v3, v3 row_mirror row_mask:0xf bank_mask:0xf
	ds_bpermute_b32 v6, v170, v3
	s_waitcnt lgkmcnt(0)
	v_add_f32_e32 v3, v3, v6
	v_fmamk_f32 v3, v3, 0x3c000000, v249
	v_mul_f32_e32 v6, 0x4b800000, v3
	v_cmp_gt_f32_e32 vcc, s5, v3
	s_nop 1
	v_cndmask_b32_e32 v3, v3, v6, vcc
	v_rsq_f32_e32 v3, v3
	s_nop 0
	v_mul_f32_e32 v6, 0x45800000, v3
	v_cndmask_b32_e32 v3, v3, v6, vcc
	v_mul_f32_e32 v4, v4, v3
	v_mul_f32_e32 v5, v5, v3
	v_mul_f32_e32 v6, v9, v3
	v_mul_f32_e32 v3, v8, v3
	v_mul_f32_e32 v4, v67, v4
	v_mul_f32_e32 v5, v71, v5
	v_mul_f32_e32 v6, v73, v6
	v_mul_f32_e32 v3, v75, v3
	v_cvt_pk_bf16_f32 v4, v4, s0
	v_cvt_pk_bf16_f32 v5, v5, s0
	v_cvt_pk_bf16_f32 v6, v6, s0
	v_cvt_pk_bf16_f32 v3, v3, s0
	ds_write_b16 v76, v4 offset:6800
	ds_write_b16 v76, v5 offset:6864
	ds_write_b16 v76, v6 offset:6928
	ds_write_b16 v76, v3 offset:6992
	ds_read2st64_b32 v[4:5], v79 offset0:28 offset1:29
	v_mov_b32_e32 v6, v16
	v_mov_b32_e32 v7, v64
	s_waitcnt lgkmcnt(0)
	v_lshlrev_b32_e32 v8, 16, v4
	v_and_b32_e32 v9, 0xffff0000, v4
	v_lshlrev_b32_e32 v11, 16, v5
	v_and_b32_e32 v10, 0xffff0000, v5
	v_pk_mul_f32 v[4:5], v[6:7], v[66:67] op_sel_hi:[1,0]
	s_nop 0
	v_pk_fma_f32 v[4:5], v[142:143], v[4:5], v[8:9] neg_lo:[1,0,0] neg_hi:[1,0,0]
	v_mov_b32_e32 v8, v48
	v_mov_b32_e32 v9, v32
	v_pk_mul_f32 v[8:9], v[8:9], v[66:67] op_sel_hi:[1,0]
	v_pk_mul_f32 v[6:7], v[4:5], v[4:5]
	v_pk_fma_f32 v[8:9], v[142:143], v[8:9], v[10:11] neg_lo:[1,0,0] neg_hi:[1,0,0]
	v_add_f32_e32 v3, v6, v7
	v_pk_mul_f32 v[10:11], v[8:9], v[8:9]
	s_nop 0
	v_add_f32_e32 v3, v3, v11
	v_add_f32_e32 v3, v10, v3
	s_waitcnt lgkmcnt(0)
	s_nop 1
	v_add_f32_dpp v3, v3, v3 quad_perm:[1,0,3,2] row_mask:0xf bank_mask:0xf
	s_waitcnt lgkmcnt(0)
	s_nop 1
	v_add_f32_dpp v3, v3, v3 quad_perm:[2,3,0,1] row_mask:0xf bank_mask:0xf
	s_waitcnt lgkmcnt(0)
	s_nop 1
	v_add_f32_dpp v3, v3, v3 row_half_mirror row_mask:0xf bank_mask:0xf
	s_waitcnt lgkmcnt(0)
	s_nop 1
	v_add_f32_dpp v3, v3, v3 row_mirror row_mask:0xf bank_mask:0xf
	ds_bpermute_b32 v6, v170, v3
	s_waitcnt lgkmcnt(0)
	v_add_f32_e32 v3, v3, v6
	v_fmamk_f32 v3, v3, 0x3c000000, v249
	v_mul_f32_e32 v6, 0x4b800000, v3
	v_cmp_gt_f32_e32 vcc, s5, v3
	s_nop 1
	v_cndmask_b32_e32 v3, v3, v6, vcc
	v_rsq_f32_e32 v3, v3
	s_nop 0
	v_mul_f32_e32 v6, 0x45800000, v3
	v_cndmask_b32_e32 v3, v3, v6, vcc
	v_mul_f32_e32 v4, v4, v3
	v_mul_f32_e32 v5, v5, v3
	v_mul_f32_e32 v6, v9, v3
	v_mul_f32_e32 v3, v8, v3
	v_mul_f32_e32 v4, v67, v4
	v_mul_f32_e32 v5, v71, v5
	v_mul_f32_e32 v6, v73, v6
	v_mul_f32_e32 v3, v75, v3
	v_cvt_pk_bf16_f32 v4, v4, s0
	v_cvt_pk_bf16_f32 v5, v5, s0
	v_cvt_pk_bf16_f32 v6, v6, s0
	v_cvt_pk_bf16_f32 v3, v3, s0
	ds_write_b16 v76, v4 offset:7072
	ds_write_b16 v76, v5 offset:7136
	ds_write_b16 v76, v6 offset:7200
	ds_write_b16 v76, v3 offset:7264
	ds_read2st64_b32 v[4:5], v79 offset0:30 offset1:31
	v_mov_b32_e32 v64, v17
	v_mov_b32_e32 v32, v49
	v_pk_mul_f32 v[10:11], v[32:33], v[0:1] op_sel_hi:[1,0]
	s_waitcnt lgkmcnt(0)
	v_lshlrev_b32_e32 v6, 16, v4
	v_and_b32_e32 v7, 0xffff0000, v4
	v_lshlrev_b32_e32 v9, 16, v5
	v_and_b32_e32 v8, 0xffff0000, v5
	v_pk_mul_f32 v[4:5], v[64:65], v[0:1] op_sel_hi:[1,0]
	v_pk_fma_f32 v[8:9], v[142:143], v[10:11], v[8:9] neg_lo:[1,0,0] neg_hi:[1,0,0]
	v_pk_fma_f32 v[4:5], v[142:143], v[4:5], v[6:7] neg_lo:[1,0,0] neg_hi:[1,0,0]
	v_pk_mul_f32 v[10:11], v[8:9], v[8:9]
	v_pk_mul_f32 v[6:7], v[4:5], v[4:5]
	s_nop 0
	v_add_f32_e32 v0, v6, v7
	v_add_f32_e32 v0, v0, v11
	v_add_f32_e32 v0, v10, v0
	s_waitcnt lgkmcnt(0)
	s_nop 1
	v_add_f32_dpp v0, v0, v0 quad_perm:[1,0,3,2] row_mask:0xf bank_mask:0xf
	s_waitcnt lgkmcnt(0)
	s_nop 1
	v_add_f32_dpp v0, v0, v0 quad_perm:[2,3,0,1] row_mask:0xf bank_mask:0xf
	s_waitcnt lgkmcnt(0)
	s_nop 1
	v_add_f32_dpp v0, v0, v0 row_half_mirror row_mask:0xf bank_mask:0xf
	s_waitcnt lgkmcnt(0)
	s_nop 1
	v_add_f32_dpp v0, v0, v0 row_mirror row_mask:0xf bank_mask:0xf
	ds_bpermute_b32 v3, v170, v0
	s_waitcnt lgkmcnt(0)
	v_add_f32_e32 v0, v0, v3
	v_fmamk_f32 v0, v0, 0x3c000000, v249
	v_mul_f32_e32 v3, 0x4b800000, v0
	v_cmp_gt_f32_e32 vcc, s5, v0
	s_nop 1
	v_cndmask_b32_e32 v0, v0, v3, vcc
	v_rsq_f32_e32 v0, v0
	s_nop 0
	v_mul_f32_e32 v3, 0x45800000, v0
	v_cndmask_b32_e32 v0, v0, v3, vcc
	v_mul_f32_e32 v3, v4, v0
	v_mul_f32_e32 v4, v5, v0
	v_mul_f32_e32 v5, v9, v0
	v_mul_f32_e32 v0, v8, v0
	v_mul_f32_e32 v3, v67, v3
	v_mul_f32_e32 v4, v71, v4
	v_mul_f32_e32 v5, v73, v5
	v_mul_f32_e32 v0, v75, v0
	v_cvt_pk_bf16_f32 v3, v3, s0
	v_cvt_pk_bf16_f32 v4, v4, s0
	v_cvt_pk_bf16_f32 v5, v5, s0
	v_cvt_pk_bf16_f32 v0, v0, s0
	ds_write_b16 v2, v3 offset:6528
	ds_write_b16 v2, v4 offset:6592
	ds_write_b16 v2, v5 offset:6656
	ds_write_b16 v2, v0 offset:6720
	s_lshl_b32 s60, s70, 12
	s_add_i32 s22, s1, s60
	s_ashr_i32 s23, s22, 31
	s_lshl_b64 s[22:23], s[22:23], 11
	s_add_u32 s1, s41, s22
	s_addc_u32 s5, s66, s23
	s_lshl_b32 s61, s71, 1
	s_add_u32 s22, s1, s61
	v_ashrrev_i32_e32 v6, 4, v162
	v_lshlrev_b32_e32 v0, 4, v162
	s_addc_u32 s23, s5, 0
	v_and_b32_e32 v0, 0xf0, v0
	v_mul_lo_u32 v2, v6, s77
	s_waitcnt lgkmcnt(0)
	v_lshl_add_u64 v[8:9], s[22:23], 0, v[0:1]
	v_add3_u32 v0, v69, v0, v2
	ds_read_b128 v[2:5], v0
	v_ashrrev_i32_e32 v7, 31, v6
	v_lshlrev_b64 v[6:7], 11, v[6:7]
	v_lshl_add_u64 v[10:11], v[8:9], 0, v[6:7]
	ds_read_b128 v[6:9], v0 offset:1088
	s_waitcnt lgkmcnt(1)
	global_store_dwordx4 v[10:11], v[2:5], off sc1
	v_mov_b32_e32 v172, v226
	s_movk_i32 s26, 0x1800
	v_add_co_u32_e32 v2, vcc, s88, v10
	v_mov_b32_e32 v145, v1
	s_nop 0
	v_addc_co_u32_e32 v3, vcc, 0, v11, vcc
	s_waitcnt lgkmcnt(0)
	global_store_dwordx4 v[2:3], v[6:9], off sc1
	ds_read_b128 v[2:5], v0 offset:2176
	ds_read_b128 v[6:9], v0 offset:3264
	v_add_co_u32_e32 v12, vcc, s14, v10
	v_readlane_b32 s1, v251, 7
	s_nop 0
	v_addc_co_u32_e32 v13, vcc, 0, v11, vcc
	s_waitcnt lgkmcnt(1)
	global_store_dwordx4 v[12:13], v[2:5], off sc1
	s_add_i32 s1, s11, s1
	v_mov_b32_e32 v16, v1
	v_add_co_u32_e32 v2, vcc, s89, v10
	v_mov_b32_e32 v17, v1
	s_nop 0
	v_addc_co_u32_e32 v3, vcc, 0, v11, vcc
	s_waitcnt lgkmcnt(0)
	global_store_dwordx4 v[2:3], v[6:9], off sc1
	ds_read_b128 v[2:5], v0 offset:4352
	ds_read_b128 v[6:9], v0 offset:5440
	v_add_co_u32_e32 v12, vcc, s81, v10
	s_add_i32 s5, s11, 0x100
	s_nop 0
	v_addc_co_u32_e32 v13, vcc, 0, v11, vcc
	s_waitcnt lgkmcnt(1)
	global_store_dwordx4 v[12:13], v[2:5], off sc1
	v_mov_b32_e32 v14, v1
	v_mov_b32_e32 v15, v1
	v_add_co_u32_e32 v2, vcc, s20, v10
	s_lshr_b32 s5, s5, 6
	s_nop 0
	v_addc_co_u32_e32 v3, vcc, 0, v11, vcc
	s_waitcnt lgkmcnt(0)
	global_store_dwordx4 v[2:3], v[6:9], off sc1
	ds_read_b128 v[2:5], v0 offset:6528
	ds_read_b128 v[6:9], v0 offset:7616
	v_add_co_u32_e32 v12, vcc, s18, v10
	s_or_b32 s11, s1, 31
	s_nop 0
	v_addc_co_u32_e32 v13, vcc, 0, v11, vcc
	s_waitcnt lgkmcnt(1)
	global_store_dwordx4 v[12:13], v[2:5], off sc1
	v_mov_b32_e32 v12, v1
	v_mov_b32_e32 v13, v1
	v_add_co_u32_e32 v2, vcc, s3, v10
	v_mov_b32_e32 v243, 0xff800000
	s_nop 0
	v_addc_co_u32_e32 v3, vcc, 0, v11, vcc
	s_waitcnt lgkmcnt(0)
	global_store_dwordx4 v[2:3], v[6:9], off sc1
	s_barrier
	s_nop 0
	v_mov_b32_e32 v6, v227
	v_mov_b64_e32 v[2:3], s[48:49]
	v_ashrrev_i32_e32 v8, 3, v6
	v_lshlrev_b32_e32 v7, 4, v6
	v_mad_i64_i32 v[4:5], s[22:23], v8, s26, v[2:3]
	v_and_b32_e32 v0, 0x70, v7
	v_and_b32_e32 v144, 0xf0, v7
	v_add_u32_e32 v7, 0x200, v6
	v_lshl_add_u64 v[150:151], v[4:5], 0, v[0:1]
	v_lshl_add_u64 v[4:5], s[30:31], 0, v[144:145]
	v_ashrrev_i32_e32 v9, 4, v6
	v_ashrrev_i32_e32 v7, 4, v7
	v_and_b32_e32 v145, 31, v172
	v_ashrrev_i32_e32 v10, 5, v172
	v_mad_i64_i32 v[152:153], s[22:23], v9, s26, v[4:5]
	v_mad_i64_i32 v[154:155], s[22:23], v7, s26, v[4:5]
	v_or_b32_e32 v173, s1, v145
	v_lshlrev_b32_e32 v4, 3, v10
	v_mad_u64_u32 v[2:3], s[30:31], v173, s26, v[2:3]
	v_ashrrev_i32_e32 v5, 31, v4
	v_lshl_add_u64 v[156:157], v[4:5], 1, v[2:3]
	global_load_dwordx4 v[114:117], v[150:151], off offset:2048
	global_load_dwordx4 v[118:121], v[152:153], off
	global_load_dwordx4 v[122:125], v[154:155], off
	global_load_dwordx4 v[126:129], v[156:157], off
	global_load_dwordx4 v[130:133], v[156:157], off offset:32
	global_load_dwordx4 v[134:137], v[156:157], off offset:64
	global_load_dwordx4 v[138:141], v[156:157], off offset:96
	v_mul_lo_u32 v174, v8, s96
	v_add_u32_e32 v2, 0, v174
	v_add_u32_e32 v238, v2, v0
	v_add_u32_e32 v2, 0, v144
	s_movk_i32 s78, 0x140
	v_mul_lo_u32 v175, v9, s78
	s_movk_i32 s78, 0x140
	v_mul_lo_u32 v176, v7, s78
	v_lshlrev_b32_e32 v241, 2, v172
	v_add_u32_e32 v239, v2, v175
	v_add_u32_e32 v240, v2, v176
	v_and_b32_e32 v2, 16, v172
	v_lshrrev_b32_e32 v3, 2, v172
	v_lshlrev_b32_e32 v179, 2, v10
	v_and_or_b32 v3, v3, 3, v179
	v_and_or_b32 v2, v241, 12, v2
	v_lshlrev_b32_e32 v181, 1, v2
	s_movk_i32 s78, 0x140
	v_mul_lo_u32 v182, v3, s78
	v_mov_b64_e32 v[2:3], s[28:29]
	v_and_b32_e32 v6, 15, v6
	v_mad_i64_i32 v[4:5], s[28:29], v7, s26, v[2:3]
	v_lshlrev_b32_e32 v6, 4, v6
	v_mov_b32_e32 v7, v1
	v_lshl_add_u64 v[4:5], v[4:5], 0, v[6:7]
	v_lshl_add_u64 v[146:147], s[16:17], 0, v[4:5]
	v_mad_i64_i32 v[4:5], s[28:29], v9, s26, v[2:3]
	v_lshl_add_u64 v[4:5], v[4:5], 0, v[6:7]
	v_mad_i64_i32 v[2:3], s[28:29], v8, s26, v[2:3]
	v_lshlrev_b32_e32 v178, 4, v10
	v_lshl_add_u64 v[148:149], s[16:17], 0, v[4:5]
	v_lshl_add_u64 v[158:159], v[2:3], 0, v[0:1]
	v_mov_b32_e32 v2, v1
	v_mov_b32_e32 v3, v1
	v_mov_b32_e32 v4, v1
	v_mov_b32_e32 v5, v1
	v_mov_b32_e32 v6, v1
	v_mov_b32_e32 v8, v1
	v_mov_b32_e32 v9, v1
	v_mov_b32_e32 v10, v1
	v_mov_b32_e32 v11, v1
	v_mov_b64_e32 v[64:65], v[16:17]
	v_mov_b64_e32 v[48:49], v[16:17]
	v_mov_b64_e32 v[32:33], v[16:17]
	v_mov_b64_e32 v[80:81], v[16:17]
	s_mov_b32 s22, 0
	v_mul_u32_u24_e32 v177, 0x90, v145
	v_cmp_gt_u32_e64 s[42:43], 32, v172
	v_lshl_add_u32 v180, v145, 2, s91
	v_subrev_u32_e32 v183, 32, v173
	v_subrev_u32_e32 v184, 33, v173
	v_subrev_u32_e32 v185, 34, v173
	v_subrev_u32_e32 v186, 35, v173
	v_add_u32_e32 v187, -8, v173
	v_subrev_u32_e32 v188, 40, v173
	v_add_u32_e32 v189, -9, v173
	v_subrev_u32_e32 v195, 41, v173
	v_add_u32_e32 v196, -10, v173
	v_subrev_u32_e32 v197, 42, v173
	v_add_u32_e32 v198, -11, v173
	v_subrev_u32_e32 v199, 43, v173
	v_add_u32_e32 v200, -16, v173
	v_subrev_u32_e32 v201, 48, v173
	v_subrev_u32_e32 v202, 17, v173
	v_subrev_u32_e32 v203, 49, v173
	v_subrev_u32_e32 v204, 18, v173
	v_subrev_u32_e32 v205, 50, v173
	v_subrev_u32_e32 v228, 19, v173
	v_subrev_u32_e32 v229, 51, v173
	v_subrev_u32_e32 v230, 24, v173
	v_subrev_u32_e32 v231, 56, v173
	v_subrev_u32_e32 v232, 25, v173
	v_subrev_u32_e32 v233, 57, v173
	v_subrev_u32_e32 v234, 26, v173
	v_subrev_u32_e32 v235, 58, v173
	v_subrev_u32_e32 v236, 27, v173
	v_subrev_u32_e32 v237, 59, v173
	v_lshl_add_u64 v[160:161], s[44:45], 0, v[158:159]
	v_mov_b64_e32 v[162:163], v[148:149]
	v_mov_b64_e32 v[164:165], v[146:147]
	v_mov_b64_e32 v[62:63], v[14:15]
	v_mov_b64_e32 v[60:61], v[12:13]
	v_mov_b64_e32 v[58:59], v[10:11]
	v_mov_b64_e32 v[56:57], v[8:9]
	v_mov_b64_e32 v[54:55], v[6:7]
	v_mov_b64_e32 v[52:53], v[4:5]
	v_mov_b64_e32 v[50:51], v[2:3]
	v_mov_b64_e32 v[46:47], v[14:15]
	v_mov_b64_e32 v[44:45], v[12:13]
	v_mov_b64_e32 v[42:43], v[10:11]
	v_mov_b64_e32 v[40:41], v[8:9]
	v_mov_b64_e32 v[38:39], v[6:7]
	v_mov_b64_e32 v[36:37], v[4:5]
	v_mov_b64_e32 v[34:35], v[2:3]
	v_mov_b64_e32 v[30:31], v[14:15]
	v_mov_b64_e32 v[28:29], v[12:13]
	v_mov_b64_e32 v[26:27], v[10:11]
	v_mov_b64_e32 v[24:25], v[8:9]
	v_mov_b64_e32 v[22:23], v[6:7]
	v_mov_b64_e32 v[20:21], v[4:5]
	v_mov_b64_e32 v[18:19], v[2:3]
	v_mov_b64_e32 v[78:79], v[14:15]
	v_mov_b64_e32 v[76:77], v[12:13]
	v_mov_b64_e32 v[74:75], v[10:11]
	v_mov_b64_e32 v[72:73], v[8:9]
	v_mov_b64_e32 v[70:71], v[6:7]
	v_mov_b64_e32 v[68:69], v[4:5]
	v_mov_b64_e32 v[66:67], v[2:3]
	s_waitcnt vmcnt(6)
	ds_write_b128 v238, v[114:117]
	s_waitcnt vmcnt(5)
	ds_write_b128 v239, v[118:121] offset:9216
	s_waitcnt vmcnt(4)
	ds_write_b128 v240, v[122:125] offset:9216
	s_waitcnt vmcnt(0) lgkmcnt(0)
	s_barrier
	s_cmp_lt_u32 s4, s5
	s_cselect_b64 s[28:29], -1, 0
	s_cmp_ge_u32 s4, s5
	s_cbranch_scc1 .LBB0_66

.LBB0_140:
	v_lshl_or_b32 v168, s36, 8, v188
	v_lshl_add_u32 v170, s40, 8, v186
	v_ashrrev_i32_e32 v169, 31, v168
	v_cmp_lt_i32_e32 vcc, v218, v213
	v_readlane_b32 s40, v255, 36
	v_lshlrev_b64 v[198:199], 1, v[168:169]
	v_cndmask_b32_e32 v130, v211, v218, vcc
	v_cmp_lt_i32_e32 vcc, v219, v213
	v_readlane_b32 s41, v255, 37
	v_ashrrev_i32_e32 v171, 31, v170
	v_lshlrev_b32_e32 v196, 2, v130
	v_cndmask_b32_e32 v130, v211, v219, vcc
	v_lshl_add_u64 v[172:173], s[40:41], 0, v[198:199]
	v_lshlrev_b64 v[200:201], 11, v[170:171]
	v_lshlrev_b32_e32 v195, 2, v130
	v_lshl_add_u64 v[130:131], v[172:173], 0, v[200:201]
	global_load_dwordx4 v[190:193], v[130:131], off
	global_load_dwordx4 v[154:157], v[130:131], off offset:256
	v_or_b32_e32 v182, 16, v170
	v_ashrrev_i32_e32 v183, 31, v182
	v_or_b32_e32 v178, 32, v170
	v_lshlrev_b64 v[184:185], 11, v[182:183]
	v_ashrrev_i32_e32 v179, 31, v178
	v_or_b32_e32 v174, 48, v170
	v_lshl_add_u64 v[130:131], v[172:173], 0, v[184:185]
	v_lshlrev_b64 v[180:181], 11, v[178:179]
	v_ashrrev_i32_e32 v175, 31, v174
	global_load_dwordx4 v[150:153], v[130:131], off
	global_load_dwordx4 v[146:149], v[130:131], off offset:256
	v_lshl_add_u64 v[130:131], v[172:173], 0, v[180:181]
	v_lshlrev_b64 v[176:177], 11, v[174:175]
	global_load_dwordx4 v[142:145], v[130:131], off
	global_load_dwordx4 v[138:141], v[130:131], off offset:256
	v_lshl_add_u64 v[130:131], v[172:173], 0, v[176:177]
	global_load_dwordx4 v[134:137], v[130:131], off
	s_nop 0
	global_load_dwordx4 v[130:133], v[130:131], off offset:256
	s_lshl_b32 s62, s36, 2
	s_ashr_i32 s63, s62, 31
	s_waitcnt vmcnt(0)
	v_lshlrev_b32_e32 v202, 16, v190
	v_and_b32_e32 v203, 0xffff0000, v190
	v_lshlrev_b32_e32 v190, 16, v191
	v_and_b32_e32 v191, 0xffff0000, v191
	v_lshlrev_b32_e32 v204, 16, v192
	v_and_b32_e32 v205, 0xffff0000, v192
	v_lshlrev_b32_e32 v192, 16, v193
	v_and_b32_e32 v193, 0xffff0000, v193
	v_pk_add_f32 v[128:129], v[128:129], v[190:191]
	v_pk_add_f32 v[126:127], v[126:127], v[202:203]
	v_pk_add_f32 v[190:191], v[124:125], v[192:193]
	v_mul_f32_e32 v124, v127, v127
	v_mul_f32_e32 v125, v129, v129
	v_pk_add_f32 v[122:123], v[122:123], v[204:205]
	v_fmac_f32_e32 v124, v126, v126
	v_fmac_f32_e32 v125, v128, v128
	v_add_f32_e32 v124, v124, v125
	v_mul_f32_e32 v125, v123, v123
	v_mul_f32_e32 v192, v191, v191
	v_fmac_f32_e32 v125, v122, v122
	v_fmac_f32_e32 v192, v190, v190
	v_add_f32_e32 v125, v125, v192
	v_add_f32_e32 v192, v124, v125
	v_cvt_pk_bf16_f32 v124, v126, v127
	v_cvt_pk_bf16_f32 v126, v122, v123
	v_lshl_add_u64 v[122:123], s[40:41], 0, v[200:201]
	v_cvt_pk_bf16_f32 v125, v128, v129
	v_cvt_pk_bf16_f32 v127, v190, v191
	v_lshl_add_u64 v[122:123], v[122:123], 0, v[198:199]
	global_store_dwordx4 v[122:123], v[124:127], off sc1
	v_lshlrev_b32_e32 v128, 16, v156
	v_and_b32_e32 v129, 0xffff0000, v156
	v_lshlrev_b32_e32 v124, 16, v154
	v_and_b32_e32 v125, 0xffff0000, v154
	v_lshlrev_b32_e32 v126, 16, v155
	v_and_b32_e32 v127, 0xffff0000, v155
	v_lshlrev_b32_e32 v154, 16, v157
	v_and_b32_e32 v155, 0xffff0000, v157
	v_pk_add_f32 v[120:121], v[120:121], v[126:127]
	v_pk_add_f32 v[118:119], v[118:119], v[124:125]
	v_pk_add_f32 v[124:125], v[116:117], v[154:155]
	v_pk_add_f32 v[116:117], v[114:115], v[128:129]
	v_mul_f32_e32 v114, v119, v119
	v_mul_f32_e32 v115, v121, v121
	v_fmac_f32_e32 v114, v118, v118
	v_fmac_f32_e32 v115, v120, v120
	v_add_f32_e32 v114, v114, v115
	v_mul_f32_e32 v115, v117, v117
	v_mul_f32_e32 v126, v125, v125
	v_fmac_f32_e32 v115, v116, v116
	v_fmac_f32_e32 v126, v124, v124
	v_add_f32_e32 v115, v115, v126
	v_add_f32_e32 v114, v114, v115
	v_add_f32_e32 v126, v192, v114
	v_cvt_pk_bf16_f32 v114, v118, v119
	v_cvt_pk_bf16_f32 v115, v120, v121
	v_cvt_pk_bf16_f32 v116, v116, v117
	v_cvt_pk_bf16_f32 v117, v124, v125
	global_store_dwordx4 v[122:123], v[114:117], off offset:256 sc1
	ds_bpermute_b32 v114, v196, v126
	s_waitcnt lgkmcnt(0)
	v_add_f32_e32 v114, v126, v114
	ds_bpermute_b32 v115, v195, v114
	s_and_saveexec_b64 s[64:65], s[44:45]
	s_cbranch_execz .LBB0_142
	v_readlane_b32 s40, v255, 40
	v_lshlrev_b64 v[116:117], 6, v[170:171]
	v_readlane_b32 s41, v255, 41
	s_lshl_b32 s36, s22, 2
	s_waitcnt lgkmcnt(0)
	v_add_f32_e32 v114, v114, v115
	v_lshl_add_u64 v[116:117], s[40:41], 0, v[116:117]
	v_lshl_add_u64 v[116:117], s[62:63], 2, v[116:117]
	v_lshl_add_u64 v[116:117], v[116:117], 0, s[36:37]
	global_store_dword v[116:117], v114, off sc1
.LBB0_142:
	s_or_b64 exec, exec, s[64:65]
	v_lshlrev_b32_e32 v114, 16, v150
	s_waitcnt lgkmcnt(0)
	v_and_b32_e32 v115, 0xffff0000, v150
	v_lshlrev_b32_e32 v116, 16, v151
	v_and_b32_e32 v117, 0xffff0000, v151
	v_lshlrev_b32_e32 v118, 16, v152
	v_and_b32_e32 v119, 0xffff0000, v152
	v_lshlrev_b32_e32 v120, 16, v153
	v_and_b32_e32 v121, 0xffff0000, v153
	v_pk_add_f32 v[112:113], v[112:113], v[116:117]
	v_pk_add_f32 v[110:111], v[110:111], v[114:115]
	v_pk_add_f32 v[114:115], v[108:109], v[120:121]
	v_pk_add_f32 v[108:109], v[106:107], v[118:119]
	v_mul_f32_e32 v106, v111, v111
	v_mul_f32_e32 v107, v113, v113
	v_fmac_f32_e32 v106, v110, v110
	v_fmac_f32_e32 v107, v112, v112
	v_add_f32_e32 v106, v106, v107
	v_mul_f32_e32 v107, v109, v109
	v_mul_f32_e32 v116, v115, v115
	v_fmac_f32_e32 v107, v108, v108
	v_fmac_f32_e32 v116, v114, v114
	v_add_f32_e32 v107, v107, v116
	v_add_f32_e32 v118, v106, v107
	v_cvt_pk_bf16_f32 v106, v110, v111
	v_cvt_pk_bf16_f32 v107, v112, v113
	v_lshlrev_b32_e32 v110, 16, v146
	v_and_b32_e32 v111, 0xffff0000, v146
	v_lshlrev_b32_e32 v112, 16, v147
	v_and_b32_e32 v113, 0xffff0000, v147
	v_cvt_pk_bf16_f32 v108, v108, v109
	v_cvt_pk_bf16_f32 v109, v114, v115
	v_lshlrev_b32_e32 v114, 16, v148
	v_and_b32_e32 v115, 0xffff0000, v148
	v_pk_add_f32 v[104:105], v[104:105], v[112:113]
	v_pk_add_f32 v[102:103], v[102:103], v[110:111]
	v_lshlrev_b32_e32 v116, 16, v149
	v_and_b32_e32 v117, 0xffff0000, v149
	v_pk_add_f32 v[112:113], v[98:99], v[114:115]
	v_mul_f32_e32 v98, v103, v103
	v_mul_f32_e32 v99, v105, v105
	v_pk_add_f32 v[110:111], v[100:101], v[116:117]
	v_fmac_f32_e32 v98, v102, v102
	v_fmac_f32_e32 v99, v104, v104
	v_add_f32_e32 v98, v98, v99
	v_mul_f32_e32 v99, v113, v113
	v_mul_f32_e32 v100, v111, v111
	v_fmac_f32_e32 v99, v112, v112
	v_fmac_f32_e32 v100, v110, v110
	v_add_f32_e32 v99, v99, v100
	v_add_f32_e32 v98, v98, v99
	v_add_f32_e32 v101, v118, v98
	ds_bpermute_b32 v116, v196, v101
	v_readlane_b32 s40, v255, 36
	v_readlane_b32 s41, v255, 37
	v_cvt_pk_bf16_f32 v100, v102, v103
	v_cvt_pk_bf16_f32 v102, v112, v113
	v_lshl_add_u64 v[98:99], s[40:41], 0, v[184:185]
	v_lshl_add_u64 v[114:115], v[168:169], 1, v[98:99]
	s_waitcnt lgkmcnt(0)
	v_add_f32_e32 v98, v101, v116
	ds_bpermute_b32 v99, v195, v98
	v_cvt_pk_bf16_f32 v101, v104, v105
	v_cvt_pk_bf16_f32 v103, v110, v111
	global_store_dwordx4 v[114:115], v[106:109], off sc1
	global_store_dwordx4 v[114:115], v[100:103], off offset:256 sc1
	s_and_saveexec_b64 s[64:65], s[44:45]
	s_cbranch_execz .LBB0_144
	v_readlane_b32 s40, v255, 40
	v_lshlrev_b64 v[100:101], 6, v[182:183]
	v_readlane_b32 s41, v255, 41
	s_lshl_b32 s36, s22, 2
	s_waitcnt lgkmcnt(0)
	v_add_f32_e32 v98, v98, v99
	v_lshl_add_u64 v[100:101], s[40:41], 0, v[100:101]
	v_lshl_add_u64 v[100:101], s[62:63], 2, v[100:101]
	v_lshl_add_u64 v[100:101], v[100:101], 0, s[36:37]
	global_store_dword v[100:101], v98, off sc1
.LBB0_144:
	s_or_b64 exec, exec, s[64:65]
	v_lshlrev_b32_e32 v98, 16, v142
	s_waitcnt lgkmcnt(0)
	v_and_b32_e32 v99, 0xffff0000, v142
	v_lshlrev_b32_e32 v100, 16, v143
	v_and_b32_e32 v101, 0xffff0000, v143
	v_lshlrev_b32_e32 v102, 16, v144
	v_and_b32_e32 v103, 0xffff0000, v144
	v_lshlrev_b32_e32 v104, 16, v145
	v_and_b32_e32 v105, 0xffff0000, v145
	v_pk_add_f32 v[96:97], v[96:97], v[100:101]
	v_pk_add_f32 v[94:95], v[94:95], v[98:99]
	v_pk_add_f32 v[98:99], v[92:93], v[104:105]
	v_pk_add_f32 v[92:93], v[90:91], v[102:103]
	v_mul_f32_e32 v90, v95, v95
	v_mul_f32_e32 v91, v97, v97
	v_fmac_f32_e32 v90, v94, v94
	v_fmac_f32_e32 v91, v96, v96
	v_add_f32_e32 v90, v90, v91
	v_mul_f32_e32 v91, v93, v93
	v_mul_f32_e32 v100, v99, v99
	v_fmac_f32_e32 v91, v92, v92
	v_fmac_f32_e32 v100, v98, v98
	v_add_f32_e32 v91, v91, v100
	v_add_f32_e32 v102, v90, v91
	v_cvt_pk_bf16_f32 v90, v94, v95
	v_cvt_pk_bf16_f32 v91, v96, v97
	v_lshlrev_b32_e32 v94, 16, v138
	v_and_b32_e32 v95, 0xffff0000, v138
	v_lshlrev_b32_e32 v96, 16, v139
	v_and_b32_e32 v97, 0xffff0000, v139
	v_cvt_pk_bf16_f32 v92, v92, v93
	v_cvt_pk_bf16_f32 v93, v98, v99
	v_lshlrev_b32_e32 v98, 16, v140
	v_and_b32_e32 v99, 0xffff0000, v140
	v_pk_add_f32 v[88:89], v[88:89], v[96:97]
	v_pk_add_f32 v[86:87], v[86:87], v[94:95]
	v_lshlrev_b32_e32 v100, 16, v141
	v_and_b32_e32 v101, 0xffff0000, v141
	v_pk_add_f32 v[96:97], v[82:83], v[98:99]
	v_mul_f32_e32 v82, v87, v87
	v_mul_f32_e32 v83, v89, v89
	v_pk_add_f32 v[94:95], v[84:85], v[100:101]
	v_fmac_f32_e32 v82, v86, v86
	v_fmac_f32_e32 v83, v88, v88
	v_add_f32_e32 v82, v82, v83
	v_mul_f32_e32 v83, v97, v97
	v_mul_f32_e32 v84, v95, v95
	v_fmac_f32_e32 v83, v96, v96
	v_fmac_f32_e32 v84, v94, v94
	v_add_f32_e32 v83, v83, v84
	v_add_f32_e32 v82, v82, v83
	v_add_f32_e32 v85, v102, v82
	ds_bpermute_b32 v100, v196, v85
	v_readlane_b32 s40, v255, 36
	v_readlane_b32 s41, v255, 37
	v_cvt_pk_bf16_f32 v84, v86, v87
	v_cvt_pk_bf16_f32 v86, v96, v97
	v_lshl_add_u64 v[82:83], s[40:41], 0, v[180:181]
	v_lshl_add_u64 v[98:99], v[168:169], 1, v[82:83]
	s_waitcnt lgkmcnt(0)
	v_add_f32_e32 v82, v85, v100
	ds_bpermute_b32 v83, v195, v82
	v_cvt_pk_bf16_f32 v85, v88, v89
	v_cvt_pk_bf16_f32 v87, v94, v95
	global_store_dwordx4 v[98:99], v[90:93], off sc1
	global_store_dwordx4 v[98:99], v[84:87], off offset:256 sc1
	s_and_saveexec_b64 s[64:65], s[44:45]
	s_cbranch_execz .LBB0_146
	v_readlane_b32 s40, v255, 40
	v_lshlrev_b64 v[84:85], 6, v[178:179]
	v_readlane_b32 s41, v255, 41
	s_lshl_b32 s36, s22, 2
	s_waitcnt lgkmcnt(0)
	v_add_f32_e32 v82, v82, v83
	v_lshl_add_u64 v[84:85], s[40:41], 0, v[84:85]
	v_lshl_add_u64 v[84:85], s[62:63], 2, v[84:85]
	v_lshl_add_u64 v[84:85], v[84:85], 0, s[36:37]
	global_store_dword v[84:85], v82, off sc1
.LBB0_146:
	s_or_b64 exec, exec, s[64:65]
	v_lshlrev_b32_e32 v82, 16, v134
	s_waitcnt lgkmcnt(0)
	v_and_b32_e32 v83, 0xffff0000, v134
	v_lshlrev_b32_e32 v84, 16, v135
	v_and_b32_e32 v85, 0xffff0000, v135
	v_lshlrev_b32_e32 v86, 16, v136
	v_and_b32_e32 v87, 0xffff0000, v136
	v_lshlrev_b32_e32 v88, 16, v137
	v_and_b32_e32 v89, 0xffff0000, v137
	v_pk_add_f32 v[80:81], v[80:81], v[84:85]
	v_pk_add_f32 v[78:79], v[78:79], v[82:83]
	v_pk_add_f32 v[82:83], v[76:77], v[88:89]
	v_pk_add_f32 v[76:77], v[74:75], v[86:87]
	v_mul_f32_e32 v74, v79, v79
	v_mul_f32_e32 v75, v81, v81
	v_fmac_f32_e32 v74, v78, v78
	v_fmac_f32_e32 v75, v80, v80
	v_add_f32_e32 v74, v74, v75
	v_mul_f32_e32 v75, v77, v77
	v_mul_f32_e32 v84, v83, v83
	v_fmac_f32_e32 v75, v76, v76
	v_fmac_f32_e32 v84, v82, v82
	v_add_f32_e32 v75, v75, v84
	v_add_f32_e32 v86, v74, v75
	v_cvt_pk_bf16_f32 v74, v78, v79
	v_cvt_pk_bf16_f32 v75, v80, v81
	v_lshlrev_b32_e32 v78, 16, v130
	v_and_b32_e32 v79, 0xffff0000, v130
	v_lshlrev_b32_e32 v80, 16, v131
	v_and_b32_e32 v81, 0xffff0000, v131
	v_cvt_pk_bf16_f32 v76, v76, v77
	v_cvt_pk_bf16_f32 v77, v82, v83
	v_lshlrev_b32_e32 v82, 16, v132
	v_and_b32_e32 v83, 0xffff0000, v132
	v_pk_add_f32 v[72:73], v[72:73], v[80:81]
	v_pk_add_f32 v[70:71], v[70:71], v[78:79]
	v_lshlrev_b32_e32 v84, 16, v133
	v_and_b32_e32 v85, 0xffff0000, v133
	v_pk_add_f32 v[80:81], v[66:67], v[82:83]
	v_mul_f32_e32 v66, v71, v71
	v_mul_f32_e32 v67, v73, v73
	v_pk_add_f32 v[78:79], v[68:69], v[84:85]
	v_fmac_f32_e32 v66, v70, v70
	v_fmac_f32_e32 v67, v72, v72
	v_add_f32_e32 v66, v66, v67
	v_mul_f32_e32 v67, v81, v81
	v_mul_f32_e32 v68, v79, v79
	v_fmac_f32_e32 v67, v80, v80
	v_fmac_f32_e32 v68, v78, v78
	v_add_f32_e32 v67, v67, v68
	v_add_f32_e32 v66, v66, v67
	v_add_f32_e32 v69, v86, v66
	ds_bpermute_b32 v84, v196, v69
	v_readlane_b32 s40, v255, 36
	v_readlane_b32 s41, v255, 37
	v_cvt_pk_bf16_f32 v68, v70, v71
	v_cvt_pk_bf16_f32 v70, v80, v81
	v_lshl_add_u64 v[66:67], s[40:41], 0, v[176:177]
	v_lshl_add_u64 v[82:83], v[168:169], 1, v[66:67]
	s_waitcnt lgkmcnt(0)
	v_add_f32_e32 v66, v69, v84
	ds_bpermute_b32 v67, v195, v66
	v_cvt_pk_bf16_f32 v69, v72, v73
	v_cvt_pk_bf16_f32 v71, v78, v79
	global_store_dwordx4 v[82:83], v[74:77], off sc1
	global_store_dwordx4 v[82:83], v[68:71], off offset:256 sc1
	s_and_saveexec_b64 s[64:65], s[44:45]
	s_cbranch_execz .LBB0_148
	v_readlane_b32 s40, v255, 40
	v_lshlrev_b64 v[68:69], 6, v[174:175]
	v_readlane_b32 s41, v255, 41
	s_lshl_b32 s36, s22, 2
	s_waitcnt lgkmcnt(0)
	v_add_f32_e32 v66, v66, v67
	v_lshl_add_u64 v[68:69], s[40:41], 0, v[68:69]
	v_lshl_add_u64 v[68:69], s[62:63], 2, v[68:69]
	v_lshl_add_u64 v[68:69], v[68:69], 0, s[36:37]
	global_store_dword v[68:69], v66, off sc1
.LBB0_148:
	s_or_b64 exec, exec, s[64:65]
	v_add_u32_e32 v106, 0x80, v170
	v_ashrrev_i32_e32 v107, 31, v106
	v_lshlrev_b64 v[112:113], 11, v[106:107]
	s_waitcnt lgkmcnt(0)
	v_lshl_add_u64 v[66:67], v[172:173], 0, v[112:113]
	global_load_dwordx4 v[108:111], v[66:67], off
	global_load_dwordx4 v[90:93], v[66:67], off offset:256
	v_add_u32_e32 v102, 0x90, v170
	v_ashrrev_i32_e32 v103, 31, v102
	v_add_u32_e32 v98, 0xa0, v170
	v_lshlrev_b64 v[104:105], 11, v[102:103]
	v_ashrrev_i32_e32 v99, 31, v98
	v_add_u32_e32 v94, 0xb0, v170
	v_lshl_add_u64 v[66:67], v[172:173], 0, v[104:105]
	v_lshlrev_b64 v[100:101], 11, v[98:99]
	v_ashrrev_i32_e32 v95, 31, v94
	global_load_dwordx4 v[86:89], v[66:67], off
	global_load_dwordx4 v[82:85], v[66:67], off offset:256
	v_lshl_add_u64 v[66:67], v[172:173], 0, v[100:101]
	v_lshlrev_b64 v[96:97], 11, v[94:95]
	global_load_dwordx4 v[78:81], v[66:67], off
	global_load_dwordx4 v[74:77], v[66:67], off offset:256
	v_lshl_add_u64 v[66:67], v[172:173], 0, v[96:97]
	global_load_dwordx4 v[70:73], v[66:67], off
	s_nop 0
	global_load_dwordx4 v[66:69], v[66:67], off offset:256
	v_readlane_b32 s40, v255, 36
	v_readlane_b32 s41, v255, 37
	s_waitcnt vmcnt(7)
	v_lshlrev_b32_e32 v114, 16, v108
	v_and_b32_e32 v115, 0xffff0000, v108
	v_lshlrev_b32_e32 v108, 16, v109
	v_and_b32_e32 v109, 0xffff0000, v109
	v_lshlrev_b32_e32 v116, 16, v110
	v_and_b32_e32 v117, 0xffff0000, v110
	v_lshlrev_b32_e32 v110, 16, v111
	v_and_b32_e32 v111, 0xffff0000, v111
	v_pk_add_f32 v[64:65], v[64:65], v[108:109]
	v_pk_add_f32 v[62:63], v[62:63], v[114:115]
	v_pk_add_f32 v[108:109], v[60:61], v[110:111]
	v_mul_f32_e32 v60, v63, v63
	v_mul_f32_e32 v61, v65, v65
	v_pk_add_f32 v[58:59], v[58:59], v[116:117]
	v_fmac_f32_e32 v60, v62, v62
	v_fmac_f32_e32 v61, v64, v64
	v_add_f32_e32 v60, v60, v61
	v_mul_f32_e32 v61, v59, v59
	v_mul_f32_e32 v110, v109, v109
	v_fmac_f32_e32 v61, v58, v58
	v_fmac_f32_e32 v110, v108, v108
	v_add_f32_e32 v61, v61, v110
	v_add_f32_e32 v110, v60, v61
	v_cvt_pk_bf16_f32 v60, v62, v63
	v_cvt_pk_bf16_f32 v62, v58, v59
	v_lshl_add_u64 v[58:59], s[40:41], 0, v[112:113]
	v_cvt_pk_bf16_f32 v61, v64, v65
	v_cvt_pk_bf16_f32 v63, v108, v109
	v_lshl_add_u64 v[58:59], v[168:169], 1, v[58:59]
	global_store_dwordx4 v[58:59], v[60:63], off sc1
	s_waitcnt vmcnt(7)
	v_lshlrev_b32_e32 v64, 16, v92
	v_and_b32_e32 v65, 0xffff0000, v92
	v_lshlrev_b32_e32 v60, 16, v90
	v_and_b32_e32 v61, 0xffff0000, v90
	v_lshlrev_b32_e32 v62, 16, v91
	v_and_b32_e32 v63, 0xffff0000, v91
	v_lshlrev_b32_e32 v90, 16, v93
	v_and_b32_e32 v91, 0xffff0000, v93
	v_pk_add_f32 v[56:57], v[56:57], v[62:63]
	v_pk_add_f32 v[54:55], v[54:55], v[60:61]
	v_pk_add_f32 v[60:61], v[52:53], v[90:91]
	v_pk_add_f32 v[52:53], v[50:51], v[64:65]
	v_mul_f32_e32 v50, v55, v55
	v_mul_f32_e32 v51, v57, v57
	v_fmac_f32_e32 v50, v54, v54
	v_fmac_f32_e32 v51, v56, v56
	v_add_f32_e32 v50, v50, v51
	v_mul_f32_e32 v51, v53, v53
	v_mul_f32_e32 v62, v61, v61
	v_fmac_f32_e32 v51, v52, v52
	v_fmac_f32_e32 v62, v60, v60
	v_add_f32_e32 v51, v51, v62
	v_add_f32_e32 v50, v50, v51
	v_add_f32_e32 v62, v110, v50
	v_cvt_pk_bf16_f32 v50, v54, v55
	v_cvt_pk_bf16_f32 v51, v56, v57
	v_cvt_pk_bf16_f32 v52, v52, v53
	v_cvt_pk_bf16_f32 v53, v60, v61
	global_store_dwordx4 v[58:59], v[50:53], off offset:256 sc1
	ds_bpermute_b32 v50, v196, v62
	s_waitcnt lgkmcnt(0)
	v_add_f32_e32 v50, v62, v50
	ds_bpermute_b32 v51, v195, v50
	s_and_saveexec_b64 s[64:65], s[44:45]
	s_cbranch_execz .LBB0_150
	v_readlane_b32 s40, v255, 40
	v_lshlrev_b64 v[52:53], 6, v[106:107]
	v_readlane_b32 s41, v255, 41
	s_lshl_b32 s36, s22, 2
	s_waitcnt lgkmcnt(0)
	v_add_f32_e32 v50, v50, v51
	v_lshl_add_u64 v[52:53], s[40:41], 0, v[52:53]
	v_lshl_add_u64 v[52:53], s[62:63], 2, v[52:53]
	v_lshl_add_u64 v[52:53], v[52:53], 0, s[36:37]
	global_store_dword v[52:53], v50, off sc1
.LBB0_150:
	s_or_b64 exec, exec, s[64:65]
	s_waitcnt vmcnt(7)
	v_lshlrev_b32_e32 v50, 16, v86
	s_waitcnt lgkmcnt(0)
	v_and_b32_e32 v51, 0xffff0000, v86
	v_lshlrev_b32_e32 v52, 16, v87
	v_and_b32_e32 v53, 0xffff0000, v87
	v_lshlrev_b32_e32 v54, 16, v88
	v_and_b32_e32 v55, 0xffff0000, v88
	v_lshlrev_b32_e32 v56, 16, v89
	v_and_b32_e32 v57, 0xffff0000, v89
	v_pk_add_f32 v[48:49], v[48:49], v[52:53]
	v_pk_add_f32 v[46:47], v[46:47], v[50:51]
	v_pk_add_f32 v[50:51], v[44:45], v[56:57]
	v_pk_add_f32 v[44:45], v[42:43], v[54:55]
	v_mul_f32_e32 v42, v47, v47
	v_mul_f32_e32 v43, v49, v49
	v_fmac_f32_e32 v42, v46, v46
	v_fmac_f32_e32 v43, v48, v48
	v_add_f32_e32 v42, v42, v43
	v_mul_f32_e32 v43, v45, v45
	v_mul_f32_e32 v52, v51, v51
	v_fmac_f32_e32 v43, v44, v44
	v_fmac_f32_e32 v52, v50, v50
	v_add_f32_e32 v43, v43, v52
	v_add_f32_e32 v54, v42, v43
	v_cvt_pk_bf16_f32 v42, v46, v47
	v_cvt_pk_bf16_f32 v43, v48, v49
	s_waitcnt vmcnt(6)
	v_lshlrev_b32_e32 v46, 16, v82
	v_and_b32_e32 v47, 0xffff0000, v82
	v_lshlrev_b32_e32 v48, 16, v83
	v_and_b32_e32 v49, 0xffff0000, v83
	v_cvt_pk_bf16_f32 v44, v44, v45
	v_cvt_pk_bf16_f32 v45, v50, v51
	v_lshlrev_b32_e32 v50, 16, v84
	v_and_b32_e32 v51, 0xffff0000, v84
	v_pk_add_f32 v[40:41], v[40:41], v[48:49]
	v_pk_add_f32 v[38:39], v[38:39], v[46:47]
	v_lshlrev_b32_e32 v52, 16, v85
	v_and_b32_e32 v53, 0xffff0000, v85
	v_pk_add_f32 v[48:49], v[34:35], v[50:51]
	v_mul_f32_e32 v34, v39, v39
	v_mul_f32_e32 v35, v41, v41
	v_pk_add_f32 v[46:47], v[36:37], v[52:53]
	v_fmac_f32_e32 v34, v38, v38
	v_fmac_f32_e32 v35, v40, v40
	v_add_f32_e32 v34, v34, v35
	v_mul_f32_e32 v35, v49, v49
	v_mul_f32_e32 v36, v47, v47
	v_fmac_f32_e32 v35, v48, v48
	v_fmac_f32_e32 v36, v46, v46
	v_add_f32_e32 v35, v35, v36
	v_add_f32_e32 v34, v34, v35
	v_add_f32_e32 v37, v54, v34
	ds_bpermute_b32 v52, v196, v37
	v_readlane_b32 s40, v255, 36
	v_readlane_b32 s41, v255, 37
	v_cvt_pk_bf16_f32 v36, v38, v39
	v_cvt_pk_bf16_f32 v38, v48, v49
	v_lshl_add_u64 v[34:35], s[40:41], 0, v[104:105]
	v_lshl_add_u64 v[50:51], v[168:169], 1, v[34:35]
	s_waitcnt lgkmcnt(0)
	v_add_f32_e32 v34, v37, v52
	ds_bpermute_b32 v35, v195, v34
	v_cvt_pk_bf16_f32 v37, v40, v41
	v_cvt_pk_bf16_f32 v39, v46, v47
	global_store_dwordx4 v[50:51], v[42:45], off sc1
	global_store_dwordx4 v[50:51], v[36:39], off offset:256 sc1
	s_and_saveexec_b64 s[64:65], s[44:45]
	s_cbranch_execz .LBB0_152
	v_readlane_b32 s40, v255, 40
	v_lshlrev_b64 v[36:37], 6, v[102:103]
	v_readlane_b32 s41, v255, 41
	s_lshl_b32 s36, s22, 2
	s_waitcnt lgkmcnt(0)
	v_add_f32_e32 v34, v34, v35
	v_lshl_add_u64 v[36:37], s[40:41], 0, v[36:37]
	v_lshl_add_u64 v[36:37], s[62:63], 2, v[36:37]
	v_lshl_add_u64 v[36:37], v[36:37], 0, s[36:37]
	global_store_dword v[36:37], v34, off sc1
.LBB0_152:
	s_or_b64 exec, exec, s[64:65]
	s_waitcnt vmcnt(7)
	v_lshlrev_b32_e32 v34, 16, v78
	s_waitcnt lgkmcnt(0)
	v_and_b32_e32 v35, 0xffff0000, v78
	v_lshlrev_b32_e32 v36, 16, v79
	v_and_b32_e32 v37, 0xffff0000, v79
	v_lshlrev_b32_e32 v38, 16, v80
	v_and_b32_e32 v39, 0xffff0000, v80
	v_lshlrev_b32_e32 v40, 16, v81
	v_and_b32_e32 v41, 0xffff0000, v81
	v_pk_add_f32 v[32:33], v[32:33], v[36:37]
	v_pk_add_f32 v[30:31], v[30:31], v[34:35]
	v_pk_add_f32 v[34:35], v[28:29], v[40:41]
	v_pk_add_f32 v[28:29], v[26:27], v[38:39]
	v_mul_f32_e32 v26, v31, v31
	v_mul_f32_e32 v27, v33, v33
	v_fmac_f32_e32 v26, v30, v30
	v_fmac_f32_e32 v27, v32, v32
	v_add_f32_e32 v26, v26, v27
	v_mul_f32_e32 v27, v29, v29
	v_mul_f32_e32 v36, v35, v35
	v_fmac_f32_e32 v27, v28, v28
	v_fmac_f32_e32 v36, v34, v34
	v_add_f32_e32 v27, v27, v36
	v_add_f32_e32 v38, v26, v27
	v_cvt_pk_bf16_f32 v26, v30, v31
	v_cvt_pk_bf16_f32 v27, v32, v33
	s_waitcnt vmcnt(6)
	v_lshlrev_b32_e32 v30, 16, v74
	v_and_b32_e32 v31, 0xffff0000, v74
	v_lshlrev_b32_e32 v32, 16, v75
	v_and_b32_e32 v33, 0xffff0000, v75
	v_cvt_pk_bf16_f32 v28, v28, v29
	v_cvt_pk_bf16_f32 v29, v34, v35
	v_lshlrev_b32_e32 v34, 16, v76
	v_and_b32_e32 v35, 0xffff0000, v76
	v_pk_add_f32 v[24:25], v[24:25], v[32:33]
	v_pk_add_f32 v[22:23], v[22:23], v[30:31]
	v_lshlrev_b32_e32 v36, 16, v77
	v_and_b32_e32 v37, 0xffff0000, v77
	v_pk_add_f32 v[32:33], v[18:19], v[34:35]
	v_mul_f32_e32 v18, v23, v23
	v_mul_f32_e32 v19, v25, v25
	v_pk_add_f32 v[30:31], v[20:21], v[36:37]
	v_fmac_f32_e32 v18, v22, v22
	v_fmac_f32_e32 v19, v24, v24
	v_add_f32_e32 v18, v18, v19
	v_mul_f32_e32 v19, v33, v33
	v_mul_f32_e32 v20, v31, v31
	v_fmac_f32_e32 v19, v32, v32
	v_fmac_f32_e32 v20, v30, v30
	v_add_f32_e32 v19, v19, v20
	v_add_f32_e32 v18, v18, v19
	v_add_f32_e32 v21, v38, v18
	ds_bpermute_b32 v36, v196, v21
	v_readlane_b32 s40, v255, 36
	v_readlane_b32 s41, v255, 37
	v_cvt_pk_bf16_f32 v20, v22, v23
	v_cvt_pk_bf16_f32 v22, v32, v33
	v_lshl_add_u64 v[18:19], s[40:41], 0, v[100:101]
	v_lshl_add_u64 v[34:35], v[168:169], 1, v[18:19]
	s_waitcnt lgkmcnt(0)
	v_add_f32_e32 v18, v21, v36
	ds_bpermute_b32 v19, v195, v18
	v_cvt_pk_bf16_f32 v21, v24, v25
	v_cvt_pk_bf16_f32 v23, v30, v31
	global_store_dwordx4 v[34:35], v[26:29], off sc1
	global_store_dwordx4 v[34:35], v[20:23], off offset:256 sc1
	s_and_saveexec_b64 s[64:65], s[44:45]
	s_cbranch_execz .LBB0_154
	v_readlane_b32 s40, v255, 40
	v_lshlrev_b64 v[20:21], 6, v[98:99]
	v_readlane_b32 s41, v255, 41
	s_lshl_b32 s36, s22, 2
	s_waitcnt lgkmcnt(0)
	v_add_f32_e32 v18, v18, v19
	v_lshl_add_u64 v[20:21], s[40:41], 0, v[20:21]
	v_lshl_add_u64 v[20:21], s[62:63], 2, v[20:21]
	v_lshl_add_u64 v[20:21], v[20:21], 0, s[36:37]
	global_store_dword v[20:21], v18, off sc1
.LBB0_154:
	s_or_b64 exec, exec, s[64:65]
	s_waitcnt vmcnt(7)
	v_lshlrev_b32_e32 v18, 16, v70
	s_waitcnt lgkmcnt(0)
	v_and_b32_e32 v19, 0xffff0000, v70
	v_lshlrev_b32_e32 v20, 16, v71
	v_and_b32_e32 v21, 0xffff0000, v71
	v_lshlrev_b32_e32 v22, 16, v72
	v_and_b32_e32 v23, 0xffff0000, v72
	v_lshlrev_b32_e32 v24, 16, v73
	v_and_b32_e32 v25, 0xffff0000, v73
	v_pk_add_f32 v[16:17], v[16:17], v[20:21]
	v_pk_add_f32 v[14:15], v[14:15], v[18:19]
	v_pk_add_f32 v[18:19], v[12:13], v[24:25]
	v_pk_add_f32 v[12:13], v[10:11], v[22:23]
	v_mul_f32_e32 v10, v15, v15
	v_mul_f32_e32 v11, v17, v17
	v_fmac_f32_e32 v10, v14, v14
	v_fmac_f32_e32 v11, v16, v16
	v_add_f32_e32 v10, v10, v11
	v_mul_f32_e32 v11, v13, v13
	v_mul_f32_e32 v20, v19, v19
	v_fmac_f32_e32 v11, v12, v12
	v_fmac_f32_e32 v20, v18, v18
	v_add_f32_e32 v11, v11, v20
	v_add_f32_e32 v22, v10, v11
	v_cvt_pk_bf16_f32 v10, v14, v15
	v_cvt_pk_bf16_f32 v11, v16, v17
	s_waitcnt vmcnt(6)
	v_lshlrev_b32_e32 v14, 16, v66
	v_and_b32_e32 v15, 0xffff0000, v66
	v_lshlrev_b32_e32 v16, 16, v67
	v_and_b32_e32 v17, 0xffff0000, v67
	v_cvt_pk_bf16_f32 v12, v12, v13
	v_cvt_pk_bf16_f32 v13, v18, v19
	v_lshlrev_b32_e32 v18, 16, v68
	v_and_b32_e32 v19, 0xffff0000, v68
	v_pk_add_f32 v[8:9], v[8:9], v[16:17]
	v_pk_add_f32 v[6:7], v[6:7], v[14:15]
	v_lshlrev_b32_e32 v20, 16, v69
	v_and_b32_e32 v21, 0xffff0000, v69
	v_pk_add_f32 v[16:17], v[2:3], v[18:19]
	v_mul_f32_e32 v2, v7, v7
	v_mul_f32_e32 v3, v9, v9
	v_pk_add_f32 v[14:15], v[4:5], v[20:21]
	v_fmac_f32_e32 v2, v6, v6
	v_fmac_f32_e32 v3, v8, v8
	v_add_f32_e32 v2, v2, v3
	v_mul_f32_e32 v3, v17, v17
	v_mul_f32_e32 v4, v15, v15
	v_fmac_f32_e32 v3, v16, v16
	v_fmac_f32_e32 v4, v14, v14
	v_add_f32_e32 v3, v3, v4
	v_add_f32_e32 v2, v2, v3
	v_add_f32_e32 v5, v22, v2
	ds_bpermute_b32 v20, v196, v5
	v_readlane_b32 s40, v255, 36
	v_readlane_b32 s41, v255, 37
	v_cvt_pk_bf16_f32 v4, v6, v7
	v_cvt_pk_bf16_f32 v6, v16, v17
	v_lshl_add_u64 v[2:3], s[40:41], 0, v[96:97]
	v_lshl_add_u64 v[18:19], v[168:169], 1, v[2:3]
	s_waitcnt lgkmcnt(0)
	v_add_f32_e32 v2, v5, v20
	ds_bpermute_b32 v3, v195, v2
	v_cvt_pk_bf16_f32 v5, v8, v9
	v_cvt_pk_bf16_f32 v7, v14, v15
	global_store_dwordx4 v[18:19], v[10:13], off sc1
	global_store_dwordx4 v[18:19], v[4:7], off offset:256 sc1
	s_and_saveexec_b64 s[64:65], s[44:45]
	s_cbranch_execz .LBB0_156
	v_readlane_b32 s40, v255, 40
	v_lshlrev_b64 v[4:5], 6, v[94:95]
	v_readlane_b32 s41, v255, 41
	s_lshl_b32 s36, s22, 2
	s_waitcnt lgkmcnt(0)
	v_add_f32_e32 v2, v2, v3
	v_lshl_add_u64 v[4:5], s[40:41], 0, v[4:5]
	v_lshl_add_u64 v[4:5], s[62:63], 2, v[4:5]
	v_lshl_add_u64 v[4:5], v[4:5], 0, s[36:37]
	global_store_dword v[4:5], v2, off sc1

.LBB0_207:
	v_readlane_b32 s4, v255, 34
	v_readlane_b32 s5, v255, 35
	s_load_dwordx2 s[4:5], s[4:5], 0x18
	v_lshlrev_b64 v[88:89], 2, v[162:163]
	v_lshlrev_b32_e32 v0, 4, v0
	v_lshl_add_u64 v[162:163], v[172:173], 0, v[0:1]
	v_lshlrev_b64 v[158:159], 12, v[158:159]
	s_waitcnt lgkmcnt(0)
	v_lshl_add_u64 v[10:11], s[4:5], 0, v[88:89]
	global_load_dwordx4 v[6:9], v[10:11], off offset:16
	global_load_dwordx4 v[14:17], v[10:11], off
	global_load_dwordx4 v[2:5], v[10:11], off offset:528
	s_nop 0
	global_load_dwordx4 v[10:13], v[10:11], off offset:512
	s_nop 0
	global_load_dword v172, v[162:163], off sc1
	global_load_dword v184, v[162:163], off offset:4 sc1
	global_load_dword v173, v[162:163], off offset:8 sc1
	global_load_dword v185, v[162:163], off offset:12 sc1
	v_lshl_add_u64 v[158:159], s[30:31], 0, v[158:159]
	v_lshl_add_u64 v[158:159], v[158:159], 0, v[88:89]
	v_lshl_add_u64 v[82:83], v[82:83], 0, v[0:1]
	s_waitcnt vmcnt(0)
	v_pk_add_f32 v[162:163], v[172:173], v[184:185]
	s_nop 0
	v_add_f32_e32 v162, v162, v163
	ds_bpermute_b32 v163, v182, v162
	v_lshl_add_u64 v[172:173], v[174:175], 0, v[0:1]
	s_waitcnt lgkmcnt(0)
	v_add_f32_e32 v162, v162, v163
	ds_bpermute_b32 v163, v183, v162
	s_waitcnt lgkmcnt(0)
	v_add_f32_e32 v162, v162, v163
	v_fmamk_f32 v162, v162, 0x3a800000, v249
	v_mul_f32_e32 v163, 0x4b800000, v162
	v_cmp_gt_f32_e32 vcc, s9, v162
	s_nop 1
	v_cndmask_b32_e32 v162, v162, v163, vcc
	v_rsq_f32_e32 v162, v162
	s_nop 0
	v_mul_f32_e32 v163, 0x45800000, v162
	v_cndmask_b32_e32 v162, v162, v163, vcc
	v_pk_mul_f32 v[126:127], v[126:127], v[162:163] op_sel_hi:[1,0]
	v_pk_mul_f32 v[128:129], v[128:129], v[162:163] op_sel_hi:[1,0]
	v_pk_mul_f32 v[174:175], v[122:123], v[162:163] op_sel_hi:[1,0]
	v_pk_mul_f32 v[124:125], v[124:125], v[162:163] op_sel_hi:[1,0]
	v_pk_mul_f32 v[184:185], v[164:165], v[162:163] op_sel_hi:[1,0]
	v_pk_mul_f32 v[164:165], v[120:121], v[162:163] op_sel_hi:[1,0]
	v_pk_mul_f32 v[186:187], v[168:169], v[162:163] op_sel_hi:[1,0]
	v_pk_mul_f32 v[166:167], v[166:167], v[162:163] op_sel_hi:[1,0]
	v_pk_mul_f32 v[122:123], v[16:17], v[128:129]
	v_pk_mul_f32 v[120:121], v[14:15], v[126:127]
	v_pk_mul_f32 v[126:127], v[8:9], v[124:125]
	v_pk_mul_f32 v[124:125], v[6:7], v[174:175]
	v_pk_mul_f32 v[164:165], v[12:13], v[164:165]
	v_pk_mul_f32 v[162:163], v[10:11], v[184:185]
	v_pk_mul_f32 v[168:169], v[4:5], v[166:167]
	v_pk_mul_f32 v[166:167], v[2:3], v[186:187]
	global_store_dwordx4 v[158:159], v[120:123], off sc1
	global_store_dwordx4 v[158:159], v[124:127], off offset:16 sc1
	global_store_dwordx4 v[158:159], v[162:165], off offset:512 sc1
	global_store_dwordx4 v[158:159], v[166:169], off offset:528 sc1
	global_load_dword v120, v[172:173], off sc1
	s_nop 0
	global_load_dword v122, v[172:173], off offset:4 sc1
	global_load_dword v121, v[172:173], off offset:8 sc1
	global_load_dword v123, v[172:173], off offset:12 sc1
	v_lshl_add_u64 v[126:127], v[176:177], 0, v[0:1]
	s_waitcnt vmcnt(0)
	v_pk_add_f32 v[120:121], v[120:121], v[122:123]
	s_nop 0
	v_add_f32_e32 v120, v120, v121
	ds_bpermute_b32 v121, v182, v120
	s_waitcnt lgkmcnt(0)
	v_add_f32_e32 v122, v120, v121
	ds_bpermute_b32 v123, v183, v122
	v_lshlrev_b64 v[120:121], 12, v[160:161]
	v_lshl_add_u64 v[120:121], s[30:31], 0, v[120:121]
	v_lshl_add_u64 v[128:129], v[120:121], 0, v[88:89]
	s_waitcnt lgkmcnt(0)
	v_add_f32_e32 v122, v122, v123
	v_fmamk_f32 v122, v122, 0x3a800000, v249
	v_mul_f32_e32 v123, 0x4b800000, v122
	v_cmp_gt_f32_e32 vcc, s9, v122
	s_nop 1
	v_cndmask_b32_e32 v122, v122, v123, vcc
	v_rsq_f32_e32 v122, v122
	s_nop 0
	v_mul_f32_e32 v120, 0x45800000, v122
	v_cndmask_b32_e32 v120, v122, v120, vcc
	v_pk_mul_f32 v[110:111], v[110:111], v[120:121] op_sel_hi:[1,0]
	v_pk_mul_f32 v[112:113], v[112:113], v[120:121] op_sel_hi:[1,0]
	v_pk_mul_f32 v[122:123], v[106:107], v[120:121] op_sel_hi:[1,0]
	v_pk_mul_f32 v[124:125], v[108:109], v[120:121] op_sel_hi:[1,0]
	v_pk_mul_f32 v[146:147], v[146:147], v[120:121] op_sel_hi:[1,0]
	v_pk_mul_f32 v[118:119], v[118:119], v[120:121] op_sel_hi:[1,0]
	v_pk_mul_f32 v[150:151], v[150:151], v[120:121] op_sel_hi:[1,0]
	v_pk_mul_f32 v[148:149], v[148:149], v[120:121] op_sel_hi:[1,0]
	v_pk_mul_f32 v[108:109], v[16:17], v[112:113]
	v_pk_mul_f32 v[106:107], v[14:15], v[110:111]
	v_pk_mul_f32 v[112:113], v[8:9], v[124:125]
	v_pk_mul_f32 v[110:111], v[6:7], v[122:123]
	v_pk_mul_f32 v[120:121], v[12:13], v[118:119]
	v_pk_mul_f32 v[118:119], v[10:11], v[146:147]
	v_pk_mul_f32 v[124:125], v[4:5], v[148:149]
	v_pk_mul_f32 v[122:123], v[2:3], v[150:151]
	global_store_dwordx4 v[128:129], v[106:109], off sc1
	global_store_dwordx4 v[128:129], v[110:113], off offset:16 sc1
	global_store_dwordx4 v[128:129], v[118:121], off offset:512 sc1
	global_store_dwordx4 v[128:129], v[122:125], off offset:528 sc1
	global_load_dword v106, v[126:127], off sc1
	s_nop 0
	global_load_dword v108, v[126:127], off offset:4 sc1
	global_load_dword v107, v[126:127], off offset:8 sc1
	global_load_dword v109, v[126:127], off offset:12 sc1
	v_lshl_add_u64 v[122:123], v[178:179], 0, v[0:1]
	s_waitcnt vmcnt(0)
	v_pk_add_f32 v[106:107], v[106:107], v[108:109]
	s_nop 0
	v_add_f32_e32 v106, v106, v107
	ds_bpermute_b32 v107, v182, v106
	s_waitcnt lgkmcnt(0)
	v_add_f32_e32 v108, v106, v107
	ds_bpermute_b32 v109, v183, v108
	v_lshlrev_b64 v[106:107], 12, v[156:157]
	v_lshl_add_u64 v[106:107], s[30:31], 0, v[106:107]
	v_lshl_add_u64 v[124:125], v[106:107], 0, v[88:89]
	s_waitcnt lgkmcnt(0)
	v_add_f32_e32 v108, v108, v109
	v_fmamk_f32 v108, v108, 0x3a800000, v249
	v_mul_f32_e32 v109, 0x4b800000, v108
	v_cmp_gt_f32_e32 vcc, s9, v108
	s_nop 1
	v_cndmask_b32_e32 v108, v108, v109, vcc
	v_rsq_f32_e32 v108, v108
	s_nop 0
	v_mul_f32_e32 v106, 0x45800000, v108
	v_cndmask_b32_e32 v106, v108, v106, vcc
	v_pk_mul_f32 v[108:109], v[98:99], v[106:107] op_sel_hi:[1,0]
	v_pk_mul_f32 v[96:97], v[96:97], v[106:107] op_sel_hi:[1,0]
	v_pk_mul_f32 v[110:111], v[114:115], v[106:107] op_sel_hi:[1,0]
	v_pk_mul_f32 v[102:103], v[102:103], v[106:107] op_sel_hi:[1,0]
	v_pk_mul_f32 v[114:115], v[140:141], v[106:107] op_sel_hi:[1,0]
	v_pk_mul_f32 v[112:113], v[138:139], v[106:107] op_sel_hi:[1,0]
	v_pk_mul_f32 v[118:119], v[152:153], v[106:107] op_sel_hi:[1,0]
	v_pk_mul_f32 v[120:121], v[142:143], v[106:107] op_sel_hi:[1,0]
	v_pk_mul_f32 v[98:99], v[16:17], v[96:97]
	v_pk_mul_f32 v[96:97], v[14:15], v[108:109]
	v_pk_mul_f32 v[108:109], v[8:9], v[102:103]
	v_pk_mul_f32 v[106:107], v[6:7], v[110:111]
	v_pk_mul_f32 v[112:113], v[12:13], v[112:113]
	v_pk_mul_f32 v[110:111], v[10:11], v[114:115]
	v_pk_mul_f32 v[120:121], v[4:5], v[120:121]
	v_pk_mul_f32 v[118:119], v[2:3], v[118:119]
	global_store_dwordx4 v[124:125], v[96:99], off sc1
	global_store_dwordx4 v[124:125], v[106:109], off offset:16 sc1
	global_store_dwordx4 v[124:125], v[110:113], off offset:512 sc1
	global_store_dwordx4 v[124:125], v[118:121], off offset:528 sc1
	global_load_dword v96, v[122:123], off sc1
	s_nop 0
	global_load_dword v98, v[122:123], off offset:4 sc1
	global_load_dword v97, v[122:123], off offset:8 sc1
	global_load_dword v99, v[122:123], off offset:12 sc1
	v_lshl_add_u64 v[110:111], v[180:181], 0, v[0:1]
	s_waitcnt vmcnt(0)
	v_pk_add_f32 v[96:97], v[96:97], v[98:99]
	s_nop 0
	v_add_f32_e32 v96, v96, v97
	ds_bpermute_b32 v97, v182, v96
	s_waitcnt lgkmcnt(0)
	v_add_f32_e32 v98, v96, v97
	ds_bpermute_b32 v99, v183, v98
	v_lshlrev_b64 v[96:97], 12, v[154:155]
	v_lshl_add_u64 v[96:97], s[30:31], 0, v[96:97]
	v_lshl_add_u64 v[112:113], v[96:97], 0, v[88:89]
	s_waitcnt lgkmcnt(0)
	v_add_f32_e32 v98, v98, v99
	v_fmamk_f32 v98, v98, 0x3a800000, v249
	v_mul_f32_e32 v99, 0x4b800000, v98
	v_cmp_gt_f32_e32 vcc, s9, v98
	s_nop 1
	v_cndmask_b32_e32 v98, v98, v99, vcc
	v_rsq_f32_e32 v98, v98
	s_nop 0
	v_mul_f32_e32 v96, 0x45800000, v98
	v_cndmask_b32_e32 v96, v98, v96, vcc
	v_pk_mul_f32 v[98:99], v[100:101], v[96:97] op_sel_hi:[1,0]
	v_pk_mul_f32 v[94:95], v[94:95], v[96:97] op_sel_hi:[1,0]
	v_pk_mul_f32 v[102:103], v[116:117], v[96:97] op_sel_hi:[1,0]
	v_pk_mul_f32 v[100:101], v[104:105], v[96:97] op_sel_hi:[1,0]
	v_pk_mul_f32 v[106:107], v[134:135], v[96:97] op_sel_hi:[1,0]
	v_pk_mul_f32 v[104:105], v[130:131], v[96:97] op_sel_hi:[1,0]
	v_pk_mul_f32 v[114:115], v[170:171], v[96:97] op_sel_hi:[1,0]
	v_pk_mul_f32 v[108:109], v[144:145], v[96:97] op_sel_hi:[1,0]
	v_pk_mul_f32 v[96:97], v[16:17], v[94:95]
	v_pk_mul_f32 v[94:95], v[14:15], v[98:99]
	v_pk_mul_f32 v[100:101], v[8:9], v[100:101]
	v_pk_mul_f32 v[98:99], v[6:7], v[102:103]
	v_pk_mul_f32 v[104:105], v[12:13], v[104:105]
	v_pk_mul_f32 v[102:103], v[10:11], v[106:107]
	v_pk_mul_f32 v[108:109], v[4:5], v[108:109]
	v_pk_mul_f32 v[106:107], v[2:3], v[114:115]
	global_store_dwordx4 v[112:113], v[94:97], off sc1
	global_store_dwordx4 v[112:113], v[98:101], off offset:16 sc1
	global_store_dwordx4 v[112:113], v[102:105], off offset:512 sc1
	global_store_dwordx4 v[112:113], v[106:109], off offset:528 sc1
	global_load_dword v94, v[110:111], off sc1
	s_nop 0
	global_load_dword v96, v[110:111], off offset:4 sc1
	global_load_dword v95, v[110:111], off offset:8 sc1
	global_load_dword v97, v[110:111], off offset:12 sc1
	s_waitcnt vmcnt(0)
	v_pk_add_f32 v[94:95], v[94:95], v[96:97]
	s_nop 0
	v_add_f32_e32 v94, v94, v95
	ds_bpermute_b32 v95, v182, v94
	s_waitcnt lgkmcnt(0)
	v_add_f32_e32 v96, v94, v95
	ds_bpermute_b32 v97, v183, v96
	v_lshlrev_b64 v[94:95], 12, v[136:137]
	v_lshl_add_u64 v[94:95], s[30:31], 0, v[94:95]
	v_lshl_add_u64 v[94:95], v[94:95], 0, v[88:89]
	s_waitcnt lgkmcnt(0)
	v_add_f32_e32 v96, v96, v97
	v_fmamk_f32 v96, v96, 0x3a800000, v249
	v_mul_f32_e32 v97, 0x4b800000, v96
	v_cmp_gt_f32_e32 vcc, s9, v96
	s_nop 1
	v_cndmask_b32_e32 v96, v96, v97, vcc
	v_rsq_f32_e32 v96, v96
	s_nop 0
	v_mul_f32_e32 v97, 0x45800000, v96
	v_cndmask_b32_e32 v96, v96, v97, vcc
	v_pk_mul_f32 v[62:63], v[62:63], v[96:97] op_sel_hi:[1,0]
	v_pk_mul_f32 v[64:65], v[64:65], v[96:97] op_sel_hi:[1,0]
	v_pk_mul_f32 v[58:59], v[58:59], v[96:97] op_sel_hi:[1,0]
	v_pk_mul_f32 v[60:61], v[60:61], v[96:97] op_sel_hi:[1,0]
	v_pk_mul_f32 v[98:99], v[54:55], v[96:97] op_sel_hi:[1,0]
	v_pk_mul_f32 v[100:101], v[56:57], v[96:97] op_sel_hi:[1,0]
	v_pk_mul_f32 v[102:103], v[50:51], v[96:97] op_sel_hi:[1,0]
	v_pk_mul_f32 v[96:97], v[52:53], v[96:97] op_sel_hi:[1,0]
	v_pk_mul_f32 v[52:53], v[16:17], v[64:65]
	v_pk_mul_f32 v[50:51], v[14:15], v[62:63]
	v_pk_mul_f32 v[56:57], v[8:9], v[60:61]
	v_pk_mul_f32 v[54:55], v[6:7], v[58:59]
	v_pk_mul_f32 v[60:61], v[12:13], v[100:101]
	v_pk_mul_f32 v[58:59], v[10:11], v[98:99]
	v_pk_mul_f32 v[64:65], v[4:5], v[96:97]
	v_pk_mul_f32 v[62:63], v[2:3], v[102:103]
	global_store_dwordx4 v[94:95], v[50:53], off sc1
	global_store_dwordx4 v[94:95], v[54:57], off offset:16 sc1
	global_store_dwordx4 v[94:95], v[58:61], off offset:512 sc1
	global_store_dwordx4 v[94:95], v[62:65], off offset:528 sc1
	global_load_dword v50, v[82:83], off sc1
	s_nop 0
	global_load_dword v52, v[82:83], off offset:4 sc1
	global_load_dword v51, v[82:83], off offset:8 sc1
	global_load_dword v53, v[82:83], off offset:12 sc1
	s_waitcnt vmcnt(0)
	v_pk_add_f32 v[50:51], v[50:51], v[52:53]
	s_nop 0
	v_add_f32_e32 v50, v50, v51
	ds_bpermute_b32 v51, v182, v50
	s_waitcnt lgkmcnt(0)
	v_add_f32_e32 v52, v50, v51
	ds_bpermute_b32 v53, v183, v52
	v_lshlrev_b64 v[50:51], 12, v[132:133]
	v_lshl_add_u64 v[50:51], s[30:31], 0, v[50:51]
	v_lshl_add_u64 v[50:51], v[50:51], 0, v[88:89]
	s_waitcnt lgkmcnt(0)
	v_add_f32_e32 v52, v52, v53
	v_fmamk_f32 v52, v52, 0x3a800000, v249
	v_mul_f32_e32 v53, 0x4b800000, v52
	v_cmp_gt_f32_e32 vcc, s9, v52
	s_nop 1
	v_cndmask_b32_e32 v52, v52, v53, vcc
	v_rsq_f32_e32 v54, v52
	v_lshl_add_u64 v[52:53], v[84:85], 0, v[0:1]
	v_mul_f32_e32 v55, 0x45800000, v54
	v_cndmask_b32_e32 v54, v54, v55, vcc
	v_pk_mul_f32 v[46:47], v[46:47], v[54:55] op_sel_hi:[1,0]
	v_pk_mul_f32 v[48:49], v[48:49], v[54:55] op_sel_hi:[1,0]
	v_pk_mul_f32 v[42:43], v[42:43], v[54:55] op_sel_hi:[1,0]
	v_pk_mul_f32 v[44:45], v[44:45], v[54:55] op_sel_hi:[1,0]
	v_pk_mul_f32 v[56:57], v[38:39], v[54:55] op_sel_hi:[1,0]
	v_pk_mul_f32 v[58:59], v[40:41], v[54:55] op_sel_hi:[1,0]
	v_pk_mul_f32 v[60:61], v[34:35], v[54:55] op_sel_hi:[1,0]
	v_pk_mul_f32 v[54:55], v[36:37], v[54:55] op_sel_hi:[1,0]
	v_pk_mul_f32 v[36:37], v[16:17], v[48:49]
	v_pk_mul_f32 v[34:35], v[14:15], v[46:47]
	v_pk_mul_f32 v[40:41], v[8:9], v[44:45]
	v_pk_mul_f32 v[38:39], v[6:7], v[42:43]
	v_pk_mul_f32 v[44:45], v[12:13], v[58:59]
	v_pk_mul_f32 v[42:43], v[10:11], v[56:57]
	v_pk_mul_f32 v[48:49], v[4:5], v[54:55]
	v_pk_mul_f32 v[46:47], v[2:3], v[60:61]
	global_store_dwordx4 v[50:51], v[34:37], off sc1
	global_store_dwordx4 v[50:51], v[38:41], off offset:16 sc1
	global_store_dwordx4 v[50:51], v[42:45], off offset:512 sc1
	global_store_dwordx4 v[50:51], v[46:49], off offset:528 sc1
	global_load_dword v34, v[52:53], off sc1
	s_nop 0
	global_load_dword v36, v[52:53], off offset:4 sc1
	global_load_dword v35, v[52:53], off offset:8 sc1
	global_load_dword v37, v[52:53], off offset:12 sc1
	s_waitcnt vmcnt(0)
	v_pk_add_f32 v[34:35], v[34:35], v[36:37]
	s_nop 0
	v_add_f32_e32 v34, v34, v35
	ds_bpermute_b32 v35, v182, v34
	s_waitcnt lgkmcnt(0)
	v_add_f32_e32 v36, v34, v35
	ds_bpermute_b32 v37, v183, v36
	v_lshlrev_b64 v[34:35], 12, v[92:93]
	v_lshl_add_u64 v[34:35], s[30:31], 0, v[34:35]
	v_lshl_add_u64 v[34:35], v[34:35], 0, v[88:89]
	s_waitcnt lgkmcnt(0)
	v_add_f32_e32 v36, v36, v37
	v_fmamk_f32 v36, v36, 0x3a800000, v249
	v_mul_f32_e32 v37, 0x4b800000, v36
	v_cmp_gt_f32_e32 vcc, s9, v36
	s_nop 1
	v_cndmask_b32_e32 v36, v36, v37, vcc
	v_rsq_f32_e32 v38, v36
	v_lshl_add_u64 v[36:37], v[86:87], 0, v[0:1]
	v_mul_f32_e32 v0, 0x45800000, v38
	v_cndmask_b32_e32 v0, v38, v0, vcc
	v_pk_mul_f32 v[30:31], v[30:31], v[0:1] op_sel_hi:[1,0]
	v_pk_mul_f32 v[32:33], v[32:33], v[0:1] op_sel_hi:[1,0]
	v_pk_mul_f32 v[26:27], v[26:27], v[0:1] op_sel_hi:[1,0]
	v_pk_mul_f32 v[28:29], v[28:29], v[0:1] op_sel_hi:[1,0]
	v_pk_mul_f32 v[38:39], v[22:23], v[0:1] op_sel_hi:[1,0]
	v_pk_mul_f32 v[40:41], v[24:25], v[0:1] op_sel_hi:[1,0]
	v_pk_mul_f32 v[42:43], v[18:19], v[0:1] op_sel_hi:[1,0]
	v_pk_mul_f32 v[44:45], v[20:21], v[0:1] op_sel_hi:[1,0]
	v_pk_mul_f32 v[20:21], v[16:17], v[32:33]
	v_pk_mul_f32 v[18:19], v[14:15], v[30:31]
	v_pk_mul_f32 v[24:25], v[8:9], v[28:29]
	v_pk_mul_f32 v[22:23], v[6:7], v[26:27]
	v_pk_mul_f32 v[28:29], v[12:13], v[40:41]
	v_pk_mul_f32 v[26:27], v[10:11], v[38:39]
	v_pk_mul_f32 v[32:33], v[4:5], v[44:45]
	v_pk_mul_f32 v[30:31], v[2:3], v[42:43]
	global_store_dwordx4 v[34:35], v[18:21], off sc1
	global_store_dwordx4 v[34:35], v[22:25], off offset:16 sc1
	global_store_dwordx4 v[34:35], v[26:29], off offset:512 sc1
	global_store_dwordx4 v[34:35], v[30:33], off offset:528 sc1
	global_load_dword v18, v[36:37], off sc1
	s_nop 0
	global_load_dword v20, v[36:37], off offset:4 sc1
	global_load_dword v19, v[36:37], off offset:8 sc1
	global_load_dword v21, v[36:37], off offset:12 sc1
	s_waitcnt vmcnt(0)
	v_pk_add_f32 v[18:19], v[18:19], v[20:21]
	s_nop 0
	v_add_f32_e32 v0, v18, v19
	ds_bpermute_b32 v18, v182, v0
	s_waitcnt lgkmcnt(0)
	v_add_f32_e32 v0, v0, v18
	ds_bpermute_b32 v18, v183, v0
	s_waitcnt lgkmcnt(0)
	v_add_f32_e32 v0, v0, v18
	v_fmamk_f32 v0, v0, 0x3a800000, v249
	v_mul_f32_e32 v18, 0x4b800000, v0
	v_cmp_gt_f32_e32 vcc, s9, v0
	s_nop 1
	v_cndmask_b32_e32 v0, v0, v18, vcc
	v_rsq_f32_e32 v0, v0
	v_lshlrev_b64 v[18:19], 12, v[90:91]
	v_lshl_add_u64 v[18:19], s[30:31], 0, v[18:19]
	v_lshl_add_u64 v[18:19], v[18:19], 0, v[88:89]
	v_mul_f32_e32 v20, 0x45800000, v0
	v_cndmask_b32_e32 v0, v0, v20, vcc
	v_pk_mul_f32 v[20:21], v[68:69], v[0:1] op_sel_hi:[1,0]
	v_pk_mul_f32 v[22:23], v[66:67], v[0:1] op_sel_hi:[1,0]
	v_pk_mul_f32 v[24:25], v[74:75], v[0:1] op_sel_hi:[1,0]
	v_pk_mul_f32 v[26:27], v[70:71], v[0:1] op_sel_hi:[1,0]
	v_pk_mul_f32 v[28:29], v[78:79], v[0:1] op_sel_hi:[1,0]
	v_pk_mul_f32 v[30:31], v[72:73], v[0:1] op_sel_hi:[1,0]
	v_pk_mul_f32 v[32:33], v[80:81], v[0:1] op_sel_hi:[1,0]
	v_pk_mul_f32 v[34:35], v[76:77], v[0:1] op_sel_hi:[1,0]
	v_pk_mul_f32 v[16:17], v[16:17], v[22:23]
	v_pk_mul_f32 v[14:15], v[14:15], v[20:21]
	v_pk_mul_f32 v[8:9], v[8:9], v[26:27]
	v_pk_mul_f32 v[6:7], v[6:7], v[24:25]
	v_pk_mul_f32 v[12:13], v[12:13], v[30:31]
	v_pk_mul_f32 v[10:11], v[10:11], v[28:29]
	v_pk_mul_f32 v[4:5], v[4:5], v[34:35]
	v_pk_mul_f32 v[2:3], v[2:3], v[32:33]
	global_store_dwordx4 v[18:19], v[14:17], off sc1
	global_store_dwordx4 v[18:19], v[6:9], off offset:16 sc1
	global_store_dwordx4 v[18:19], v[10:13], off offset:512 sc1
	global_store_dwordx4 v[18:19], v[2:5], off offset:528 sc1

.LBB0_222:
	s_nop 1
	v_rcp_f32_e32 v2, v112
	v_rcp_f32_e32 v4, v114
	v_readlane_b32 s4, v251, 15
	v_rcp_f32_e32 v3, v113
	v_mul_f32_e32 v6, v48, v2
	v_mul_f32_e32 v7, v64, v2
	v_rcp_f32_e32 v2, v115
	v_mul_f32_e32 v9, v50, v4
	v_mul_f32_e32 v10, v66, v4
	v_rcp_f32_e32 v4, v116
	v_mul_f32_e32 v11, v51, v2
	v_mul_f32_e32 v12, v67, v2
	v_rcp_f32_e32 v2, v117
	v_mul_f32_e32 v13, v52, v4
	v_mul_f32_e32 v14, v68, v4
	v_rcp_f32_e32 v4, v118
	v_mul_f32_e32 v15, v53, v2
	v_mul_f32_e32 v16, v69, v2
	v_rcp_f32_e32 v2, v119
	v_mul_f32_e32 v17, v54, v4
	v_mul_f32_e32 v18, v70, v4
	v_rcp_f32_e32 v4, v120
	v_mul_f32_e32 v19, v55, v2
	v_mul_f32_e32 v20, v71, v2
	v_rcp_f32_e32 v2, v121
	v_mul_f32_e32 v21, v56, v4
	v_mul_f32_e32 v22, v72, v4
	v_rcp_f32_e32 v4, v122
	v_mul_f32_e32 v23, v57, v2
	v_mul_f32_e32 v24, v73, v2
	v_rcp_f32_e32 v2, v123
	v_mul_f32_e32 v25, v58, v4
	v_mul_f32_e32 v26, v74, v4
	v_rcp_f32_e32 v4, v124
	v_mul_f32_e32 v27, v59, v2
	v_mul_f32_e32 v28, v75, v2
	v_rcp_f32_e32 v2, v125
	v_mul_f32_e32 v29, v60, v4
	v_mul_f32_e32 v30, v76, v4
	v_rcp_f32_e32 v4, v126
	v_mul_f32_e32 v31, v61, v2
	v_mul_f32_e32 v32, v77, v2
	v_mov_b32_e32 v2, s4
	v_rcp_f32_e32 v5, v127
	v_mul_f32_e32 v8, v49, v3
	v_add_u32_e32 v37, 0, v2
	v_lshlrev_b32_e32 v2, 1, v144
	v_and_b32_e32 v2, 62, v2
	v_mul_f32_e32 v3, v65, v3
	v_mul_f32_e32 v33, v62, v4
	v_mul_f32_e32 v34, v78, v4
	v_and_b32_e32 v4, 0xffffffc, v146
	v_add_u32_e32 v2, v37, v2
	s_movk_i32 s10, 0x90
	v_mul_f32_e32 v35, v63, v5
	v_mul_f32_e32 v36, v79, v5
	v_mad_u64_u32 v[4:5], s[4:5], v4, s10, v[2:3]
	v_cvt_pk_bf16_f32 v3, v3, s0
	ds_write_b16 v4, v3 offset:208
	v_cvt_pk_bf16_f32 v3, v9, s0
	ds_write_b16 v4, v3 offset:288
	v_cvt_pk_bf16_f32 v3, v10, s0
	v_cvt_pk_bf16_f32 v5, v6, s0
	ds_write_b16 v4, v3 offset:352
	v_or_b32_e32 v3, 3, v146
	ds_write_b16 v4, v5
	v_cvt_pk_bf16_f32 v5, v7, s0
	v_mad_u64_u32 v[2:3], s[4:5], v3, s10, v[2:3]
	ds_write_b16 v4, v5 offset:64
	v_cvt_pk_bf16_f32 v5, v8, s0
	v_cvt_pk_bf16_f32 v3, v11, s0
	ds_write_b16 v4, v5 offset:144
	ds_write_b16 v2, v3
	v_cvt_pk_bf16_f32 v3, v12, s0
	ds_write_b16 v2, v3 offset:64
	v_cvt_pk_bf16_f32 v3, v13, s0
	ds_write_b16 v4, v3 offset:1152
	v_cvt_pk_bf16_f32 v3, v14, s0
	ds_write_b16 v4, v3 offset:1216
	v_cvt_pk_bf16_f32 v3, v15, s0
	ds_write_b16 v4, v3 offset:1296
	v_cvt_pk_bf16_f32 v3, v16, s0
	ds_write_b16 v4, v3 offset:1360
	v_cvt_pk_bf16_f32 v3, v17, s0
	ds_write_b16 v4, v3 offset:1440
	v_cvt_pk_bf16_f32 v3, v18, s0
	ds_write_b16 v4, v3 offset:1504
	v_cvt_pk_bf16_f32 v3, v19, s0
	ds_write_b16 v2, v3 offset:1152
	v_cvt_pk_bf16_f32 v3, v20, s0
	ds_write_b16 v2, v3 offset:1216
	v_cvt_pk_bf16_f32 v3, v21, s0
	ds_write_b16 v4, v3 offset:2304
	v_cvt_pk_bf16_f32 v3, v22, s0
	ds_write_b16 v4, v3 offset:2368
	v_cvt_pk_bf16_f32 v3, v23, s0
	ds_write_b16 v4, v3 offset:2448
	v_cvt_pk_bf16_f32 v3, v24, s0
	ds_write_b16 v4, v3 offset:2512
	v_cvt_pk_bf16_f32 v3, v25, s0
	ds_write_b16 v4, v3 offset:2592
	v_cvt_pk_bf16_f32 v3, v26, s0
	ds_write_b16 v4, v3 offset:2656
	v_cvt_pk_bf16_f32 v3, v27, s0
	ds_write_b16 v2, v3 offset:2304
	v_cvt_pk_bf16_f32 v3, v28, s0
	ds_write_b16 v2, v3 offset:2368
	v_cvt_pk_bf16_f32 v3, v29, s0
	ds_write_b16 v4, v3 offset:3456
	v_cvt_pk_bf16_f32 v3, v30, s0
	ds_write_b16 v4, v3 offset:3520
	v_cvt_pk_bf16_f32 v3, v31, s0
	s_add_i32 s4, s82, s1
	ds_write_b16 v4, v3 offset:3600
	v_cvt_pk_bf16_f32 v3, v32, s0
	s_ashr_i32 s5, s4, 31
	ds_write_b16 v4, v3 offset:3664
	v_cvt_pk_bf16_f32 v3, v33, s0
	s_lshl_b64 s[4:5], s[4:5], 11
	v_readlane_b32 s1, v255, 54
	ds_write_b16 v4, v3 offset:3744
	v_cvt_pk_bf16_f32 v3, v34, s0
	s_add_u32 s1, s1, s4
	v_readlane_b32 s4, v255, 55
	ds_write_b16 v4, v3 offset:3808
	v_cvt_pk_bf16_f32 v3, v35, s0
	s_addc_u32 s5, s4, s5
	ds_write_b16 v2, v3 offset:3456
	v_cvt_pk_bf16_f32 v3, v36, s0
	s_add_u32 s4, s1, s16
	ds_write_b16 v2, v3 offset:3520
	s_addc_u32 s5, s5, 0
	v_lshlrev_b32_e32 v0, 4, v0
	v_mul_lo_u32 v2, v146, s10
	s_waitcnt lgkmcnt(0)
	v_lshl_add_u64 v[6:7], s[4:5], 0, v[0:1]
	v_add3_u32 v0, v37, v0, v2
	ds_read_b128 v[2:5], v0
	v_ashrrev_i32_e32 v147, 31, v146
	v_lshlrev_b64 v[8:9], 11, v[146:147]
	v_lshl_add_u64 v[10:11], v[6:7], 0, v[8:9]
	ds_read_b128 v[6:9], v0 offset:1152
	s_waitcnt lgkmcnt(1)
	global_store_dwordx4 v[10:11], v[2:5], off sc1
	v_readlane_b32 s90, v254, 58
	v_readlane_b32 s91, v254, 59
	v_add_co_u32_e32 v2, vcc, 0x4000, v10
	s_add_i32 s9, s9, s90
	s_nop 0
	v_addc_co_u32_e32 v3, vcc, 0, v11, vcc
	s_waitcnt lgkmcnt(0)
	global_store_dwordx4 v[2:3], v[6:9], off sc1
	ds_read_b128 v[2:5], v0 offset:2304
	ds_read_b128 v[6:9], v0 offset:3456
	v_add_co_u32_e32 v12, vcc, 0x8000, v10
	s_add_i32 s41, s41, s90
	s_nop 0
	v_addc_co_u32_e32 v13, vcc, 0, v11, vcc
	s_waitcnt lgkmcnt(1)
	global_store_dwordx4 v[12:13], v[2:5], off sc1
	s_movk_i32 s96, 0x90
	s_cmpk_gt_i32 s9, 0xff
	v_add_co_u32_e32 v2, vcc, 0xc000, v10
	v_readlane_b32 s91, v254, 53
	s_nop 0
	v_addc_co_u32_e32 v3, vcc, 0, v11, vcc
	s_waitcnt lgkmcnt(0)
	global_store_dwordx4 v[2:3], v[6:9], off sc1
	s_cbranch_scc1 .LBB0_360

.LBB0_292:
	s_nop 1
	v_rcp_f32_e32 v2, v112
	v_rcp_f32_e32 v4, v114
	v_readlane_b32 s1, v251, 15
	v_rcp_f32_e32 v3, v113
	v_mul_f32_e32 v6, v48, v2
	v_mul_f32_e32 v7, v64, v2
	v_rcp_f32_e32 v2, v115
	v_mul_f32_e32 v9, v50, v4
	v_mul_f32_e32 v10, v66, v4
	v_rcp_f32_e32 v4, v116
	v_mul_f32_e32 v11, v51, v2
	v_mul_f32_e32 v12, v67, v2
	v_rcp_f32_e32 v2, v117
	v_mul_f32_e32 v13, v52, v4
	v_mul_f32_e32 v14, v68, v4
	v_rcp_f32_e32 v4, v118
	v_mul_f32_e32 v15, v53, v2
	v_mul_f32_e32 v16, v69, v2
	v_rcp_f32_e32 v2, v119
	v_mul_f32_e32 v17, v54, v4
	v_mul_f32_e32 v18, v70, v4
	v_rcp_f32_e32 v4, v120
	v_mul_f32_e32 v19, v55, v2
	v_mul_f32_e32 v20, v71, v2
	v_rcp_f32_e32 v2, v121
	v_mul_f32_e32 v21, v56, v4
	v_mul_f32_e32 v22, v72, v4
	v_rcp_f32_e32 v4, v122
	v_mul_f32_e32 v23, v57, v2
	v_mul_f32_e32 v24, v73, v2
	v_rcp_f32_e32 v2, v123
	v_mul_f32_e32 v25, v58, v4
	v_mul_f32_e32 v26, v74, v4
	v_rcp_f32_e32 v4, v124
	v_mul_f32_e32 v27, v59, v2
	v_mul_f32_e32 v28, v75, v2
	v_rcp_f32_e32 v2, v125
	v_mul_f32_e32 v29, v60, v4
	v_mul_f32_e32 v30, v76, v4
	v_rcp_f32_e32 v4, v126
	v_mul_f32_e32 v31, v61, v2
	v_mul_f32_e32 v32, v77, v2
	v_mov_b32_e32 v2, s1
	v_rcp_f32_e32 v5, v127
	v_mul_f32_e32 v8, v49, v3
	v_add_u32_e32 v37, 0, v2
	v_lshlrev_b32_e32 v2, 1, v144
	v_and_b32_e32 v2, 62, v2
	v_mul_f32_e32 v3, v65, v3
	v_mul_f32_e32 v33, v62, v4
	v_mul_f32_e32 v34, v78, v4
	v_and_b32_e32 v4, 0xffffffc, v148
	v_add_u32_e32 v2, v37, v2
	s_movk_i32 s36, 0x90
	v_mul_f32_e32 v35, v63, v5
	v_mul_f32_e32 v36, v79, v5
	v_mad_u64_u32 v[4:5], s[42:43], v4, s36, v[2:3]
	v_cvt_pk_bf16_f32 v3, v3, s0
	ds_write_b16 v4, v3 offset:208
	v_cvt_pk_bf16_f32 v3, v9, s0
	ds_write_b16 v4, v3 offset:288
	v_cvt_pk_bf16_f32 v3, v10, s0
	v_cvt_pk_bf16_f32 v5, v6, s0
	ds_write_b16 v4, v3 offset:352
	v_or_b32_e32 v3, 3, v148
	ds_write_b16 v4, v5
	v_cvt_pk_bf16_f32 v5, v7, s0
	v_mad_u64_u32 v[2:3], s[42:43], v3, s36, v[2:3]
	ds_write_b16 v4, v5 offset:64
	v_cvt_pk_bf16_f32 v5, v8, s0
	v_cvt_pk_bf16_f32 v3, v11, s0
	ds_write_b16 v4, v5 offset:144
	ds_write_b16 v2, v3
	v_cvt_pk_bf16_f32 v3, v12, s0
	ds_write_b16 v2, v3 offset:64
	v_cvt_pk_bf16_f32 v3, v13, s0
	ds_write_b16 v4, v3 offset:1152
	v_cvt_pk_bf16_f32 v3, v14, s0
	ds_write_b16 v4, v3 offset:1216
	v_cvt_pk_bf16_f32 v3, v15, s0
	ds_write_b16 v4, v3 offset:1296
	v_cvt_pk_bf16_f32 v3, v16, s0
	ds_write_b16 v4, v3 offset:1360
	v_cvt_pk_bf16_f32 v3, v17, s0
	ds_write_b16 v4, v3 offset:1440
	v_cvt_pk_bf16_f32 v3, v18, s0
	ds_write_b16 v4, v3 offset:1504
	v_cvt_pk_bf16_f32 v3, v19, s0
	ds_write_b16 v2, v3 offset:1152
	v_cvt_pk_bf16_f32 v3, v20, s0
	ds_write_b16 v2, v3 offset:1216
	v_cvt_pk_bf16_f32 v3, v21, s0
	ds_write_b16 v4, v3 offset:2304
	v_cvt_pk_bf16_f32 v3, v22, s0
	ds_write_b16 v4, v3 offset:2368
	v_cvt_pk_bf16_f32 v3, v23, s0
	ds_write_b16 v4, v3 offset:2448
	v_cvt_pk_bf16_f32 v3, v24, s0
	ds_write_b16 v4, v3 offset:2512
	v_cvt_pk_bf16_f32 v3, v25, s0
	ds_write_b16 v4, v3 offset:2592
	v_cvt_pk_bf16_f32 v3, v26, s0
	ds_write_b16 v4, v3 offset:2656
	v_cvt_pk_bf16_f32 v3, v27, s0
	ds_write_b16 v2, v3 offset:2304
	v_cvt_pk_bf16_f32 v3, v28, s0
	ds_write_b16 v2, v3 offset:2368
	v_cvt_pk_bf16_f32 v3, v29, s0
	ds_write_b16 v4, v3 offset:3456
	v_cvt_pk_bf16_f32 v3, v30, s0
	s_lshl_b32 s1, s11, 12
	ds_write_b16 v4, v3 offset:3520
	v_cvt_pk_bf16_f32 v3, v31, s0
	s_add_i32 s42, s82, s1
	ds_write_b16 v4, v3 offset:3600
	v_cvt_pk_bf16_f32 v3, v32, s0
	s_ashr_i32 s43, s42, 31
	ds_write_b16 v4, v3 offset:3664
	v_cvt_pk_bf16_f32 v3, v33, s0
	s_lshl_b64 s[42:43], s[42:43], 11
	v_readlane_b32 s11, v255, 54
	ds_write_b16 v4, v3 offset:3744
	v_cvt_pk_bf16_f32 v3, v34, s0
	s_add_u32 s11, s11, s42
	v_readlane_b32 s17, v255, 55
	ds_write_b16 v4, v3 offset:3808
	v_cvt_pk_bf16_f32 v3, v35, s0
	s_addc_u32 s17, s17, s43
	ds_write_b16 v2, v3 offset:3456
	v_cvt_pk_bf16_f32 v3, v36, s0
	s_add_u32 s42, s11, s16
	ds_write_b16 v2, v3 offset:3520
	s_addc_u32 s43, s17, 0
	v_lshlrev_b32_e32 v0, 4, v0
	v_mul_lo_u32 v2, v148, s36
	s_waitcnt lgkmcnt(0)
	v_lshl_add_u64 v[6:7], s[42:43], 0, v[0:1]
	v_add3_u32 v0, v37, v0, v2
	ds_read_b128 v[2:5], v0
	v_ashrrev_i32_e32 v149, 31, v148
	v_lshlrev_b64 v[8:9], 11, v[148:149]
	v_lshl_add_u64 v[10:11], v[6:7], 0, v[8:9]
	ds_read_b128 v[6:9], v0 offset:1152
	s_waitcnt lgkmcnt(1)
	global_store_dwordx4 v[10:11], v[2:5], off sc1
	s_lshl_b32 s11, s10, 8
	v_readlane_b32 s17, v251, 7
	v_add_co_u32_e32 v2, vcc, s14, v10
	s_add_i32 s82, s11, s17
	s_nop 0
	v_addc_co_u32_e32 v3, vcc, 0, v11, vcc
	s_waitcnt lgkmcnt(0)
	global_store_dwordx4 v[2:3], v[6:9], off sc1
	ds_read_b128 v[2:5], v0 offset:2304
	ds_read_b128 v[6:9], v0 offset:3456
	v_add_co_u32_e32 v12, vcc, s81, v10
	s_mul_i32 s36, s82, 0x1400
	s_nop 0
	v_addc_co_u32_e32 v13, vcc, 0, v11, vcc
	s_waitcnt lgkmcnt(1)
	global_store_dwordx4 v[12:13], v[2:5], off sc1
	v_mov_b32_e32 v144, v226
	v_mov_b32_e32 v0, v227
	v_add_co_u32_e32 v2, vcc, s18, v10
	s_mov_b32 s83, s37
	s_nop 0
	v_addc_co_u32_e32 v3, vcc, 0, v11, vcc
	s_mul_hi_u32 s17, s82, 0x1400
	s_add_u32 s42, s84, s36
	s_waitcnt lgkmcnt(0)
	global_store_dwordx4 v[2:3], v[6:9], off sc1
	s_addc_u32 s43, s85, s17
	v_and_b32_e32 v161, 31, v144
	v_ashrrev_i32_e32 v18, 5, v144
	s_lshl_b64 s[44:45], s[82:83], 2
	v_mul_u32_u24_e32 v0, 0xa00, v161
	v_lshlrev_b32_e32 v148, 2, v18
	s_add_u32 s44, s28, s44
	v_lshl_add_u32 v0, v18, 3, v0
	s_addc_u32 s45, s29, s45
	v_ashrrev_i32_e32 v149, 31, v148
	v_lshl_add_u64 v[2:3], v[0:1], 1, s[42:43]
	v_lshl_add_u64 v[14:15], v[148:149], 2, s[44:45]
	global_load_dwordx4 v[128:131], v[2:3], off offset:2048
	global_load_dwordx4 v[20:23], v[2:3], off offset:3072
	s_nop 0
	global_load_dwordx4 v[2:5], v[14:15], off
	global_load_dwordx4 v[6:9], v[14:15], off offset:32
	global_load_dwordx4 v[10:13], v[14:15], off offset:64
	s_nop 0
	global_load_dwordx4 v[14:17], v[14:15], off offset:96
	v_add_u32_e32 v24, 16, v0
	v_mov_b32_e32 v25, v1
	v_lshl_add_u64 v[28:29], v[24:25], 1, s[42:43]
	global_load_dwordx4 v[24:27], v[28:29], off offset:3072
	global_load_dwordx4 v[140:143], v[28:29], off offset:2048
	s_waitcnt vmcnt(2)
	v_mfma_f32_32x32x16_bf16 v[2:17], v[20:23], v[128:131], v[2:17]
	v_add_u32_e32 v20, 32, v0
	v_mov_b32_e32 v21, v1
	v_lshl_add_u64 v[28:29], v[20:21], 1, s[42:43]
	global_load_dwordx4 v[20:23], v[28:29], off offset:3072
	global_load_dwordx4 v[136:139], v[28:29], off offset:2048
	v_add_u32_e32 v0, 48, v0
	v_lshl_add_u64 v[28:29], v[0:1], 1, s[42:43]
	s_waitcnt vmcnt(2)
	v_mfma_f32_32x32x16_bf16 v[2:17], v[24:27], v[140:143], v[2:17]
	global_load_dwordx4 v[24:27], v[28:29], off offset:3072
	global_load_dwordx4 v[132:135], v[28:29], off offset:2048
	v_cmp_gt_i32_e64 s[42:43], v148, v161
	v_cmp_lt_i32_e64 s[44:45], v148, v161
	v_cmp_eq_u32_e32 vcc, 0, v144
	s_waitcnt vmcnt(2)
	v_mfma_f32_32x32x16_bf16 v[2:17], v[20:23], v[136:139], v[2:17]
	s_waitcnt vmcnt(0)
	v_mfma_f32_32x32x16_bf16 v[2:17], v[24:27], v[132:135], v[2:17]
	s_nop 11
	v_max_f32_e32 v0, v2, v2
	v_max_f32_e32 v0, 0xff800000, v0
	v_cndmask_b32_e64 v0, v0, v220, s[42:43]
	v_max_f32_e32 v2, v3, v3
	v_max_f32_e32 v2, v0, v2
	v_cndmask_b32_e64 v0, v0, v2, s[44:45]
	v_or_b32_e32 v2, 2, v148
	v_max_f32_e32 v3, v4, v4
	v_max_f32_e32 v3, v0, v3
	v_cmp_gt_i32_e64 s[46:47], v2, v161
	v_or_b32_e32 v2, 3, v148
	v_cmp_gt_i32_e64 s[48:49], v2, v161
	v_cndmask_b32_e64 v0, v3, v0, s[46:47]
	v_max_f32_e32 v3, v5, v5
	v_max_f32_e32 v3, v0, v3
	v_cndmask_b32_e64 v0, v3, v0, s[48:49]
	v_add_u32_e32 v2, 8, v148
	v_max_f32_e32 v3, v6, v6
	v_max_f32_e32 v3, v0, v3
	v_cmp_gt_i32_e64 s[50:51], v2, v161
	v_add_u32_e32 v2, 9, v148
	v_max_f32_e32 v4, v7, v7
	v_cndmask_b32_e64 v0, v3, v0, s[50:51]
	v_max_f32_e32 v3, v0, v0
	v_max_f32_e32 v3, v3, v4
	v_cmp_gt_i32_e64 s[52:53], v2, v161
	v_add_u32_e32 v2, 10, v148
	v_max_f32_e32 v4, v8, v8
	v_cndmask_b32_e64 v0, v3, v0, s[52:53]
	v_max_f32_e32 v3, v0, v0
	v_max_f32_e32 v3, v3, v4
	v_cmp_gt_i32_e64 s[54:55], v2, v161
	v_add_u32_e32 v2, 11, v148
	v_max_f32_e32 v4, v9, v9
	v_cndmask_b32_e64 v0, v3, v0, s[54:55]
	v_max_f32_e32 v3, v0, v0
	v_max_f32_e32 v3, v3, v4
	v_cmp_gt_i32_e64 s[56:57], v2, v161
	v_add_u32_e32 v2, 16, v148
	v_max_f32_e32 v4, v10, v10
	v_cndmask_b32_e64 v0, v3, v0, s[56:57]
	v_max_f32_e32 v3, v0, v0
	v_max_f32_e32 v3, v3, v4
	v_cmp_gt_i32_e64 s[58:59], v2, v161
	v_add_u32_e32 v2, 17, v148
	v_max_f32_e32 v4, v11, v11
	v_cndmask_b32_e64 v0, v3, v0, s[58:59]
	v_max_f32_e32 v3, v0, v0
	v_max_f32_e32 v3, v3, v4
	v_cmp_gt_i32_e64 s[60:61], v2, v161
	v_add_u32_e32 v2, 18, v148
	v_max_f32_e32 v4, v12, v12
	v_cndmask_b32_e64 v0, v3, v0, s[60:61]
	v_max_f32_e32 v3, v0, v0
	v_max_f32_e32 v3, v3, v4
	v_cmp_gt_i32_e64 s[62:63], v2, v161
	v_add_u32_e32 v2, 19, v148
	v_max_f32_e32 v4, v13, v13
	v_cndmask_b32_e64 v0, v3, v0, s[62:63]
	v_max_f32_e32 v3, v0, v0
	v_max_f32_e32 v3, v3, v4
	v_cmp_gt_i32_e64 s[64:65], v2, v161
	v_add_u32_e32 v2, 24, v148
	v_max_f32_e32 v4, v14, v14
	v_cndmask_b32_e64 v0, v3, v0, s[64:65]
	v_max_f32_e32 v3, v0, v0
	v_max_f32_e32 v3, v3, v4
	v_cmp_gt_i32_e64 s[66:67], v2, v161
	v_add_u32_e32 v2, 25, v148
	v_max_f32_e32 v4, v15, v15
	v_cndmask_b32_e64 v0, v3, v0, s[66:67]
	v_max_f32_e32 v3, v0, v0
	v_max_f32_e32 v3, v3, v4
	v_cmp_gt_i32_e64 s[68:69], v2, v161
	v_add_u32_e32 v2, 26, v148
	v_max_f32_e32 v5, v16, v16
	v_cndmask_b32_e64 v0, v3, v0, s[68:69]
	global_load_dword v3, v1, s[96:97]
	v_max_f32_e32 v4, v0, v0
	v_max_f32_e32 v4, v4, v5
	v_cmp_gt_i32_e64 s[70:71], v2, v161
	v_max_f32_e32 v5, v17, v17
	v_and_b32_e32 v6, 0xffff0000, v128
	v_cndmask_b32_e64 v0, v4, v0, s[70:71]
	v_max_f32_e32 v4, v0, v0
	v_max_f32_e32 v4, v4, v5
	v_lshlrev_b32_e32 v5, 16, v128
	v_mul_f32_e32 v6, v6, v6
	v_fmac_f32_e32 v6, v5, v5
	v_lshlrev_b32_e32 v5, 16, v129
	v_fmac_f32_e32 v6, v5, v5
	v_and_b32_e32 v5, 0xffff0000, v129
	v_fmac_f32_e32 v6, v5, v5
	v_lshlrev_b32_e32 v5, 16, v130
	v_fmac_f32_e32 v6, v5, v5
	v_and_b32_e32 v5, 0xffff0000, v130
	v_fmac_f32_e32 v6, v5, v5
	v_lshlrev_b32_e32 v5, 16, v131
	v_fmac_f32_e32 v6, v5, v5
	v_and_b32_e32 v5, 0xffff0000, v131
	v_fmac_f32_e32 v6, v5, v5
	v_lshlrev_b32_e32 v5, 16, v140
	v_fmac_f32_e32 v6, v5, v5
	v_and_b32_e32 v5, 0xffff0000, v140
	v_fmac_f32_e32 v6, v5, v5
	v_lshlrev_b32_e32 v5, 16, v141
	v_fmac_f32_e32 v6, v5, v5
	v_and_b32_e32 v5, 0xffff0000, v141
	v_fmac_f32_e32 v6, v5, v5
	v_lshlrev_b32_e32 v5, 16, v142
	v_fmac_f32_e32 v6, v5, v5
	v_and_b32_e32 v5, 0xffff0000, v142
	v_fmac_f32_e32 v6, v5, v5
	v_lshlrev_b32_e32 v5, 16, v143
	v_fmac_f32_e32 v6, v5, v5
	v_and_b32_e32 v5, 0xffff0000, v143
	v_fmac_f32_e32 v6, v5, v5
	v_lshlrev_b32_e32 v5, 16, v136
	v_fmac_f32_e32 v6, v5, v5
	v_and_b32_e32 v5, 0xffff0000, v136
	v_fmac_f32_e32 v6, v5, v5
	v_lshlrev_b32_e32 v5, 16, v137
	v_fmac_f32_e32 v6, v5, v5
	v_and_b32_e32 v5, 0xffff0000, v137
	v_fmac_f32_e32 v6, v5, v5
	v_lshlrev_b32_e32 v5, 16, v138
	v_fmac_f32_e32 v6, v5, v5
	v_and_b32_e32 v5, 0xffff0000, v138
	v_fmac_f32_e32 v6, v5, v5
	v_lshlrev_b32_e32 v5, 16, v139
	v_fmac_f32_e32 v6, v5, v5
	v_and_b32_e32 v5, 0xffff0000, v139
	v_fmac_f32_e32 v6, v5, v5
	v_lshlrev_b32_e32 v5, 16, v132
	v_fmac_f32_e32 v6, v5, v5
	v_and_b32_e32 v5, 0xffff0000, v132
	v_fmac_f32_e32 v6, v5, v5
	v_lshlrev_b32_e32 v5, 16, v133
	v_fmac_f32_e32 v6, v5, v5
	v_and_b32_e32 v5, 0xffff0000, v133
	v_fmac_f32_e32 v6, v5, v5
	v_lshlrev_b32_e32 v5, 16, v134
	v_fmac_f32_e32 v6, v5, v5
	v_and_b32_e32 v5, 0xffff0000, v134
	v_fmac_f32_e32 v6, v5, v5
	v_lshlrev_b32_e32 v5, 16, v135
	v_fmac_f32_e32 v6, v5, v5
	v_and_b32_e32 v5, 0xffff0000, v135
	v_fmac_f32_e32 v6, v5, v5
	v_add_u32_e32 v2, 27, v148
	ds_bpermute_b32 v5, v147, v6
	v_cmp_gt_i32_e64 s[72:73], v2, v161
	s_nop 1
	v_cndmask_b32_e64 v0, v4, v0, s[72:73]
	ds_bpermute_b32 v2, v147, v0
	s_waitcnt lgkmcnt(1)
	v_add_f32_e32 v4, v6, v5
	s_waitcnt vmcnt(0)
	v_mul_f32_e32 v3, v3, v4
	v_sqrt_f32_e32 v3, v3
	v_max_f32_e32 v0, v0, v0
	s_waitcnt lgkmcnt(0)
	v_max_f32_e32 v2, v2, v2
	v_max_f32_e32 v0, v0, v2
	v_add_f32_e32 v162, 0xc2200000, v0
	v_fmamk_f32 v0, v3, 0xbf8020c5, v162
	v_add_f32_e32 v0, 0xbc23d70a, v0
	ds_bpermute_b32 v2, v156, v0
	s_waitcnt lgkmcnt(0)
	v_max_f32_e32 v2, v2, v2
	v_min_f32_e32 v0, v0, v2
	ds_bpermute_b32 v2, v157, v0
	s_waitcnt lgkmcnt(0)
	v_max_f32_e32 v2, v2, v2
	v_min_f32_e32 v0, v0, v2
	ds_bpermute_b32 v2, v158, v0
	s_waitcnt lgkmcnt(0)
	v_max_f32_e32 v2, v2, v2
	v_min_f32_e32 v0, v0, v2
	ds_bpermute_b32 v2, v159, v0
	s_waitcnt lgkmcnt(0)
	v_max_f32_e32 v2, v2, v2
	v_min_f32_e32 v0, v0, v2
	ds_bpermute_b32 v2, v160, v0
	s_and_saveexec_b64 s[74:75], vcc
	s_cbranch_execz .LBB0_294
	s_waitcnt lgkmcnt(0)
	v_max_f32_e32 v2, v2, v2
	v_max_f32_e32 v0, v0, v0
	v_readlane_b32 s17, v251, 13
	v_min_f32_e32 v0, v0, v2
	s_nop 0
	v_mov_b32_e32 v2, s17
	ds_write_b32 v2, v0

.LBB0_372:
	s_and_b32 s1, 0xffff, s9
	s_lshl_b32 s1, s1, 8
	v_lshl_add_u32 v130, s4, 8, v137
	v_lshl_or_b32 v0, v136, 3, s1
	v_ashrrev_i32_e32 v131, 31, v130
	v_or_b32_e32 v0, s26, v0
	v_or_b32_e32 v132, 16, v130
	v_or_b32_e32 v134, 32, v130
	v_or_b32_e32 v136, 48, v130
	v_lshlrev_b64 v[130:131], 11, v[130:131]
	v_lshl_add_u64 v[130:131], s[28:29], 0, v[130:131]
	v_lshlrev_b32_e32 v0, 1, v0
	v_lshl_add_u64 v[130:131], v[130:131], 0, v[0:1]
	s_mov_b32 s1, 0x40000
	s_mov_b64 s[4:5], 0x40000
	v_cvt_pk_bf16_f32 v62, v62, v63
	v_cvt_pk_bf16_f32 v63, v64, v65
	v_cvt_pk_bf16_f32 v64, v58, v59
	v_add_co_u32_e32 v58, vcc, s1, v130
	v_cvt_pk_bf16_f32 v70, v70, v71
	v_cvt_pk_bf16_f32 v71, v72, v73
	v_cvt_pk_bf16_f32 v72, v66, v67
	v_lshl_add_u64 v[66:67], v[130:131], 0, s[4:5]
	v_addc_co_u32_e32 v59, vcc, 0, v131, vcc
	v_cvt_pk_bf16_f32 v46, v46, v47
	v_cvt_pk_bf16_f32 v47, v48, v49
	v_cvt_pk_bf16_f32 v48, v42, v43
	v_cvt_pk_bf16_f32 v49, v44, v45
	s_mov_b32 s1, 0x48000
	v_ashrrev_i32_e32 v133, 31, v132
	global_store_dwordx4 v[66:67], v[46:49], off offset:256 sc1
	s_mov_b64 s[4:5], 0x48000
	v_ashrrev_i32_e32 v135, 31, v134
	v_add_co_u32_e32 v48, vcc, s1, v130
	v_cvt_pk_bf16_f32 v110, v110, v111
	v_cvt_pk_bf16_f32 v111, v112, v113
	v_cvt_pk_bf16_f32 v112, v106, v107
	v_lshlrev_b64 v[106:107], 11, v[132:133]
	v_lshl_add_u64 v[46:47], v[130:131], 0, s[4:5]
	v_addc_co_u32_e32 v49, vcc, 0, v131, vcc
	v_cvt_pk_bf16_f32 v30, v30, v31
	v_cvt_pk_bf16_f32 v31, v32, v33
	v_cvt_pk_bf16_f32 v32, v26, v27
	v_cvt_pk_bf16_f32 v33, v28, v29
	s_mov_b32 s1, 0x50000
	v_ashrrev_i32_e32 v137, 31, v136
	v_cvt_pk_bf16_f32 v113, v108, v109
	v_lshl_add_u64 v[106:107], s[28:29], 0, v[106:107]
	v_cvt_pk_bf16_f32 v94, v94, v95
	v_cvt_pk_bf16_f32 v95, v96, v97
	v_cvt_pk_bf16_f32 v96, v90, v91
	v_lshlrev_b64 v[90:91], 11, v[134:135]
	global_store_dwordx4 v[46:47], v[30:33], off offset:256 sc1
	global_store_dwordx4 v[130:131], v[110:113], off offset:256 sc1
	v_cvt_pk_bf16_f32 v97, v92, v93
	v_add_co_u32_e32 v32, vcc, s1, v130
	v_lshl_add_u64 v[110:111], v[106:107], 0, v[0:1]
	v_lshl_add_u64 v[90:91], s[28:29], 0, v[90:91]
	v_cvt_pk_bf16_f32 v78, v78, v79
	v_cvt_pk_bf16_f32 v79, v80, v81
	v_cvt_pk_bf16_f32 v80, v74, v75
	v_lshlrev_b64 v[74:75], 11, v[136:137]
	v_lshl_add_u64 v[30:31], v[130:131], 0, s[92:93]
	v_addc_co_u32_e32 v33, vcc, 0, v131, vcc
	v_cvt_pk_bf16_f32 v14, v14, v15
	v_cvt_pk_bf16_f32 v15, v16, v17
	v_cvt_pk_bf16_f32 v16, v10, v11
	v_cvt_pk_bf16_f32 v17, v12, v13
	s_mov_b32 s1, 0x58000
	global_store_dwordx4 v[110:111], v[94:97], off offset:256 sc1
	v_cvt_pk_bf16_f32 v81, v76, v77
	v_lshl_add_u64 v[74:75], s[28:29], 0, v[74:75]
	v_lshl_add_u64 v[94:95], v[90:91], 0, v[0:1]
	global_store_dwordx4 v[30:31], v[14:17], off offset:256 sc1
	s_mov_b64 s[4:5], 0x58000
	v_cvt_pk_bf16_f32 v126, v126, v127
	v_add_co_u32_e32 v16, vcc, s1, v130
	v_cvt_pk_bf16_f32 v127, v128, v129
	v_cvt_pk_bf16_f32 v128, v122, v123
	v_cvt_pk_bf16_f32 v129, v124, v125
	v_cvt_pk_bf16_f32 v106, v118, v119
	v_cvt_pk_bf16_f32 v107, v120, v121
	v_cvt_pk_bf16_f32 v108, v114, v115
	v_cvt_pk_bf16_f32 v109, v116, v117
	v_cvt_pk_bf16_f32 v90, v102, v103
	v_cvt_pk_bf16_f32 v91, v104, v105
	v_cvt_pk_bf16_f32 v92, v98, v99
	v_cvt_pk_bf16_f32 v93, v100, v101
	global_store_dwordx4 v[94:95], v[78:81], off offset:256 sc1
	v_cvt_pk_bf16_f32 v76, v82, v83
	v_cvt_pk_bf16_f32 v77, v84, v85
	v_lshl_add_u64 v[78:79], v[74:75], 0, v[0:1]
	v_cvt_pk_bf16_f32 v74, v86, v87
	v_cvt_pk_bf16_f32 v75, v88, v89
	v_cvt_pk_bf16_f32 v73, v68, v69
	v_cvt_pk_bf16_f32 v65, v60, v61
	v_cvt_pk_bf16_f32 v42, v54, v55
	v_cvt_pk_bf16_f32 v43, v56, v57
	v_cvt_pk_bf16_f32 v44, v50, v51
	v_cvt_pk_bf16_f32 v45, v52, v53
	v_cvt_pk_bf16_f32 v26, v38, v39
	v_cvt_pk_bf16_f32 v27, v40, v41
	v_cvt_pk_bf16_f32 v28, v34, v35
	v_cvt_pk_bf16_f32 v29, v36, v37
	v_lshl_add_u64 v[14:15], v[130:131], 0, s[4:5]
	v_cvt_pk_bf16_f32 v10, v22, v23
	v_cvt_pk_bf16_f32 v11, v24, v25
	v_cvt_pk_bf16_f32 v12, v18, v19
	v_cvt_pk_bf16_f32 v13, v20, v21
	v_addc_co_u32_e32 v17, vcc, 0, v131, vcc
	v_cvt_pk_bf16_f32 v6, v6, v7
	v_cvt_pk_bf16_f32 v7, v8, v9
	v_cvt_pk_bf16_f32 v8, v2, v3
	v_cvt_pk_bf16_f32 v9, v4, v5
	global_store_dwordx4 v[130:131], v[126:129], off sc1
	global_store_dwordx4 v[110:111], v[106:109], off sc1
	global_store_dwordx4 v[94:95], v[90:93], off sc1
	global_store_dwordx4 v[78:79], v[74:77], off sc1
	global_store_dwordx4 v[78:79], v[70:73], off offset:256 sc1
	global_store_dwordx4 v[58:59], v[62:65], off sc1
	global_store_dwordx4 v[48:49], v[42:45], off sc1
	global_store_dwordx4 v[32:33], v[26:29], off sc1
	global_store_dwordx4 v[16:17], v[10:13], off sc1
	global_store_dwordx4 v[14:15], v[6:9], off offset:256 sc1
	s_waitcnt vmcnt(0)
	s_barrier
	v_readlane_b32 s66, v255, 31

.LBB0_387:
	v_readlane_b32 s10, v255, 34
	v_readlane_b32 s11, v255, 35
	s_load_dwordx2 s[10:11], s[10:11], 0xf0
	s_mul_i32 s23, s23, s22
	v_or_b32_e32 v50, s42, v12
	s_waitcnt lgkmcnt(0)
	s_add_u32 s10, s10, s30
	s_addc_u32 s11, s11, s31
	s_sub_i32 s9, s9, s23
	s_lshl_b32 s28, s9, 5
	s_ashr_i32 s29, s28, 31
	s_lshl_b64 s[22:23], s[28:29], 2
	s_add_u32 s16, s16, s22
	s_addc_u32 s17, s17, s23
	v_lshl_add_u64 v[2:3], s[16:17], 0, v[0:1]
	v_mad_i64_i32 v[4:5], s[16:17], v50, s5, 0
	v_lshl_add_u64 v[4:5], v[4:5], 2, v[2:3]
	global_load_dwordx4 v[26:29], v[4:5], off
	v_or_b32_e32 v4, 8, v50
	v_mad_i64_i32 v[4:5], s[16:17], v4, s5, 0
	v_lshl_add_u64 v[4:5], v[4:5], 2, v[2:3]
	global_load_dwordx4 v[30:33], v[4:5], off
	v_or_b32_e32 v4, 16, v50
	v_mad_i64_i32 v[4:5], s[16:17], v4, s5, 0
	v_lshl_add_u64 v[4:5], v[4:5], 2, v[2:3]
	global_load_dwordx4 v[34:37], v[4:5], off
	v_or_b32_e32 v4, 24, v50
	v_mad_i64_i32 v[4:5], s[16:17], v4, s5, 0
	v_lshl_add_u64 v[4:5], v[4:5], 2, v[2:3]
	global_load_dwordx4 v[38:41], v[4:5], off
	v_or_b32_e32 v4, 32, v50
	v_mad_i64_i32 v[4:5], s[16:17], v4, s5, 0
	v_lshl_add_u64 v[4:5], v[4:5], 2, v[2:3]
	global_load_dwordx4 v[42:45], v[4:5], off
	v_or_b32_e32 v4, 40, v50
	v_mad_i64_i32 v[4:5], s[16:17], v4, s5, 0
	v_lshl_add_u64 v[4:5], v[4:5], 2, v[2:3]
	global_load_dwordx4 v[46:49], v[4:5], off
	v_or_b32_e32 v4, 48, v50
	v_mad_i64_i32 v[4:5], s[16:17], v4, s5, 0
	v_lshl_add_u64 v[4:5], v[4:5], 2, v[2:3]
	global_load_dwordx4 v[6:9], v[4:5], off
	v_or_b32_e32 v4, 56, v50
	v_mad_i64_i32 v[4:5], s[16:17], v4, s5, 0
	v_lshl_add_u64 v[2:3], v[4:5], 2, v[2:3]
	global_load_dwordx4 v[2:5], v[2:3], off
	s_waitcnt vmcnt(0)
	ds_bpermute_b32 v50, v13, v11
	s_ashr_i32 s43, s42, 31
	s_lshl_b64 s[16:17], s[42:43], 1
	s_add_u32 s10, s10, s16
	s_addc_u32 s11, s11, s17
	s_waitcnt lgkmcnt(0)
	v_pk_mul_f32 v[26:27], v[26:27], v[50:51] op_sel_hi:[1,0]
	ds_write2_b32 v25, v26, v27 offset1:1
	v_pk_mul_f32 v[26:27], v[28:29], v[50:51] op_sel_hi:[1,0]
	ds_write2_b32 v25, v26, v27 offset0:2 offset1:3
	ds_bpermute_b32 v26, v15, v11
	s_waitcnt lgkmcnt(0)
	v_pk_mul_f32 v[28:29], v[30:31], v[26:27] op_sel_hi:[1,0]
	v_add_u32_e32 v27, 0x420, v25
	ds_write2_b32 v27, v28, v29 offset1:1
	v_pk_mul_f32 v[26:27], v[32:33], v[26:27] op_sel_hi:[1,0]
	v_add_u32_e32 v28, 0x428, v25
	ds_write2_b32 v28, v26, v27 offset1:1
	ds_bpermute_b32 v26, v17, v11
	s_waitcnt lgkmcnt(0)
	v_pk_mul_f32 v[28:29], v[34:35], v[26:27] op_sel_hi:[1,0]
	v_add_u32_e32 v27, 0x840, v25
	ds_write2_b32 v27, v28, v29 offset1:1
	v_pk_mul_f32 v[26:27], v[36:37], v[26:27] op_sel_hi:[1,0]
	v_add_u32_e32 v28, 0x848, v25
	ds_write2_b32 v28, v26, v27 offset1:1
	ds_bpermute_b32 v26, v19, v11
	s_waitcnt lgkmcnt(0)
	v_pk_mul_f32 v[28:29], v[38:39], v[26:27] op_sel_hi:[1,0]
	v_add_u32_e32 v27, 0xc60, v25
	ds_write2_b32 v27, v28, v29 offset1:1
	v_pk_mul_f32 v[26:27], v[40:41], v[26:27] op_sel_hi:[1,0]
	v_add_u32_e32 v28, 0xc68, v25
	ds_write2_b32 v28, v26, v27 offset1:1
	ds_bpermute_b32 v26, v20, v11
	s_waitcnt lgkmcnt(0)
	v_pk_mul_f32 v[28:29], v[42:43], v[26:27] op_sel_hi:[1,0]
	v_add_u32_e32 v27, 0x1080, v25
	ds_write2_b32 v27, v28, v29 offset1:1
	v_pk_mul_f32 v[26:27], v[44:45], v[26:27] op_sel_hi:[1,0]
	v_add_u32_e32 v28, 0x1088, v25
	ds_write2_b32 v28, v26, v27 offset1:1
	ds_bpermute_b32 v26, v21, v11
	s_waitcnt lgkmcnt(0)
	v_pk_mul_f32 v[28:29], v[46:47], v[26:27] op_sel_hi:[1,0]
	v_add_u32_e32 v27, 0x14a0, v25
	ds_write2_b32 v27, v28, v29 offset1:1
	v_pk_mul_f32 v[26:27], v[48:49], v[26:27] op_sel_hi:[1,0]
	v_add_u32_e32 v28, 0x14a8, v25
	ds_write2_b32 v28, v26, v27 offset1:1
	ds_bpermute_b32 v26, v22, v11
	s_waitcnt lgkmcnt(0)
	v_pk_mul_f32 v[6:7], v[6:7], v[26:27] op_sel_hi:[1,0]
	v_add_u32_e32 v27, 0x18c0, v25
	ds_write2_b32 v27, v6, v7 offset1:1
	v_pk_mul_f32 v[6:7], v[8:9], v[26:27] op_sel_hi:[1,0]
	v_add_u32_e32 v8, 0x18c8, v25
	ds_write2_b32 v8, v6, v7 offset1:1
	ds_bpermute_b32 v6, v23, v11
	v_mov_b32_e32 v11, v1
	s_waitcnt lgkmcnt(0)
	v_pk_mul_f32 v[2:3], v[2:3], v[6:7] op_sel_hi:[1,0]
	v_add_u32_e32 v7, 0x1ce0, v25
	ds_write2_b32 v7, v2, v3 offset1:1
	v_pk_mul_f32 v[2:3], v[4:5], v[6:7] op_sel_hi:[1,0]
	v_add_u32_e32 v4, 0x1ce8, v25
	ds_write2_b32 v4, v2, v3 offset1:1
	s_waitcnt lgkmcnt(0)
	ds_read2_b32 v[8:9], v24 offset0:33 offset1:41
	ds_read2_b32 v[26:27], v24 offset1:8
	ds_read2_b32 v[28:29], v24 offset0:66 offset1:74
	ds_read2_b32 v[30:31], v24 offset0:99 offset1:107
	ds_read2_b32 v[32:33], v24 offset0:132 offset1:140
	ds_read2_b32 v[34:35], v24 offset0:165 offset1:173
	ds_read2_b32 v[36:37], v24 offset0:198 offset1:206
	ds_read2_b32 v[38:39], v24 offset0:231 offset1:239
	v_lshl_add_u64 v[6:7], s[10:11], 0, v[10:11]
	s_waitcnt lgkmcnt(6)
	v_cvt_pk_bf16_f32 v2, v26, v8
	v_or_b32_e32 v8, s28, v12
	v_mad_i64_i32 v[40:41], s[10:11], v8, s4, 0
	s_waitcnt lgkmcnt(4)
	v_cvt_pk_bf16_f32 v3, v28, v30
	s_waitcnt lgkmcnt(2)
	v_cvt_pk_bf16_f32 v4, v32, v34
	s_waitcnt lgkmcnt(0)
	v_cvt_pk_bf16_f32 v5, v36, v38
	v_lshl_add_u64 v[40:41], v[40:41], 1, v[6:7]
	v_or_b32_e32 v8, s28, v14
	global_store_dwordx4 v[40:41], v[2:5], off sc1
	s_nop 1
	v_cvt_pk_bf16_f32 v2, v27, v9
	v_mad_i64_i32 v[8:9], s[10:11], v8, s4, 0
	v_cvt_pk_bf16_f32 v3, v29, v31
	v_cvt_pk_bf16_f32 v4, v33, v35
	v_cvt_pk_bf16_f32 v5, v37, v39
	v_lshl_add_u64 v[8:9], v[8:9], 1, v[6:7]
	global_store_dwordx4 v[8:9], v[2:5], off sc1
	ds_read2_b32 v[8:9], v24 offset0:16 offset1:24
	ds_read2_b32 v[26:27], v24 offset0:49 offset1:57
	ds_read2_b32 v[28:29], v24 offset0:82 offset1:90
	ds_read2_b32 v[30:31], v24 offset0:115 offset1:123
	ds_read2_b32 v[32:33], v24 offset0:148 offset1:156
	ds_read2_b32 v[34:35], v24 offset0:181 offset1:189
	ds_read2_b32 v[36:37], v24 offset0:214 offset1:222
	ds_read2_b32 v[38:39], v24 offset0:247 offset1:255
	s_waitcnt lgkmcnt(6)
	v_cvt_pk_bf16_f32 v2, v8, v26
	v_or_b32_e32 v8, s28, v16
	v_mad_i64_i32 v[40:41], s[10:11], v8, s4, 0
	s_waitcnt lgkmcnt(4)
	v_cvt_pk_bf16_f32 v3, v28, v30
	s_waitcnt lgkmcnt(2)
	v_cvt_pk_bf16_f32 v4, v32, v34
	s_waitcnt lgkmcnt(0)
	v_cvt_pk_bf16_f32 v5, v36, v38
	v_lshl_add_u64 v[40:41], v[40:41], 1, v[6:7]
	v_or_b32_e32 v8, s28, v18
	global_store_dwordx4 v[40:41], v[2:5], off sc1
	s_nop 1
	v_cvt_pk_bf16_f32 v2, v9, v27
	v_mad_i64_i32 v[8:9], s[4:5], v8, s4, 0
	v_cvt_pk_bf16_f32 v3, v29, v31
	v_cvt_pk_bf16_f32 v4, v33, v35
	v_cvt_pk_bf16_f32 v5, v37, v39
	v_lshl_add_u64 v[6:7], v[8:9], 1, v[6:7]
	global_store_dwordx4 v[6:7], v[2:5], off sc1
	s_waitcnt lgkmcnt(0)
	v_readlane_b32 s4, v254, 49
	s_add_i32 s1, s1, s4
	s_cmpk_lt_i32 s1, 0x1a00
	v_readlane_b32 s5, v254, 50
	s_cbranch_scc0 .LBB0_428

.LBB0_447:
	v_readlane_b32 s4, v255, 46
	v_readlane_b32 s5, v255, 47
	s_and_b64 vcc, exec, s[4:5]
	v_readlane_b32 s9, v255, 28
	v_readlane_b32 s64, v255, 29
	v_readlane_b32 s65, v255, 30
	s_cbranch_vccz .LBB0_625
	v_readlane_b32 s4, v255, 2
	v_readlane_b32 s5, v255, 3
	s_andn2_b64 vcc, exec, s[4:5]
	s_cbranch_vccnz .LBB0_450
	v_readlane_b32 s10, v255, 34
	v_readlane_b32 s11, v255, 35
	s_load_dwordx2 s[10:11], s[10:11], 0xf0
	v_readlane_b32 s4, v251, 34
	v_readlane_b32 s5, v251, 35
	v_lshlrev_b32_e32 v0, 8, v226
	s_waitcnt lgkmcnt(0)
	s_add_u32 s4, s10, s4
	s_addc_u32 s5, s11, s5
	v_lshl_add_u64 v[22:23], s[4:5], 0, v[0:1]
	s_mov_b64 s[4:5], 0xeb00000
	v_lshl_add_u64 v[66:67], v[22:23], 0, s[4:5]
	global_load_dwordx4 v[46:49], v[66:67], off offset:16
	global_load_dwordx4 v[42:45], v[66:67], off offset:32
	global_load_dwordx4 v[14:17], v[66:67], off offset:96
	global_load_dwordx4 v[6:9], v[66:67], off offset:112
	global_load_dwordx4 v[30:33], v[66:67], off offset:128
	global_load_dwordx4 v[18:21], v[66:67], off offset:144
	global_load_dwordx4 v[10:13], v[66:67], off offset:160
	global_load_dwordx4 v[2:5], v[66:67], off offset:176
	global_load_dwordx4 v[38:41], v[66:67], off offset:192
	global_load_dwordx4 v[26:29], v[66:67], off offset:208
	global_load_dwordx4 v[58:61], v[66:67], off offset:48
	global_load_dwordx4 v[54:57], v[66:67], off offset:64
	global_load_dwordx4 v[50:53], v[66:67], off offset:80
	v_add_co_u32_e32 v68, vcc, 0xeb00000, v22
	s_waitcnt vmcnt(0)
	v_add_f32_e32 v0, v46, v47
	v_addc_co_u32_e32 v69, vcc, 0, v23, vcc
	global_load_dwordx4 v[62:65], v[68:69], off
	global_load_dwordx4 v[34:37], v[66:67], off offset:224
	global_load_dwordx4 v[22:25], v[66:67], off offset:240
	v_mov_b32_e32 v70, v14
	v_mov_b32_e32 v71, v6
	v_mov_b32_e32 v72, v15
	v_mov_b32_e32 v73, v7
	v_mov_b32_e32 v74, v16
	v_mov_b32_e32 v75, v8
	v_mov_b32_e32 v76, v17
	v_mov_b32_e32 v77, v9
	v_mov_b32_e32 v78, v30
	v_mov_b32_e32 v79, v18
	v_mov_b32_e32 v80, v31
	v_mov_b32_e32 v81, v19
	v_mov_b32_e32 v82, v32
	v_mov_b32_e32 v83, v20
	v_mov_b32_e32 v84, v33
	v_mov_b32_e32 v85, v21
	v_mov_b32_e32 v86, v10
	v_mov_b32_e32 v87, v2
	v_pk_add_f32 v[70:71], v[70:71], v[72:73]
	v_mov_b32_e32 v72, v11
	v_mov_b32_e32 v73, v3
	v_pk_add_f32 v[74:75], v[74:75], v[76:77]
	v_mov_b32_e32 v76, v12
	v_mov_b32_e32 v77, v4
	v_pk_add_f32 v[78:79], v[78:79], v[80:81]
	v_mov_b32_e32 v80, v13
	v_mov_b32_e32 v81, v5
	v_pk_add_f32 v[82:83], v[82:83], v[84:85]
	v_mov_b32_e32 v84, v38
	v_mov_b32_e32 v85, v26
	v_pk_add_f32 v[72:73], v[86:87], v[72:73]
	v_mov_b32_e32 v86, v39
	v_mov_b32_e32 v87, v27
	v_pk_add_f32 v[76:77], v[76:77], v[80:81]
	v_mov_b32_e32 v80, v40
	v_mov_b32_e32 v81, v28
	v_pk_add_f32 v[84:85], v[84:85], v[86:87]
	v_mov_b32_e32 v86, v41
	v_mov_b32_e32 v87, v29
	v_add_f32_e32 v88, v48, v49
	v_add_f32_e32 v89, v42, v43
	v_pk_add_f32 v[80:81], v[80:81], v[86:87]
	v_add_f32_e32 v86, v44, v45
	v_add_f32_e32 v87, v58, v59
	v_pk_add_f32 v[70:71], v[70:71], v[74:75]
	v_add_f32_e32 v74, v60, v61
	v_add_f32_e32 v75, v54, v55
	v_add_f32_e32 v0, v0, v88
	v_add_f32_e32 v88, v56, v57
	v_add_f32_e32 v86, v89, v86
	v_add_f32_e32 v89, v50, v51
	v_add_f32_e32 v87, v87, v74
	v_add_f32_e32 v74, v52, v53
	v_add_f32_e32 v88, v75, v88
	v_add_f32_e32 v89, v89, v74
	v_pk_add_f32 v[72:73], v[72:73], v[76:77]
	s_waitcnt vmcnt(2)
	v_add_f32_e32 v75, v62, v63
	v_add_f32_e32 v74, v64, v65
	v_add_f32_e32 v90, v75, v74
	v_sub_f32_e64 v0, -v90, v0
	v_sub_f32_e32 v0, v0, v86
	v_sub_f32_e32 v0, v0, v87
	v_sub_f32_e32 v0, v0, v88
	v_sub_f32_e32 v0, v0, v89
	v_sub_f32_e32 v0, v0, v70
	v_pk_add_f32 v[74:75], v[78:79], v[82:83]
	v_sub_f32_e32 v0, v0, v71
	v_sub_f32_e32 v0, v0, v74
	v_sub_f32_e32 v0, v0, v75
	v_sub_f32_e32 v0, v0, v72
	v_sub_f32_e32 v0, v0, v73
	v_pk_add_f32 v[70:71], v[84:85], v[80:81]
	s_waitcnt vmcnt(1)
	v_mov_b32_e32 v72, v35
	v_sub_f32_e32 v0, v0, v70
	v_sub_f32_e32 v0, v0, v71
	v_mov_b32_e32 v70, v34
	s_waitcnt vmcnt(0)
	v_mov_b32_e32 v71, v22
	v_mov_b32_e32 v73, v23
	v_pk_add_f32 v[70:71], v[70:71], v[72:73]
	v_mov_b32_e32 v72, v36
	v_mov_b32_e32 v73, v24
	v_mov_b32_e32 v74, v37
	v_mov_b32_e32 v75, v25
	v_pk_add_f32 v[72:73], v[72:73], v[74:75]
	s_nop 0
	v_pk_add_f32 v[70:71], v[70:71], v[72:73]
	v_and_b32_e32 v72, 64, v211
	v_sub_f32_e32 v0, v0, v70
	v_add_u32_e32 v70, -1, v211
	v_cmp_lt_i32_e32 vcc, v70, v72
	v_sub_f32_e32 v0, v0, v71
	v_add_u32_e32 v71, -2, v211
	v_cndmask_b32_e32 v70, v70, v211, vcc
	v_lshlrev_b32_e32 v70, 2, v70
	ds_bpermute_b32 v70, v70, v0
	v_cmp_eq_u32_e32 vcc, 0, v226
	s_waitcnt lgkmcnt(0)
	v_add_f32_e32 v70, v0, v70
	v_cndmask_b32_e32 v70, v70, v0, vcc
	v_cmp_lt_i32_e32 vcc, v71, v72
	s_nop 1
	v_cndmask_b32_e32 v71, v71, v211, vcc
	v_lshlrev_b32_e32 v71, 2, v71
	ds_bpermute_b32 v71, v71, v70
	v_cmp_gt_u32_e32 vcc, 2, v226
	s_waitcnt lgkmcnt(0)
	v_add_f32_e32 v71, v70, v71
	v_cndmask_b32_e32 v70, v71, v70, vcc
	v_add_u32_e32 v71, -4, v211
	v_cmp_lt_i32_e32 vcc, v71, v72
	s_nop 1
	v_cndmask_b32_e32 v71, v71, v211, vcc
	v_lshlrev_b32_e32 v71, 2, v71
	ds_bpermute_b32 v71, v71, v70
	v_cmp_gt_u32_e32 vcc, 4, v226
	s_waitcnt lgkmcnt(0)
	v_add_f32_e32 v71, v70, v71
	v_cndmask_b32_e32 v70, v71, v70, vcc
	v_add_u32_e32 v71, -8, v211
	v_cmp_lt_i32_e32 vcc, v71, v72
	s_nop 1
	v_cndmask_b32_e32 v71, v71, v211, vcc
	v_lshlrev_b32_e32 v71, 2, v71
	ds_bpermute_b32 v71, v71, v70
	v_cmp_gt_u32_e32 vcc, 8, v226
	s_waitcnt lgkmcnt(0)
	v_add_f32_e32 v71, v70, v71
	v_cndmask_b32_e32 v70, v71, v70, vcc
	v_add_u32_e32 v71, -16, v211
	v_cmp_lt_i32_e32 vcc, v71, v72
	s_nop 1
	v_cndmask_b32_e32 v71, v71, v211, vcc
	v_lshlrev_b32_e32 v71, 2, v71
	ds_bpermute_b32 v71, v71, v70
	v_cmp_gt_u32_e32 vcc, 16, v226
	s_waitcnt lgkmcnt(0)
	v_add_f32_e32 v71, v70, v71
	v_cndmask_b32_e32 v70, v71, v70, vcc
	v_subrev_u32_e32 v71, 32, v211
	v_cmp_lt_i32_e32 vcc, v71, v72
	s_nop 1
	v_cndmask_b32_e32 v71, v71, v211, vcc
	v_lshlrev_b32_e32 v71, 2, v71
	ds_bpermute_b32 v71, v71, v70
	v_cmp_gt_u32_e32 vcc, 32, v226
	s_waitcnt lgkmcnt(0)
	v_add_f32_e32 v71, v70, v71
	v_cndmask_b32_e32 v70, v71, v70, vcc
	v_sub_f32_e32 v0, v70, v0
	v_sub_f32_e32 v62, v0, v62
	v_sub_f32_e32 v63, v62, v63
	v_sub_f32_e32 v64, v63, v64
	v_sub_f32_e32 v65, v64, v65
	v_sub_f32_e32 v46, v65, v46
	v_sub_f32_e32 v47, v46, v47
	v_sub_f32_e32 v48, v47, v48
	v_sub_f32_e32 v49, v48, v49
	v_sub_f32_e32 v42, v49, v42
	v_sub_f32_e32 v43, v42, v43
	v_sub_f32_e32 v44, v43, v44
	v_sub_f32_e32 v45, v44, v45
	global_store_dwordx4 v[66:67], v[42:45], off offset:32 sc1
	global_store_dwordx4 v[68:69], v[62:65], off sc1
	global_store_dwordx4 v[66:67], v[46:49], off offset:16 sc1
	v_sub_f32_e32 v42, v45, v58
	v_sub_f32_e32 v43, v42, v59
	v_sub_f32_e32 v44, v43, v60
	v_sub_f32_e32 v45, v44, v61
	global_store_dwordx4 v[66:67], v[42:45], off offset:48 sc1
	s_nop 1
	v_sub_f32_e32 v42, v45, v54
	v_sub_f32_e32 v43, v42, v55
	v_sub_f32_e32 v44, v43, v56
	v_sub_f32_e32 v45, v44, v57
	global_store_dwordx4 v[66:67], v[42:45], off offset:64 sc1
	s_nop 1
	v_sub_f32_e32 v42, v45, v50
	v_sub_f32_e32 v43, v42, v51
	v_sub_f32_e32 v44, v43, v52
	v_sub_f32_e32 v45, v44, v53
	v_sub_f32_e32 v14, v45, v14
	v_sub_f32_e32 v15, v14, v15
	v_sub_f32_e32 v16, v15, v16
	v_sub_f32_e32 v17, v16, v17
	v_sub_f32_e32 v6, v17, v6
	v_sub_f32_e32 v7, v6, v7
	v_sub_f32_e32 v8, v7, v8
	v_sub_f32_e32 v9, v8, v9
	global_store_dwordx4 v[66:67], v[6:9], off offset:112 sc1
	global_store_dwordx4 v[66:67], v[42:45], off offset:80 sc1
	global_store_dwordx4 v[66:67], v[14:17], off offset:96 sc1
	v_sub_f32_e32 v6, v9, v30
	v_sub_f32_e32 v7, v6, v31
	v_sub_f32_e32 v8, v7, v32
	v_sub_f32_e32 v9, v8, v33
	global_store_dwordx4 v[66:67], v[6:9], off offset:128 sc1
	s_nop 1
	v_sub_f32_e32 v6, v9, v18
	v_sub_f32_e32 v7, v6, v19
	v_sub_f32_e32 v8, v7, v20
	v_sub_f32_e32 v9, v8, v21
	global_store_dwordx4 v[66:67], v[6:9], off offset:144 sc1
	s_nop 1
	v_sub_f32_e32 v6, v9, v10
	v_sub_f32_e32 v7, v6, v11
	v_sub_f32_e32 v8, v7, v12
	v_sub_f32_e32 v9, v8, v13
	v_sub_f32_e32 v2, v9, v2
	v_sub_f32_e32 v3, v2, v3
	v_sub_f32_e32 v4, v3, v4
	v_sub_f32_e32 v5, v4, v5
	global_store_dwordx4 v[66:67], v[2:5], off offset:176 sc1
	global_store_dwordx4 v[66:67], v[6:9], off offset:160 sc1
	s_nop 0
	v_sub_f32_e32 v2, v5, v38
	v_sub_f32_e32 v3, v2, v39
	v_sub_f32_e32 v4, v3, v40
	v_sub_f32_e32 v5, v4, v41
	global_store_dwordx4 v[66:67], v[2:5], off offset:192 sc1
	s_nop 1
	v_sub_f32_e32 v2, v5, v26
	v_sub_f32_e32 v3, v2, v27
	v_sub_f32_e32 v4, v3, v28
	v_sub_f32_e32 v5, v4, v29
	global_store_dwordx4 v[66:67], v[2:5], off offset:208 sc1
	s_nop 1
	v_sub_f32_e32 v2, v5, v34
	v_sub_f32_e32 v3, v2, v35
	v_sub_f32_e32 v4, v3, v36
	v_sub_f32_e32 v5, v4, v37
	global_store_dwordx4 v[66:67], v[2:5], off offset:224 sc1
	s_nop 1
	v_sub_f32_e32 v2, v5, v22
	v_sub_f32_e32 v3, v2, v23
	v_sub_f32_e32 v4, v3, v24
	v_sub_f32_e32 v5, v4, v25
	global_store_dwordx4 v[66:67], v[2:5], off offset:240 sc1

.LBB0_474:
	s_cmp_ge_i32 s67, s9
	s_cselect_b64 s[44:45], -1, 0
	s_cmp_lt_i32 s67, s5
	s_cselect_b64 s[60:61], -1, 0
	v_mov_b32_e32 v143, s4
	s_and_b64 vcc, s[44:45], s[60:61]
	v_lshl_or_b32 v160, s67, 8, v154
	v_cndmask_b32_e32 v145, 1.0, v143, vcc
	v_ashrrev_i32_e32 v161, 31, v160
	v_mul_f32_e32 v162, v145, v142
	v_mad_i64_i32 v[142:143], s[44:45], v144, s1, 0
	v_lshl_add_u64 v[164:165], v[142:143], 1, s[16:17]
	v_lshlrev_b64 v[142:143], 1, v[160:161]
	v_lshl_add_u64 v[160:161], v[164:165], 0, v[142:143]
	v_pk_mul_f32 v[128:129], v[128:129], v[162:163] op_sel_hi:[1,0]
	v_pk_mul_f32 v[126:127], v[126:127], v[162:163] op_sel_hi:[1,0]
	v_pk_mul_f32 v[164:165], v[124:125], v[162:163] op_sel_hi:[1,0]
	v_pk_mul_f32 v[124:125], v[122:123], v[162:163] op_sel_hi:[1,0]
	v_cvt_pk_bf16_f32 v122, v126, v127
	v_cvt_pk_bf16_f32 v123, v128, v129
	v_cvt_pk_bf16_f32 v124, v124, v125
	v_cvt_pk_bf16_f32 v125, v164, v165
	global_store_dwordx4 v[160:161], v[122:125], off sc1
	v_pk_mul_f32 v[120:121], v[120:121], v[162:163] op_sel_hi:[1,0]
	v_pk_mul_f32 v[118:119], v[118:119], v[162:163] op_sel_hi:[1,0]
	v_pk_mul_f32 v[122:123], v[112:113], v[162:163] op_sel_hi:[1,0]
	v_pk_mul_f32 v[112:113], v[110:111], v[162:163] op_sel_hi:[1,0]
	v_cvt_pk_bf16_f32 v110, v118, v119
	v_cvt_pk_bf16_f32 v111, v120, v121
	v_cvt_pk_bf16_f32 v112, v112, v113
	v_cvt_pk_bf16_f32 v113, v122, v123
	global_store_dwordx4 v[160:161], v[110:113], off offset:256 sc1
	s_andn2_b64 vcc, exec, s[50:51]
	s_nop 0
	v_mad_u64_u32 v[112:113], s[44:45], v150, s1, 0
	v_mov_b32_e32 v118, v113
	v_mad_u64_u32 v[118:119], s[44:45], v151, s1, v[118:119]
	v_mul_f32_e32 v110, v145, v156
	v_mov_b32_e32 v113, v118
	v_lshl_add_u64 v[112:113], v[112:113], 1, s[16:17]
	v_pk_mul_f32 v[116:117], v[116:117], v[110:111] op_sel_hi:[1,0]
	v_pk_mul_f32 v[114:115], v[114:115], v[110:111] op_sel_hi:[1,0]
	v_pk_mul_f32 v[118:119], v[108:109], v[110:111] op_sel_hi:[1,0]
	v_pk_mul_f32 v[108:109], v[106:107], v[110:111] op_sel_hi:[1,0]
	v_lshl_add_u64 v[112:113], v[112:113], 0, v[142:143]
	v_cvt_pk_bf16_f32 v106, v114, v115
	v_cvt_pk_bf16_f32 v107, v116, v117
	v_cvt_pk_bf16_f32 v108, v108, v109
	v_cvt_pk_bf16_f32 v109, v118, v119
	global_store_dwordx4 v[112:113], v[106:109], off sc1
	v_pk_mul_f32 v[104:105], v[104:105], v[110:111] op_sel_hi:[1,0]
	v_pk_mul_f32 v[102:103], v[102:103], v[110:111] op_sel_hi:[1,0]
	v_pk_mul_f32 v[106:107], v[96:97], v[110:111] op_sel_hi:[1,0]
	v_pk_mul_f32 v[96:97], v[94:95], v[110:111] op_sel_hi:[1,0]
	v_cvt_pk_bf16_f32 v94, v102, v103
	v_cvt_pk_bf16_f32 v95, v104, v105
	v_cvt_pk_bf16_f32 v96, v96, v97
	v_cvt_pk_bf16_f32 v97, v106, v107
	global_store_dwordx4 v[112:113], v[94:97], off offset:256 sc1
	s_nop 1
	v_mad_u64_u32 v[96:97], s[44:45], v148, s1, 0
	v_mov_b32_e32 v102, v97
	v_mad_u64_u32 v[102:103], s[44:45], v149, s1, v[102:103]
	v_mul_f32_e32 v94, v145, v158
	v_mov_b32_e32 v97, v102
	v_lshl_add_u64 v[96:97], v[96:97], 1, s[16:17]
	v_pk_mul_f32 v[100:101], v[100:101], v[94:95] op_sel_hi:[1,0]
	v_pk_mul_f32 v[98:99], v[98:99], v[94:95] op_sel_hi:[1,0]
	v_pk_mul_f32 v[102:103], v[92:93], v[94:95] op_sel_hi:[1,0]
	v_pk_mul_f32 v[92:93], v[90:91], v[94:95] op_sel_hi:[1,0]
	v_lshl_add_u64 v[96:97], v[96:97], 0, v[142:143]
	v_cvt_pk_bf16_f32 v90, v98, v99
	v_cvt_pk_bf16_f32 v91, v100, v101
	v_cvt_pk_bf16_f32 v92, v92, v93
	v_cvt_pk_bf16_f32 v93, v102, v103
	global_store_dwordx4 v[96:97], v[90:93], off sc1
	v_pk_mul_f32 v[88:89], v[88:89], v[94:95] op_sel_hi:[1,0]
	v_pk_mul_f32 v[86:87], v[86:87], v[94:95] op_sel_hi:[1,0]
	v_pk_mul_f32 v[90:91], v[80:81], v[94:95] op_sel_hi:[1,0]
	v_pk_mul_f32 v[80:81], v[78:79], v[94:95] op_sel_hi:[1,0]
	v_cvt_pk_bf16_f32 v78, v86, v87
	v_cvt_pk_bf16_f32 v79, v88, v89
	v_cvt_pk_bf16_f32 v80, v80, v81
	v_cvt_pk_bf16_f32 v81, v90, v91
	global_store_dwordx4 v[96:97], v[78:81], off offset:256 sc1
	s_nop 1
	v_mad_u64_u32 v[80:81], s[44:45], v146, s1, 0
	v_mov_b32_e32 v86, v81
	v_mad_u64_u32 v[86:87], s[44:45], v147, s1, v[86:87]
	v_mul_f32_e32 v78, v145, v157
	v_mov_b32_e32 v81, v86
	v_lshl_add_u64 v[80:81], v[80:81], 1, s[16:17]
	v_pk_mul_f32 v[84:85], v[84:85], v[78:79] op_sel_hi:[1,0]
	v_pk_mul_f32 v[82:83], v[82:83], v[78:79] op_sel_hi:[1,0]
	v_pk_mul_f32 v[86:87], v[76:77], v[78:79] op_sel_hi:[1,0]
	v_pk_mul_f32 v[76:77], v[74:75], v[78:79] op_sel_hi:[1,0]
	v_lshl_add_u64 v[80:81], v[80:81], 0, v[142:143]
	v_cvt_pk_bf16_f32 v74, v82, v83
	v_cvt_pk_bf16_f32 v75, v84, v85
	v_cvt_pk_bf16_f32 v76, v76, v77
	v_cvt_pk_bf16_f32 v77, v86, v87
	global_store_dwordx4 v[80:81], v[74:77], off sc1
	v_pk_mul_f32 v[72:73], v[72:73], v[78:79] op_sel_hi:[1,0]
	v_pk_mul_f32 v[70:71], v[70:71], v[78:79] op_sel_hi:[1,0]
	v_pk_mul_f32 v[74:75], v[68:69], v[78:79] op_sel_hi:[1,0]
	v_pk_mul_f32 v[68:69], v[66:67], v[78:79] op_sel_hi:[1,0]
	v_cvt_pk_bf16_f32 v66, v70, v71
	v_cvt_pk_bf16_f32 v67, v72, v73
	v_cvt_pk_bf16_f32 v68, v68, v69
	v_cvt_pk_bf16_f32 v69, v74, v75
	v_add_u32_e32 v72, 0x80, v144
	global_store_dwordx4 v[80:81], v[66:69], off offset:256 sc1
	v_ashrrev_i32_e32 v73, 31, v72
	v_add_u32_e32 v70, 0x90, v144
	v_add_u32_e32 v68, 0xa0, v144
	v_add_u32_e32 v66, 0xb0, v144
	s_cbranch_vccnz .LBB0_481
	v_ashrrev_i32_e32 v71, 31, v70
	v_ashrrev_i32_e32 v69, 31, v68
	v_ashrrev_i32_e32 v67, 31, v66
	v_lshlrev_b64 v[74:75], 6, v[72:73]
	v_lshlrev_b64 v[76:77], 6, v[70:71]
	v_lshlrev_b64 v[82:83], 6, v[68:69]
	v_lshlrev_b64 v[84:85], 6, v[66:67]
	v_lshl_add_u64 v[74:75], v[136:137], 0, v[74:75]
	v_lshl_add_u64 v[78:79], v[136:137], 0, v[76:77]
	v_lshl_add_u64 v[82:83], v[136:137], 0, v[82:83]
	v_lshl_add_u64 v[86:87], v[136:137], 0, v[84:85]
	global_load_dwordx4 v[74:77], v[74:75], off
	s_nop 0
	global_load_dwordx4 v[78:81], v[78:79], off
	s_nop 0
	global_load_dwordx4 v[82:85], v[82:83], off
	s_nop 0
	global_load_dwordx4 v[86:89], v[86:87], off
	s_waitcnt vmcnt(0)
	v_mov_b32_e32 v90, v74
	v_mov_b32_e32 v91, v78
	v_mov_b32_e32 v78, v75
	v_cmp_lt_i32_e32 vcc, v218, v213
	v_pk_add_f32 v[74:75], v[90:91], v[78:79]
	v_mov_b32_e32 v78, v76
	v_mov_b32_e32 v79, v80
	v_mov_b32_e32 v80, v77
	v_cndmask_b32_e32 v73, v211, v218, vcc
	v_pk_add_f32 v[76:77], v[78:79], v[80:81]
	v_lshlrev_b32_e32 v92, 2, v73
	v_pk_add_f32 v[74:75], v[74:75], v[76:77]
	ds_bpermute_b32 v76, v92, v74
	ds_bpermute_b32 v77, v92, v75
	v_cmp_lt_i32_e32 vcc, v219, v213
	s_mov_b32 s44, 0x358637bd
	s_mov_b32 s62, 0x3a800000
	v_cndmask_b32_e32 v73, v211, v219, vcc
	v_lshlrev_b32_e32 v93, 2, v73
	s_waitcnt lgkmcnt(0)
	v_pk_add_f32 v[74:75], v[74:75], v[76:77]
	ds_bpermute_b32 v76, v93, v74
	ds_bpermute_b32 v77, v93, v75
	s_mov_b32 s60, 0x45800000
	v_add_f32_e32 v80, v84, v85
	s_waitcnt lgkmcnt(0)
	v_pk_add_f32 v[74:75], v[74:75], v[76:77]
	v_mov_b64_e32 v[76:77], s[44:45]
	v_pk_fma_f32 v[74:75], v[74:75], s[62:63], v[76:77] op_sel_hi:[1,0,0]
	s_nop 0
	v_mul_f32_e32 v73, 0x4b800000, v74
	v_cmp_gt_f32_e64 s[44:45], s53, v74
	v_cmp_gt_f32_e32 vcc, s53, v75
	s_nop 0
	v_cndmask_b32_e64 v73, v74, v73, s[44:45]
	v_rsq_f32_e32 v74, v73
	v_mul_f32_e32 v73, 0x4b800000, v75
	v_cndmask_b32_e32 v73, v75, v73, vcc
	v_rsq_f32_e32 v75, v73
	s_nop 0
	v_pk_mul_f32 v[78:79], v[74:75], s[60:61] op_sel_hi:[1,0]
	s_nop 0
	v_cndmask_b32_e64 v74, v74, v78, s[44:45]
	v_add_f32_e32 v78, v82, v83
	v_mov_b32_e32 v82, v87
	v_mov_b32_e32 v83, v88
	v_mov_b32_e32 v87, v89
	v_pk_add_f32 v[82:83], v[82:83], v[86:87]
	v_cndmask_b32_e32 v73, v75, v79, vcc
	v_mov_b32_e32 v79, v82
	v_mov_b32_e32 v81, v83
	v_pk_add_f32 v[78:79], v[78:79], v[80:81]
	ds_bpermute_b32 v80, v92, v78
	ds_bpermute_b32 v81, v92, v79
	s_waitcnt lgkmcnt(0)
	v_pk_add_f32 v[78:79], v[78:79], v[80:81]
	ds_bpermute_b32 v80, v93, v78
	ds_bpermute_b32 v81, v93, v79
	s_waitcnt lgkmcnt(0)
	v_pk_add_f32 v[78:79], v[78:79], v[80:81]
	s_nop 0
	v_pk_fma_f32 v[76:77], v[78:79], s[62:63], v[76:77] op_sel_hi:[1,0,0]
	s_nop 0
	v_mul_f32_e32 v75, 0x4b800000, v76
	v_cmp_gt_f32_e64 s[44:45], s53, v76
	v_cmp_gt_f32_e32 vcc, s53, v77
	s_nop 0
	v_cndmask_b32_e64 v75, v76, v75, s[44:45]
	v_rsq_f32_e32 v76, v75
	v_mul_f32_e32 v75, 0x4b800000, v77
	v_cndmask_b32_e32 v75, v77, v75, vcc
	v_rsq_f32_e32 v77, v75
	s_nop 0
	v_pk_mul_f32 v[78:79], v[76:77], s[60:61] op_sel_hi:[1,0]
	s_nop 0
	v_cndmask_b32_e64 v76, v76, v78, s[44:45]
	v_cndmask_b32_e32 v75, v77, v79, vcc
	s_cbranch_execnz .LBB0_477

.LBB0_477:
	v_mul_f32_e32 v74, v145, v74
	v_mad_i64_i32 v[78:79], s[44:45], v72, s1, 0
	v_lshl_add_u64 v[78:79], v[78:79], 1, s[16:17]
	v_pk_mul_f32 v[64:65], v[64:65], v[74:75] op_sel_hi:[1,0]
	v_pk_mul_f32 v[62:63], v[62:63], v[74:75] op_sel_hi:[1,0]
	v_pk_mul_f32 v[80:81], v[60:61], v[74:75] op_sel_hi:[1,0]
	v_pk_mul_f32 v[60:61], v[58:59], v[74:75] op_sel_hi:[1,0]
	v_lshl_add_u64 v[78:79], v[78:79], 0, v[142:143]
	v_cvt_pk_bf16_f32 v58, v62, v63
	v_cvt_pk_bf16_f32 v59, v64, v65
	v_cvt_pk_bf16_f32 v60, v60, v61
	v_cvt_pk_bf16_f32 v61, v80, v81
	global_store_dwordx4 v[78:79], v[58:61], off sc1
	v_pk_mul_f32 v[56:57], v[56:57], v[74:75] op_sel_hi:[1,0]
	v_pk_mul_f32 v[54:55], v[54:55], v[74:75] op_sel_hi:[1,0]
	v_pk_mul_f32 v[58:59], v[48:49], v[74:75] op_sel_hi:[1,0]
	v_pk_mul_f32 v[48:49], v[46:47], v[74:75] op_sel_hi:[1,0]
	v_cvt_pk_bf16_f32 v46, v54, v55
	v_cvt_pk_bf16_f32 v47, v56, v57
	v_cvt_pk_bf16_f32 v48, v48, v49
	v_cvt_pk_bf16_f32 v49, v58, v59
	global_store_dwordx4 v[78:79], v[46:49], off offset:256 sc1
	s_andn2_b64 vcc, exec, s[42:43]
	s_mov_b64 s[42:43], -1
	v_mad_u64_u32 v[48:49], s[44:45], v70, s1, 0
	v_mov_b32_e32 v54, v49
	v_mad_u64_u32 v[54:55], s[44:45], v71, s1, v[54:55]
	v_mul_f32_e32 v46, v145, v73
	v_mov_b32_e32 v49, v54
	v_lshl_add_u64 v[48:49], v[48:49], 1, s[16:17]
	v_pk_mul_f32 v[52:53], v[52:53], v[46:47] op_sel_hi:[1,0]
	v_pk_mul_f32 v[50:51], v[50:51], v[46:47] op_sel_hi:[1,0]
	v_pk_mul_f32 v[54:55], v[44:45], v[46:47] op_sel_hi:[1,0]
	v_pk_mul_f32 v[44:45], v[42:43], v[46:47] op_sel_hi:[1,0]
	v_lshl_add_u64 v[48:49], v[48:49], 0, v[142:143]
	v_cvt_pk_bf16_f32 v42, v50, v51
	v_cvt_pk_bf16_f32 v43, v52, v53
	v_cvt_pk_bf16_f32 v44, v44, v45
	v_cvt_pk_bf16_f32 v45, v54, v55
	global_store_dwordx4 v[48:49], v[42:45], off sc1
	v_pk_mul_f32 v[40:41], v[40:41], v[46:47] op_sel_hi:[1,0]
	v_pk_mul_f32 v[38:39], v[38:39], v[46:47] op_sel_hi:[1,0]
	v_pk_mul_f32 v[42:43], v[32:33], v[46:47] op_sel_hi:[1,0]
	v_pk_mul_f32 v[32:33], v[30:31], v[46:47] op_sel_hi:[1,0]
	v_cvt_pk_bf16_f32 v30, v38, v39
	v_cvt_pk_bf16_f32 v31, v40, v41
	v_cvt_pk_bf16_f32 v32, v32, v33
	v_cvt_pk_bf16_f32 v33, v42, v43
	global_store_dwordx4 v[48:49], v[30:33], off offset:256 sc1
	s_nop 1
	v_mad_u64_u32 v[32:33], s[44:45], v68, s1, 0
	v_mov_b32_e32 v38, v33
	v_mad_u64_u32 v[38:39], s[44:45], v69, s1, v[38:39]
	v_mul_f32_e32 v30, v145, v76
	v_mov_b32_e32 v33, v38
	v_lshl_add_u64 v[32:33], v[32:33], 1, s[16:17]
	v_pk_mul_f32 v[36:37], v[36:37], v[30:31] op_sel_hi:[1,0]
	v_pk_mul_f32 v[34:35], v[34:35], v[30:31] op_sel_hi:[1,0]
	v_pk_mul_f32 v[38:39], v[28:29], v[30:31] op_sel_hi:[1,0]
	v_pk_mul_f32 v[28:29], v[26:27], v[30:31] op_sel_hi:[1,0]
	v_lshl_add_u64 v[32:33], v[32:33], 0, v[142:143]
	v_cvt_pk_bf16_f32 v26, v34, v35
	v_cvt_pk_bf16_f32 v27, v36, v37
	v_cvt_pk_bf16_f32 v28, v28, v29
	v_cvt_pk_bf16_f32 v29, v38, v39
	global_store_dwordx4 v[32:33], v[26:29], off sc1
	v_pk_mul_f32 v[24:25], v[24:25], v[30:31] op_sel_hi:[1,0]
	v_pk_mul_f32 v[22:23], v[22:23], v[30:31] op_sel_hi:[1,0]
	v_pk_mul_f32 v[26:27], v[16:17], v[30:31] op_sel_hi:[1,0]
	v_pk_mul_f32 v[16:17], v[14:15], v[30:31] op_sel_hi:[1,0]
	v_cvt_pk_bf16_f32 v14, v22, v23
	v_cvt_pk_bf16_f32 v15, v24, v25
	v_cvt_pk_bf16_f32 v16, v16, v17
	v_cvt_pk_bf16_f32 v17, v26, v27
	global_store_dwordx4 v[32:33], v[14:17], off offset:256 sc1
	s_nop 1
	v_mad_u64_u32 v[16:17], s[44:45], v66, s1, 0
	v_mov_b32_e32 v22, v17
	v_mad_u64_u32 v[22:23], s[44:45], v67, s1, v[22:23]
	v_mul_f32_e32 v14, v145, v75
	v_mov_b32_e32 v17, v22
	v_lshl_add_u64 v[16:17], v[16:17], 1, s[16:17]
	v_pk_mul_f32 v[20:21], v[20:21], v[14:15] op_sel_hi:[1,0]
	v_pk_mul_f32 v[18:19], v[18:19], v[14:15] op_sel_hi:[1,0]
	v_pk_mul_f32 v[22:23], v[12:13], v[14:15] op_sel_hi:[1,0]
	v_pk_mul_f32 v[12:13], v[10:11], v[14:15] op_sel_hi:[1,0]
	v_lshl_add_u64 v[16:17], v[16:17], 0, v[142:143]
	v_cvt_pk_bf16_f32 v10, v18, v19
	v_cvt_pk_bf16_f32 v11, v20, v21
	v_cvt_pk_bf16_f32 v12, v12, v13
	v_cvt_pk_bf16_f32 v13, v22, v23
	global_store_dwordx4 v[16:17], v[10:13], off sc1
	v_pk_mul_f32 v[8:9], v[8:9], v[14:15] op_sel_hi:[1,0]
	v_pk_mul_f32 v[6:7], v[6:7], v[14:15] op_sel_hi:[1,0]
	v_pk_mul_f32 v[10:11], v[4:5], v[14:15] op_sel_hi:[1,0]
	v_pk_mul_f32 v[4:5], v[2:3], v[14:15] op_sel_hi:[1,0]
	v_cvt_pk_bf16_f32 v2, v6, v7
	v_cvt_pk_bf16_f32 v3, v8, v9
	v_cvt_pk_bf16_f32 v4, v4, v5
	v_cvt_pk_bf16_f32 v5, v10, v11
	global_store_dwordx4 v[16:17], v[2:5], off offset:256 sc1
	s_cbranch_vccnz .LBB0_464
	s_andn2_b64 vcc, exec, s[30:31]
	s_cbranch_vccnz .LBB0_463
	s_barrier
	s_branch .LBB0_463

.LBB0_546:
	s_or_b64 exec, exec, s[16:17]
	v_readlane_b32 s10, v255, 34
	v_readlane_b32 s11, v255, 35
	s_load_dwordx2 s[10:11], s[10:11], 0xf0
	s_waitcnt lgkmcnt(0)
	s_barrier
	ds_read_b128 v[134:137], v0 offset:4096
	s_waitcnt lgkmcnt(0)
	s_add_u32 s16, s10, 0x8000000
	s_addc_u32 s17, s11, 0
	s_lshl_b32 s4, s4, 5
	s_lshl_b32 s1, s1, 8
	v_mov_b32_e32 v138, v135
	v_mov_b32_e32 v139, v136
	v_mov_b32_e32 v135, v137
	v_pk_add_f32 v[134:135], v[138:139], v[134:135]
	s_or_b32 s1, s1, s4
	v_add_f32_e32 v0, v134, v135
	v_rcp_f32_e32 v0, v0
	v_lshl_or_b32 v20, v195, 3, s1
	v_ashrrev_i32_e32 v21, 31, v20
	v_lshlrev_b64 v[130:131], 11, v[130:131]
	v_lshl_add_u64 v[130:131], s[16:17], 0, v[130:131]
	v_lshlrev_b64 v[20:21], 1, v[20:21]
	v_lshl_add_u64 v[134:135], v[130:131], 0, v[20:21]
	v_pk_mul_f32 v[136:137], v[156:157], v[0:1] op_sel_hi:[1,0]
	v_pk_mul_f32 v[130:131], v[132:133], v[0:1] op_sel_hi:[1,0]
	v_pk_mul_f32 v[138:139], v[172:173], v[0:1] op_sel_hi:[1,0]
	v_pk_mul_f32 v[132:133], v[160:161], v[0:1] op_sel_hi:[1,0]
	v_cvt_pk_bf16_f32 v130, v130, v131
	v_cvt_pk_bf16_f32 v131, v136, v137
	v_cvt_pk_bf16_f32 v132, v132, v133
	v_cvt_pk_bf16_f32 v133, v138, v139
	global_store_dwordx4 v[134:135], v[130:133], off sc1
	v_pk_mul_f32 v[136:137], v[202:203], v[0:1] op_sel_hi:[1,0]
	v_pk_mul_f32 v[138:139], v[196:197], v[0:1] op_sel_hi:[1,0]
	v_pk_mul_f32 v[132:133], v[180:181], v[0:1] op_sel_hi:[1,0]
	v_pk_mul_f32 v[130:131], v[174:175], v[0:1] op_sel_hi:[1,0]
	v_lshl_add_u32 v0, v235, 4, 0
	v_cvt_pk_bf16_f32 v130, v130, v131
	v_cvt_pk_bf16_f32 v131, v132, v133
	v_cvt_pk_bf16_f32 v132, v138, v139
	v_cvt_pk_bf16_f32 v133, v136, v137
	global_store_dwordx4 v[134:135], v[130:133], off offset:256 sc1
	ds_read_b128 v[130:133], v0 offset:4096
	v_lshlrev_b64 v[114:115], 11, v[114:115]
	v_lshl_add_u64 v[114:115], s[16:17], 0, v[114:115]
	v_lshl_add_u64 v[114:115], v[114:115], 0, v[20:21]
	v_lshlrev_b64 v[82:83], 11, v[82:83]
	s_waitcnt lgkmcnt(0)
	v_mov_b32_e32 v134, v131
	v_mov_b32_e32 v135, v132
	v_mov_b32_e32 v131, v133
	v_pk_add_f32 v[130:131], v[134:135], v[130:131]
	v_lshl_add_u64 v[82:83], s[16:17], 0, v[82:83]
	v_add_f32_e32 v0, v130, v131
	v_rcp_f32_e32 v0, v0
	v_lshl_add_u64 v[82:83], v[82:83], 0, v[20:21]
	v_lshlrev_b64 v[50:51], 11, v[50:51]
	v_lshl_add_u64 v[50:51], s[16:17], 0, v[50:51]
	v_pk_mul_f32 v[102:103], v[102:103], v[0:1] op_sel_hi:[1,0]
	v_pk_mul_f32 v[94:95], v[94:95], v[0:1] op_sel_hi:[1,0]
	v_pk_mul_f32 v[108:109], v[108:109], v[0:1] op_sel_hi:[1,0]
	v_pk_mul_f32 v[130:131], v[100:101], v[0:1] op_sel_hi:[1,0]
	v_cvt_pk_bf16_f32 v100, v94, v95
	v_cvt_pk_bf16_f32 v101, v102, v103
	v_cvt_pk_bf16_f32 v102, v130, v131
	v_cvt_pk_bf16_f32 v103, v108, v109
	global_store_dwordx4 v[114:115], v[100:103], off sc1
	v_pk_mul_f32 v[94:95], v[96:97], v[0:1] op_sel_hi:[1,0]
	v_pk_mul_f32 v[96:97], v[104:105], v[0:1] op_sel_hi:[1,0]
	v_pk_mul_f32 v[100:101], v[106:107], v[0:1] op_sel_hi:[1,0]
	v_pk_mul_f32 v[102:103], v[110:111], v[0:1] op_sel_hi:[1,0]
	v_cvt_pk_bf16_f32 v94, v94, v95
	v_cvt_pk_bf16_f32 v95, v100, v101
	v_cvt_pk_bf16_f32 v96, v96, v97
	v_cvt_pk_bf16_f32 v97, v102, v103
	v_lshl_add_u32 v0, v234, 4, 0
	global_store_dwordx4 v[114:115], v[94:97], off offset:256 sc1
	ds_read_b128 v[94:97], v0 offset:4096
	v_lshl_add_u64 v[50:51], v[50:51], 0, v[20:21]
	v_lshlrev_b64 v[18:19], 11, v[18:19]
	v_lshl_add_u64 v[18:19], s[16:17], 0, v[18:19]
	v_lshl_add_u64 v[18:19], v[18:19], 0, v[20:21]
	s_waitcnt lgkmcnt(0)
	v_mov_b32_e32 v100, v95
	v_mov_b32_e32 v101, v96
	v_mov_b32_e32 v95, v97
	v_pk_add_f32 v[94:95], v[100:101], v[94:95]
	s_nop 0
	v_add_f32_e32 v0, v94, v95
	v_rcp_f32_e32 v0, v0
	v_lshlrev_b64 v[94:95], 11, v[98:99]
	v_lshl_add_u64 v[94:95], s[16:17], 0, v[94:95]
	v_lshl_add_u64 v[98:99], v[94:95], 0, v[20:21]
	v_pk_mul_f32 v[96:97], v[116:117], v[0:1] op_sel_hi:[1,0]
	v_pk_mul_f32 v[94:95], v[112:113], v[0:1] op_sel_hi:[1,0]
	v_pk_mul_f32 v[100:101], v[120:121], v[0:1] op_sel_hi:[1,0]
	v_pk_mul_f32 v[102:103], v[118:119], v[0:1] op_sel_hi:[1,0]
	v_cvt_pk_bf16_f32 v94, v94, v95
	v_cvt_pk_bf16_f32 v95, v96, v97
	v_cvt_pk_bf16_f32 v96, v102, v103
	v_cvt_pk_bf16_f32 v97, v100, v101
	global_store_dwordx4 v[98:99], v[94:97], off sc1
	v_pk_mul_f32 v[100:101], v[128:129], v[0:1] op_sel_hi:[1,0]
	v_pk_mul_f32 v[102:103], v[126:127], v[0:1] op_sel_hi:[1,0]
	v_pk_mul_f32 v[96:97], v[124:125], v[0:1] op_sel_hi:[1,0]
	v_pk_mul_f32 v[94:95], v[122:123], v[0:1] op_sel_hi:[1,0]
	v_lshl_add_u32 v0, v233, 4, 0
	v_cvt_pk_bf16_f32 v94, v94, v95
	v_cvt_pk_bf16_f32 v95, v96, v97
	v_cvt_pk_bf16_f32 v96, v102, v103
	v_cvt_pk_bf16_f32 v97, v100, v101
	global_store_dwordx4 v[98:99], v[94:97], off offset:256 sc1
	ds_read_b128 v[94:97], v0 offset:4096
	s_waitcnt lgkmcnt(0)
	v_mov_b32_e32 v98, v95
	v_mov_b32_e32 v99, v96
	v_mov_b32_e32 v95, v97
	v_pk_add_f32 v[94:95], v[98:99], v[94:95]
	s_nop 0
	v_add_f32_e32 v0, v94, v95
	v_rcp_f32_e32 v0, v0
	s_nop 0
	v_pk_mul_f32 v[64:65], v[64:65], v[0:1] op_sel_hi:[1,0]
	v_pk_mul_f32 v[58:59], v[58:59], v[0:1] op_sel_hi:[1,0]
	v_pk_mul_f32 v[72:73], v[72:73], v[0:1] op_sel_hi:[1,0]
	v_pk_mul_f32 v[94:95], v[62:63], v[0:1] op_sel_hi:[1,0]
	v_cvt_pk_bf16_f32 v62, v58, v59
	v_cvt_pk_bf16_f32 v63, v64, v65
	v_cvt_pk_bf16_f32 v64, v94, v95
	v_cvt_pk_bf16_f32 v65, v72, v73
	global_store_dwordx4 v[82:83], v[62:65], off sc1
	v_pk_mul_f32 v[58:59], v[60:61], v[0:1] op_sel_hi:[1,0]
	v_pk_mul_f32 v[60:61], v[68:69], v[0:1] op_sel_hi:[1,0]
	v_pk_mul_f32 v[62:63], v[70:71], v[0:1] op_sel_hi:[1,0]
	v_pk_mul_f32 v[64:65], v[74:75], v[0:1] op_sel_hi:[1,0]
	v_cvt_pk_bf16_f32 v58, v58, v59
	v_cvt_pk_bf16_f32 v59, v62, v63
	v_cvt_pk_bf16_f32 v60, v60, v61
	v_cvt_pk_bf16_f32 v61, v64, v65
	v_lshl_add_u32 v0, v232, 4, 0
	global_store_dwordx4 v[82:83], v[58:61], off offset:256 sc1
	ds_read_b128 v[58:61], v0 offset:4096
	s_waitcnt lgkmcnt(0)
	v_mov_b32_e32 v62, v59
	v_mov_b32_e32 v63, v60
	v_mov_b32_e32 v59, v61
	v_pk_add_f32 v[58:59], v[62:63], v[58:59]
	s_nop 0
	v_add_f32_e32 v0, v58, v59
	v_rcp_f32_e32 v0, v0
	v_lshlrev_b64 v[58:59], 11, v[66:67]
	v_lshl_add_u64 v[58:59], s[16:17], 0, v[58:59]
	v_lshl_add_u64 v[62:63], v[58:59], 0, v[20:21]
	v_pk_mul_f32 v[60:61], v[78:79], v[0:1] op_sel_hi:[1,0]
	v_pk_mul_f32 v[58:59], v[76:77], v[0:1] op_sel_hi:[1,0]
	v_pk_mul_f32 v[64:65], v[84:85], v[0:1] op_sel_hi:[1,0]
	v_pk_mul_f32 v[66:67], v[80:81], v[0:1] op_sel_hi:[1,0]
	v_cvt_pk_bf16_f32 v58, v58, v59
	v_cvt_pk_bf16_f32 v59, v60, v61
	v_cvt_pk_bf16_f32 v60, v66, v67
	v_cvt_pk_bf16_f32 v61, v64, v65
	global_store_dwordx4 v[62:63], v[58:61], off sc1
	v_pk_mul_f32 v[64:65], v[92:93], v[0:1] op_sel_hi:[1,0]
	v_pk_mul_f32 v[66:67], v[90:91], v[0:1] op_sel_hi:[1,0]
	v_pk_mul_f32 v[60:61], v[88:89], v[0:1] op_sel_hi:[1,0]
	v_pk_mul_f32 v[58:59], v[86:87], v[0:1] op_sel_hi:[1,0]
	v_lshl_add_u32 v0, v231, 4, 0
	v_cvt_pk_bf16_f32 v58, v58, v59
	v_cvt_pk_bf16_f32 v59, v60, v61
	v_cvt_pk_bf16_f32 v60, v66, v67
	v_cvt_pk_bf16_f32 v61, v64, v65
	global_store_dwordx4 v[62:63], v[58:61], off offset:256 sc1
	ds_read_b128 v[58:61], v0 offset:4096
	s_waitcnt lgkmcnt(0)
	v_mov_b32_e32 v62, v59
	v_mov_b32_e32 v63, v60
	v_mov_b32_e32 v59, v61
	v_pk_add_f32 v[58:59], v[62:63], v[58:59]
	s_nop 0
	v_add_f32_e32 v0, v58, v59
	v_rcp_f32_e32 v0, v0
	s_nop 0
	v_pk_mul_f32 v[28:29], v[28:29], v[0:1] op_sel_hi:[1,0]
	v_pk_mul_f32 v[22:23], v[22:23], v[0:1] op_sel_hi:[1,0]
	v_pk_mul_f32 v[36:37], v[36:37], v[0:1] op_sel_hi:[1,0]
	v_pk_mul_f32 v[58:59], v[26:27], v[0:1] op_sel_hi:[1,0]
	v_cvt_pk_bf16_f32 v26, v22, v23
	v_cvt_pk_bf16_f32 v27, v28, v29
	v_cvt_pk_bf16_f32 v28, v58, v59
	v_cvt_pk_bf16_f32 v29, v36, v37
	global_store_dwordx4 v[50:51], v[26:29], off sc1
	v_pk_mul_f32 v[22:23], v[24:25], v[0:1] op_sel_hi:[1,0]
	v_pk_mul_f32 v[24:25], v[30:31], v[0:1] op_sel_hi:[1,0]
	v_pk_mul_f32 v[26:27], v[32:33], v[0:1] op_sel_hi:[1,0]
	v_pk_mul_f32 v[28:29], v[38:39], v[0:1] op_sel_hi:[1,0]
	v_cvt_pk_bf16_f32 v22, v22, v23
	v_cvt_pk_bf16_f32 v23, v26, v27
	v_cvt_pk_bf16_f32 v24, v24, v25
	v_cvt_pk_bf16_f32 v25, v28, v29
	v_lshl_add_u32 v0, v230, 4, 0
	global_store_dwordx4 v[50:51], v[22:25], off offset:256 sc1
	ds_read_b128 v[22:25], v0 offset:4096
	s_waitcnt lgkmcnt(0)
	v_mov_b32_e32 v26, v23
	v_mov_b32_e32 v27, v24
	v_mov_b32_e32 v23, v25
	v_pk_add_f32 v[22:23], v[26:27], v[22:23]
	s_nop 0
	v_add_f32_e32 v0, v22, v23
	v_rcp_f32_e32 v0, v0
	v_lshlrev_b64 v[22:23], 11, v[34:35]
	v_lshl_add_u64 v[22:23], s[16:17], 0, v[22:23]
	v_lshl_add_u64 v[26:27], v[22:23], 0, v[20:21]
	v_pk_mul_f32 v[24:25], v[42:43], v[0:1] op_sel_hi:[1,0]
	v_pk_mul_f32 v[22:23], v[40:41], v[0:1] op_sel_hi:[1,0]
	v_pk_mul_f32 v[28:29], v[46:47], v[0:1] op_sel_hi:[1,0]
	v_pk_mul_f32 v[30:31], v[44:45], v[0:1] op_sel_hi:[1,0]
	v_cvt_pk_bf16_f32 v22, v22, v23
	v_cvt_pk_bf16_f32 v23, v24, v25
	v_cvt_pk_bf16_f32 v24, v30, v31
	v_cvt_pk_bf16_f32 v25, v28, v29
	global_store_dwordx4 v[26:27], v[22:25], off sc1
	v_pk_mul_f32 v[28:29], v[56:57], v[0:1] op_sel_hi:[1,0]
	v_pk_mul_f32 v[30:31], v[54:55], v[0:1] op_sel_hi:[1,0]
	v_pk_mul_f32 v[24:25], v[52:53], v[0:1] op_sel_hi:[1,0]
	v_pk_mul_f32 v[22:23], v[48:49], v[0:1] op_sel_hi:[1,0]
	v_lshl_add_u32 v0, v229, 4, 0
	v_cvt_pk_bf16_f32 v22, v22, v23
	v_cvt_pk_bf16_f32 v23, v24, v25
	v_cvt_pk_bf16_f32 v24, v30, v31
	v_cvt_pk_bf16_f32 v25, v28, v29
	global_store_dwordx4 v[26:27], v[22:25], off offset:256 sc1
	ds_read_b128 v[22:25], v0 offset:4096
	s_waitcnt lgkmcnt(0)
	v_mov_b32_e32 v26, v23
	v_mov_b32_e32 v27, v24
	v_mov_b32_e32 v23, v25
	v_pk_add_f32 v[22:23], v[26:27], v[22:23]
	s_nop 0
	v_add_f32_e32 v0, v22, v23
	v_rcp_f32_e32 v0, v0
	s_nop 0
	v_pk_mul_f32 v[8:9], v[8:9], v[0:1] op_sel_hi:[1,0]
	v_pk_mul_f32 v[2:3], v[2:3], v[0:1] op_sel_hi:[1,0]
	v_pk_mul_f32 v[14:15], v[14:15], v[0:1] op_sel_hi:[1,0]
	v_pk_mul_f32 v[20:21], v[6:7], v[0:1] op_sel_hi:[1,0]
	v_cvt_pk_bf16_f32 v6, v2, v3
	v_cvt_pk_bf16_f32 v7, v8, v9
	v_cvt_pk_bf16_f32 v8, v20, v21
	v_cvt_pk_bf16_f32 v9, v14, v15
	global_store_dwordx4 v[18:19], v[6:9], off sc1
	v_pk_mul_f32 v[2:3], v[4:5], v[0:1] op_sel_hi:[1,0]
	v_pk_mul_f32 v[4:5], v[10:11], v[0:1] op_sel_hi:[1,0]
	v_pk_mul_f32 v[6:7], v[12:13], v[0:1] op_sel_hi:[1,0]
	v_pk_mul_f32 v[8:9], v[16:17], v[0:1] op_sel_hi:[1,0]
	v_cvt_pk_bf16_f32 v2, v2, v3
	v_cvt_pk_bf16_f32 v3, v6, v7
	v_cvt_pk_bf16_f32 v4, v4, v5
	v_cvt_pk_bf16_f32 v5, v8, v9
	global_store_dwordx4 v[18:19], v[2:5], off offset:256 sc1

.LBB0_553:
	v_readlane_b32 s22, v255, 34
	v_readlane_b32 s23, v255, 35
	s_load_dwordx2 s[22:23], s[22:23], 0xf0
	s_mul_i32 s36, s36, s26
	v_or_b32_e32 v50, s42, v12
	s_waitcnt lgkmcnt(0)
	s_add_u32 s22, s22, s28
	s_addc_u32 s23, s23, s29
	s_sub_i32 s10, s10, s36
	s_lshl_b32 s28, s10, 5
	s_ashr_i32 s29, s28, 31
	s_lshl_b64 s[30:31], s[28:29], 2
	s_add_u32 s16, s16, s30
	s_addc_u32 s17, s17, s31
	v_lshl_add_u64 v[2:3], s[16:17], 0, v[0:1]
	v_mad_i64_i32 v[4:5], s[16:17], v50, s11, 0
	v_lshl_add_u64 v[4:5], v[4:5], 2, v[2:3]
	global_load_dwordx4 v[26:29], v[4:5], off
	v_or_b32_e32 v4, 8, v50
	v_mad_i64_i32 v[4:5], s[16:17], v4, s11, 0
	v_lshl_add_u64 v[4:5], v[4:5], 2, v[2:3]
	global_load_dwordx4 v[30:33], v[4:5], off
	v_or_b32_e32 v4, 16, v50
	v_mad_i64_i32 v[4:5], s[16:17], v4, s11, 0
	v_lshl_add_u64 v[4:5], v[4:5], 2, v[2:3]
	global_load_dwordx4 v[34:37], v[4:5], off
	v_or_b32_e32 v4, 24, v50
	v_mad_i64_i32 v[4:5], s[16:17], v4, s11, 0
	v_lshl_add_u64 v[4:5], v[4:5], 2, v[2:3]
	global_load_dwordx4 v[38:41], v[4:5], off
	v_or_b32_e32 v4, 32, v50
	v_mad_i64_i32 v[4:5], s[16:17], v4, s11, 0
	v_lshl_add_u64 v[4:5], v[4:5], 2, v[2:3]
	global_load_dwordx4 v[42:45], v[4:5], off
	v_or_b32_e32 v4, 40, v50
	v_mad_i64_i32 v[4:5], s[16:17], v4, s11, 0
	v_lshl_add_u64 v[4:5], v[4:5], 2, v[2:3]
	global_load_dwordx4 v[46:49], v[4:5], off
	v_or_b32_e32 v4, 48, v50
	v_mad_i64_i32 v[4:5], s[16:17], v4, s11, 0
	v_lshl_add_u64 v[4:5], v[4:5], 2, v[2:3]
	global_load_dwordx4 v[6:9], v[4:5], off
	v_or_b32_e32 v4, 56, v50
	v_mad_i64_i32 v[4:5], s[10:11], v4, s11, 0
	v_lshl_add_u64 v[2:3], v[4:5], 2, v[2:3]
	global_load_dwordx4 v[2:5], v[2:3], off
	s_waitcnt vmcnt(8)
	ds_bpermute_b32 v50, v13, v11
	s_ashr_i32 s43, s42, 31
	s_lshl_b64 s[10:11], s[42:43], 1
	s_add_u32 s10, s22, s10
	s_addc_u32 s11, s23, s11
	s_addk_i32 s1, 0x200
	s_cmpk_lt_i32 s4, 0x1200
	s_waitcnt vmcnt(7) lgkmcnt(0)
	v_pk_mul_f32 v[26:27], v[26:27], v[50:51] op_sel_hi:[1,0]
	ds_write2_b32 v25, v26, v27 offset1:1
	v_pk_mul_f32 v[26:27], v[28:29], v[50:51] op_sel_hi:[1,0]
	ds_write2_b32 v25, v26, v27 offset0:2 offset1:3
	ds_bpermute_b32 v26, v15, v11
	s_waitcnt vmcnt(6) lgkmcnt(0)
	v_pk_mul_f32 v[28:29], v[30:31], v[26:27] op_sel_hi:[1,0]
	v_add_u32_e32 v27, 0x420, v25
	ds_write2_b32 v27, v28, v29 offset1:1
	v_pk_mul_f32 v[26:27], v[32:33], v[26:27] op_sel_hi:[1,0]
	v_add_u32_e32 v28, 0x428, v25
	ds_write2_b32 v28, v26, v27 offset1:1
	ds_bpermute_b32 v26, v17, v11
	s_waitcnt vmcnt(5) lgkmcnt(0)
	v_pk_mul_f32 v[28:29], v[34:35], v[26:27] op_sel_hi:[1,0]
	v_add_u32_e32 v27, 0x840, v25
	ds_write2_b32 v27, v28, v29 offset1:1
	v_pk_mul_f32 v[26:27], v[36:37], v[26:27] op_sel_hi:[1,0]
	v_add_u32_e32 v28, 0x848, v25
	ds_write2_b32 v28, v26, v27 offset1:1
	ds_bpermute_b32 v26, v19, v11
	s_waitcnt vmcnt(4) lgkmcnt(0)
	v_pk_mul_f32 v[28:29], v[38:39], v[26:27] op_sel_hi:[1,0]
	v_add_u32_e32 v27, 0xc60, v25
	ds_write2_b32 v27, v28, v29 offset1:1
	v_pk_mul_f32 v[26:27], v[40:41], v[26:27] op_sel_hi:[1,0]
	v_add_u32_e32 v28, 0xc68, v25
	ds_write2_b32 v28, v26, v27 offset1:1
	ds_bpermute_b32 v26, v20, v11
	s_waitcnt vmcnt(3) lgkmcnt(0)
	v_pk_mul_f32 v[28:29], v[42:43], v[26:27] op_sel_hi:[1,0]
	v_add_u32_e32 v27, 0x1080, v25
	ds_write2_b32 v27, v28, v29 offset1:1
	v_pk_mul_f32 v[26:27], v[44:45], v[26:27] op_sel_hi:[1,0]
	v_add_u32_e32 v28, 0x1088, v25
	ds_write2_b32 v28, v26, v27 offset1:1
	ds_bpermute_b32 v26, v21, v11
	s_waitcnt vmcnt(2) lgkmcnt(0)
	v_pk_mul_f32 v[28:29], v[46:47], v[26:27] op_sel_hi:[1,0]
	v_add_u32_e32 v27, 0x14a0, v25
	ds_write2_b32 v27, v28, v29 offset1:1
	v_pk_mul_f32 v[26:27], v[48:49], v[26:27] op_sel_hi:[1,0]
	v_add_u32_e32 v28, 0x14a8, v25
	ds_write2_b32 v28, v26, v27 offset1:1
	ds_bpermute_b32 v26, v22, v11
	s_waitcnt vmcnt(1) lgkmcnt(0)
	v_pk_mul_f32 v[6:7], v[6:7], v[26:27] op_sel_hi:[1,0]
	v_add_u32_e32 v27, 0x18c0, v25
	ds_write2_b32 v27, v6, v7 offset1:1
	v_pk_mul_f32 v[6:7], v[8:9], v[26:27] op_sel_hi:[1,0]
	v_add_u32_e32 v8, 0x18c8, v25
	ds_write2_b32 v8, v6, v7 offset1:1
	ds_bpermute_b32 v6, v23, v11
	v_mov_b32_e32 v11, v1
	s_waitcnt vmcnt(0) lgkmcnt(0)
	v_pk_mul_f32 v[2:3], v[2:3], v[6:7] op_sel_hi:[1,0]
	v_add_u32_e32 v7, 0x1ce0, v25
	ds_write2_b32 v7, v2, v3 offset1:1
	v_pk_mul_f32 v[2:3], v[4:5], v[6:7] op_sel_hi:[1,0]
	v_add_u32_e32 v4, 0x1ce8, v25
	ds_write2_b32 v4, v2, v3 offset1:1
	s_waitcnt lgkmcnt(0)
	ds_read2_b32 v[8:9], v24 offset0:33 offset1:41
	ds_read2_b32 v[26:27], v24 offset1:8
	ds_read2_b32 v[28:29], v24 offset0:66 offset1:74
	ds_read2_b32 v[30:31], v24 offset0:99 offset1:107
	ds_read2_b32 v[32:33], v24 offset0:132 offset1:140
	ds_read2_b32 v[34:35], v24 offset0:165 offset1:173
	ds_read2_b32 v[36:37], v24 offset0:198 offset1:206
	ds_read2_b32 v[38:39], v24 offset0:231 offset1:239
	v_lshl_add_u64 v[6:7], s[10:11], 0, v[10:11]
	s_waitcnt lgkmcnt(6)
	v_cvt_pk_bf16_f32 v2, v26, v8
	v_or_b32_e32 v8, s28, v12
	v_mad_i64_i32 v[40:41], s[10:11], v8, s5, 0
	s_waitcnt lgkmcnt(4)
	v_cvt_pk_bf16_f32 v3, v28, v30
	s_waitcnt lgkmcnt(2)
	v_cvt_pk_bf16_f32 v4, v32, v34
	s_waitcnt lgkmcnt(0)
	v_cvt_pk_bf16_f32 v5, v36, v38
	v_lshl_add_u64 v[40:41], v[40:41], 1, v[6:7]
	v_or_b32_e32 v8, s28, v14
	global_store_dwordx4 v[40:41], v[2:5], off sc1
	s_nop 1
	v_cvt_pk_bf16_f32 v2, v27, v9
	v_mad_i64_i32 v[8:9], s[10:11], v8, s5, 0
	v_cvt_pk_bf16_f32 v3, v29, v31
	v_cvt_pk_bf16_f32 v4, v33, v35
	v_cvt_pk_bf16_f32 v5, v37, v39
	v_lshl_add_u64 v[8:9], v[8:9], 1, v[6:7]
	global_store_dwordx4 v[8:9], v[2:5], off sc1
	ds_read2_b32 v[8:9], v24 offset0:16 offset1:24
	ds_read2_b32 v[26:27], v24 offset0:49 offset1:57
	ds_read2_b32 v[28:29], v24 offset0:82 offset1:90
	ds_read2_b32 v[30:31], v24 offset0:115 offset1:123
	ds_read2_b32 v[32:33], v24 offset0:148 offset1:156
	ds_read2_b32 v[34:35], v24 offset0:181 offset1:189
	ds_read2_b32 v[36:37], v24 offset0:214 offset1:222
	ds_read2_b32 v[38:39], v24 offset0:247 offset1:255
	s_waitcnt lgkmcnt(6)
	v_cvt_pk_bf16_f32 v2, v8, v26
	v_or_b32_e32 v8, s28, v16
	v_mad_i64_i32 v[40:41], s[10:11], v8, s5, 0
	s_waitcnt lgkmcnt(4)
	v_cvt_pk_bf16_f32 v3, v28, v30
	s_waitcnt lgkmcnt(2)
	v_cvt_pk_bf16_f32 v4, v32, v34
	s_waitcnt lgkmcnt(0)
	v_cvt_pk_bf16_f32 v5, v36, v38
	v_lshl_add_u64 v[40:41], v[40:41], 1, v[6:7]
	v_or_b32_e32 v8, s28, v18
	global_store_dwordx4 v[40:41], v[2:5], off sc1
	s_nop 1
	v_cvt_pk_bf16_f32 v2, v9, v27
	v_mad_i64_i32 v[8:9], s[10:11], v8, s5, 0
	v_cvt_pk_bf16_f32 v3, v29, v31
	v_cvt_pk_bf16_f32 v4, v33, v35
	v_cvt_pk_bf16_f32 v5, v37, v39
	v_lshl_add_u64 v[6:7], v[8:9], 1, v[6:7]
	global_store_dwordx4 v[6:7], v[2:5], off sc1
	s_waitcnt lgkmcnt(0)
	s_mov_b32 s10, s4
	s_cbranch_scc0 .LBB0_600

.LBB0_621:
	v_lshl_add_u32 v144, s71, 8, v140
	v_lshl_or_b32 v146, s70, 8, v142
	v_ashrrev_i32_e32 v145, 31, v144
	v_ashrrev_i32_e32 v147, 31, v146
	v_or_b32_e32 v148, 16, v144
	v_or_b32_e32 v150, 32, v144
	v_or_b32_e32 v152, 48, v144
	v_lshlrev_b64 v[144:145], 12, v[144:145]
	v_lshl_add_u64 v[144:145], s[42:43], 0, v[144:145]
	v_lshlrev_b64 v[146:147], 1, v[146:147]
	v_lshl_add_u64 v[144:145], v[144:145], 0, v[146:147]
	s_mov_b32 s51, 0x80000
	s_mov_b64 s[58:59], 0x80000
	v_cvt_pk_bf16_f32 v62, v62, v63
	v_cvt_pk_bf16_f32 v63, v64, v65
	v_cvt_pk_bf16_f32 v64, v58, v59
	v_add_co_u32_e32 v58, vcc, s51, v144
	v_cvt_pk_bf16_f32 v70, v70, v71
	v_cvt_pk_bf16_f32 v71, v72, v73
	v_cvt_pk_bf16_f32 v72, v66, v67
	v_lshl_add_u64 v[66:67], v[144:145], 0, s[58:59]
	v_addc_co_u32_e32 v59, vcc, 0, v145, vcc
	v_cvt_pk_bf16_f32 v46, v46, v47
	v_cvt_pk_bf16_f32 v47, v48, v49
	v_cvt_pk_bf16_f32 v48, v42, v43
	v_cvt_pk_bf16_f32 v49, v44, v45
	s_mov_b32 s51, 0x90000
	global_store_dwordx4 v[66:67], v[46:49], off offset:256 sc1
	s_mov_b64 s[58:59], 0x90000
	v_ashrrev_i32_e32 v149, 31, v148
	v_add_co_u32_e32 v48, vcc, s51, v144
	v_lshl_add_u64 v[46:47], v[144:145], 0, s[58:59]
	s_nop 0
	v_addc_co_u32_e32 v49, vcc, 0, v145, vcc
	v_cvt_pk_bf16_f32 v30, v30, v31
	v_cvt_pk_bf16_f32 v31, v32, v33
	v_cvt_pk_bf16_f32 v32, v26, v27
	v_cvt_pk_bf16_f32 v33, v28, v29
	s_mov_b32 s51, 0xa0000
	v_ashrrev_i32_e32 v151, 31, v150
	v_cvt_pk_bf16_f32 v110, v110, v111
	v_cvt_pk_bf16_f32 v111, v112, v113
	v_cvt_pk_bf16_f32 v112, v106, v107
	v_lshlrev_b64 v[106:107], 12, v[148:149]
	global_store_dwordx4 v[46:47], v[30:33], off offset:256 sc1
	s_mov_b64 s[58:59], 0xa0000
	v_ashrrev_i32_e32 v153, 31, v152
	v_add_co_u32_e32 v32, vcc, s51, v144
	v_cvt_pk_bf16_f32 v113, v108, v109
	v_lshl_add_u64 v[106:107], s[42:43], 0, v[106:107]
	v_cvt_pk_bf16_f32 v94, v94, v95
	v_cvt_pk_bf16_f32 v95, v96, v97
	v_cvt_pk_bf16_f32 v96, v90, v91
	v_lshlrev_b64 v[90:91], 12, v[150:151]
	v_lshl_add_u64 v[30:31], v[144:145], 0, s[58:59]
	v_addc_co_u32_e32 v33, vcc, 0, v145, vcc
	v_cvt_pk_bf16_f32 v14, v14, v15
	v_cvt_pk_bf16_f32 v15, v16, v17
	v_cvt_pk_bf16_f32 v16, v10, v11
	v_cvt_pk_bf16_f32 v17, v12, v13
	s_mov_b32 s51, 0xb0000
	global_store_dwordx4 v[144:145], v[110:113], off offset:256 sc1
	v_cvt_pk_bf16_f32 v97, v92, v93
	v_lshl_add_u64 v[90:91], s[42:43], 0, v[90:91]
	v_lshl_add_u64 v[110:111], v[106:107], 0, v[146:147]
	v_cvt_pk_bf16_f32 v78, v78, v79
	v_cvt_pk_bf16_f32 v79, v80, v81
	v_cvt_pk_bf16_f32 v80, v74, v75
	v_lshlrev_b64 v[74:75], 12, v[152:153]
	global_store_dwordx4 v[30:31], v[14:17], off offset:256 sc1
	global_store_dwordx4 v[110:111], v[94:97], off offset:256 sc1
	v_cvt_pk_bf16_f32 v81, v76, v77
	v_add_co_u32_e32 v16, vcc, s51, v144
	v_lshl_add_u64 v[94:95], v[90:91], 0, v[146:147]
	v_lshl_add_u64 v[74:75], s[42:43], 0, v[74:75]
	s_mov_b64 s[58:59], 0xb0000
	v_addc_co_u32_e32 v17, vcc, 0, v145, vcc
	v_cvt_pk_bf16_f32 v126, v126, v127
	v_cvt_pk_bf16_f32 v127, v128, v129
	v_cvt_pk_bf16_f32 v128, v122, v123
	v_cvt_pk_bf16_f32 v129, v124, v125
	v_cvt_pk_bf16_f32 v106, v118, v119
	v_cvt_pk_bf16_f32 v107, v120, v121
	v_cvt_pk_bf16_f32 v108, v114, v115
	v_cvt_pk_bf16_f32 v109, v116, v117
	v_cvt_pk_bf16_f32 v90, v102, v103
	v_cvt_pk_bf16_f32 v91, v104, v105
	v_cvt_pk_bf16_f32 v92, v98, v99
	v_cvt_pk_bf16_f32 v93, v100, v101
	global_store_dwordx4 v[94:95], v[78:81], off offset:256 sc1
	v_cvt_pk_bf16_f32 v76, v82, v83
	v_cvt_pk_bf16_f32 v77, v84, v85
	v_lshl_add_u64 v[78:79], v[74:75], 0, v[146:147]
	v_cvt_pk_bf16_f32 v74, v86, v87
	v_cvt_pk_bf16_f32 v75, v88, v89
	v_cvt_pk_bf16_f32 v73, v68, v69
	v_cvt_pk_bf16_f32 v65, v60, v61
	v_cvt_pk_bf16_f32 v42, v54, v55
	v_cvt_pk_bf16_f32 v43, v56, v57
	v_cvt_pk_bf16_f32 v44, v50, v51
	v_cvt_pk_bf16_f32 v45, v52, v53
	v_cvt_pk_bf16_f32 v26, v38, v39
	v_cvt_pk_bf16_f32 v27, v40, v41
	v_cvt_pk_bf16_f32 v28, v34, v35
	v_cvt_pk_bf16_f32 v29, v36, v37
	v_lshl_add_u64 v[14:15], v[144:145], 0, s[58:59]
	v_cvt_pk_bf16_f32 v10, v22, v23
	v_cvt_pk_bf16_f32 v11, v24, v25
	v_cvt_pk_bf16_f32 v12, v18, v19
	v_cvt_pk_bf16_f32 v13, v20, v21
	v_cvt_pk_bf16_f32 v6, v6, v7
	v_cvt_pk_bf16_f32 v7, v8, v9
	v_cvt_pk_bf16_f32 v8, v2, v3
	v_cvt_pk_bf16_f32 v9, v4, v5
	s_andn2_b64 vcc, exec, s[48:49]
	s_mov_b64 s[48:49], -1
	v_mov_b32_e32 v238, v195
	global_store_dwordx4 v[144:145], v[126:129], off sc1
	global_store_dwordx4 v[110:111], v[106:109], off sc1
	global_store_dwordx4 v[94:95], v[90:93], off sc1
	global_store_dwordx4 v[78:79], v[74:77], off sc1
	global_store_dwordx4 v[78:79], v[70:73], off offset:256 sc1
	global_store_dwordx4 v[58:59], v[62:65], off sc1
	global_store_dwordx4 v[48:49], v[42:45], off sc1
	global_store_dwordx4 v[32:33], v[26:29], off sc1
	global_store_dwordx4 v[16:17], v[10:13], off sc1
	global_store_dwordx4 v[14:15], v[6:9], off offset:256 sc1
	s_cbranch_vccnz .LBB0_610
	s_andn2_b64 vcc, exec, s[30:31]
	s_cbranch_vccnz .LBB0_609
	s_barrier
	s_branch .LBB0_609

.LBB0_639:
	s_add_u32 s4, s28, s16
	s_addc_u32 s5, s29, s17
	s_add_u32 s10, s4, 0xea00000
	s_addc_u32 s11, s5, 0
	v_mov_b32_e32 v0, 0xea00000
	global_load_dwordx4 v[8:11], v1, s[10:11] offset:48
	global_load_dwordx4 v[12:15], v1, s[10:11] offset:32
	global_load_dwordx4 v[16:19], v1, s[10:11] offset:16
	global_load_dwordx4 v[20:23], v0, s[4:5]
	s_add_i32 s1, s1, s22
	s_add_u32 s16, s16, s30
	s_addc_u32 s17, s17, s31
	s_cmpk_gt_i32 s1, 0x3fff
	s_waitcnt vmcnt(0)
	v_add_f32_e32 v12, v12, v13
	v_add_f32_e32 v14, v14, v15
	v_mov_b32_e32 v24, v21
	v_mov_b32_e32 v25, v22
	v_mov_b32_e32 v21, v23
	v_mov_b32_e32 v22, v17
	v_mov_b32_e32 v23, v18
	v_mov_b32_e32 v17, v19
	v_pk_add_f32 v[20:21], v[24:25], v[20:21]
	v_pk_add_f32 v[16:17], v[22:23], v[16:17]
	v_pk_add_f32 v[20:21], v[20:21], v[20:21] op_sel:[0,1] op_sel_hi:[1,0]
	v_pk_add_f32 v[16:17], v[16:17], v[16:17] op_sel:[0,1] op_sel_hi:[1,0]
	v_mov_b32_e32 v21, v8
	v_mov_b32_e32 v17, v9
	v_mov_b32_e32 v13, v10
	v_mov_b32_e32 v15, v11
	v_pk_add_f32 v[8:9], v[20:21], v[16:17]
	v_pk_add_f32 v[10:11], v[12:13], v[14:15]
	s_nop 0
	v_pk_add_f32 v[8:9], v[8:9], v[10:11]
	s_nop 0
	v_add_f32_e32 v0, v8, v9
	v_fmamk_f32 v0, v0, 0x3a800000, v249
	v_cmp_gt_f32_e32 vcc, s53, v0
	v_mul_f32_e32 v8, 0x4b800000, v0
	s_nop 0
	v_cndmask_b32_e32 v0, v0, v8, vcc
	v_rsq_f32_e32 v0, v0
	s_nop 0
	v_mul_f32_e32 v8, 0x45800000, v0
	v_cndmask_b32_e32 v0, v0, v8, vcc
	v_lshl_add_u64 v[8:9], s[28:29], 0, v[6:7]
	v_add_co_u32_e32 v8, vcc, s9, v8
	v_lshl_add_u64 v[6:7], v[6:7], 0, s[38:39]
	s_nop 0
	v_addc_co_u32_e32 v9, vcc, 0, v9, vcc
	global_load_dwordx2 v[10:11], v[8:9], off
	s_waitcnt vmcnt(0)
	v_lshlrev_b32_e32 v12, 16, v10
	v_and_b32_e32 v13, 0xffff0000, v10
	v_lshlrev_b32_e32 v10, 16, v11
	v_and_b32_e32 v11, 0xffff0000, v11
	v_pk_mul_f32 v[14:15], v[0:1], v[12:13] op_sel_hi:[0,1]
	v_pk_mul_f32 v[16:17], v[0:1], v[10:11] op_sel_hi:[0,1]
	global_load_dwordx4 v[10:13], v[2:3], off
	s_waitcnt vmcnt(0)
	v_pk_mul_f32 v[12:13], v[12:13], v[16:17]
	v_pk_mul_f32 v[10:11], v[10:11], v[14:15]
	global_store_dwordx4 v[4:5], v[10:13], off offset:-2048 sc1
	global_load_dwordx2 v[10:11], v[8:9], off offset:512
	s_waitcnt vmcnt(0)
	v_lshlrev_b32_e32 v12, 16, v10
	v_and_b32_e32 v13, 0xffff0000, v10
	v_lshlrev_b32_e32 v10, 16, v11
	v_and_b32_e32 v11, 0xffff0000, v11
	v_pk_mul_f32 v[14:15], v[0:1], v[12:13] op_sel_hi:[0,1]
	v_pk_mul_f32 v[16:17], v[0:1], v[10:11] op_sel_hi:[0,1]
	global_load_dwordx4 v[10:13], v[2:3], off offset:1024
	s_waitcnt vmcnt(0)
	v_pk_mul_f32 v[12:13], v[12:13], v[16:17]
	v_pk_mul_f32 v[10:11], v[10:11], v[14:15]
	global_store_dwordx4 v[4:5], v[10:13], off offset:-1024 sc1
	global_load_dwordx2 v[10:11], v[8:9], off offset:1024
	s_waitcnt vmcnt(0)
	v_lshlrev_b32_e32 v12, 16, v10
	v_and_b32_e32 v13, 0xffff0000, v10
	v_lshlrev_b32_e32 v10, 16, v11
	v_and_b32_e32 v11, 0xffff0000, v11
	v_pk_mul_f32 v[14:15], v[0:1], v[12:13] op_sel_hi:[0,1]
	v_pk_mul_f32 v[16:17], v[0:1], v[10:11] op_sel_hi:[0,1]
	global_load_dwordx4 v[10:13], v[2:3], off offset:2048
	s_waitcnt vmcnt(0)
	v_pk_mul_f32 v[12:13], v[12:13], v[16:17]
	v_pk_mul_f32 v[10:11], v[10:11], v[14:15]
	global_store_dwordx4 v[4:5], v[10:13], off sc1
	global_load_dwordx2 v[8:9], v[8:9], off offset:1536
	s_waitcnt vmcnt(0)
	v_lshlrev_b32_e32 v10, 16, v8
	v_and_b32_e32 v11, 0xffff0000, v8
	v_lshlrev_b32_e32 v8, 16, v9
	v_and_b32_e32 v9, 0xffff0000, v9
	v_pk_mul_f32 v[12:13], v[0:1], v[10:11] op_sel_hi:[0,1]
	v_pk_mul_f32 v[14:15], v[0:1], v[8:9] op_sel_hi:[0,1]
	global_load_dwordx4 v[8:11], v[2:3], off offset:3072
	s_waitcnt vmcnt(0)
	v_pk_mul_f32 v[10:11], v[10:11], v[14:15]
	v_pk_mul_f32 v[8:9], v[8:9], v[12:13]
	global_store_dwordx4 v[4:5], v[8:11], off offset:1024 sc1
	v_lshl_add_u64 v[4:5], v[4:5], 0, s[40:41]
	s_cbranch_scc0 .LBB0_639

.LBB0_660:
	v_pk_mul_f32 v[122:123], v[122:123], v[158:159] op_sel_hi:[1,0]
	v_lshl_or_b32 v142, s38, 8, v157
	v_pk_mul_f32 v[128:129], v[128:129], v[158:159] op_sel_hi:[1,0]
	v_pk_mul_f32 v[126:127], v[126:127], v[158:159] op_sel_hi:[1,0]
	v_pk_mul_f32 v[124:125], v[124:125], v[158:159] op_sel_hi:[1,0]
	v_max_f32_e32 v122, 0, v122
	v_max_f32_e32 v123, 0, v123
	v_ashrrev_i32_e32 v143, 31, v142
	v_lshlrev_b64 v[160:161], 13, v[144:145]
	v_max_f32_e32 v126, 0, v126
	v_max_f32_e32 v127, 0, v127
	v_pk_mul_f32 v[162:163], v[122:123], v[122:123]
	v_max_f32_e32 v122, 0, v128
	v_max_f32_e32 v124, 0, v124
	v_max_f32_e32 v123, 0, v129
	v_max_f32_e32 v125, 0, v125
	v_lshl_add_u64 v[160:161], s[28:29], 0, v[160:161]
	v_lshlrev_b64 v[142:143], 1, v[142:143]
	v_pk_mul_f32 v[126:127], v[126:127], v[126:127]
	v_pk_mul_f32 v[128:129], v[122:123], v[122:123]
	v_pk_mul_f32 v[164:165], v[124:125], v[124:125]
	v_pk_mul_f32 v[114:115], v[114:115], v[158:159] op_sel_hi:[1,0]
	v_lshl_add_u64 v[160:161], v[160:161], 0, v[142:143]
	v_cvt_pk_bf16_f32 v122, v126, v127
	v_cvt_pk_bf16_f32 v123, v128, v129
	v_cvt_pk_bf16_f32 v124, v162, v163
	v_cvt_pk_bf16_f32 v125, v164, v165
	v_pk_mul_f32 v[120:121], v[120:121], v[158:159] op_sel_hi:[1,0]
	v_pk_mul_f32 v[118:119], v[118:119], v[158:159] op_sel_hi:[1,0]
	v_pk_mul_f32 v[116:117], v[116:117], v[158:159] op_sel_hi:[1,0]
	v_max_f32_e32 v114, 0, v114
	v_max_f32_e32 v115, 0, v115
	global_store_dwordx4 v[160:161], v[122:125], off sc1
	v_max_f32_e32 v118, 0, v118
	v_max_f32_e32 v119, 0, v119
	v_pk_mul_f32 v[122:123], v[114:115], v[114:115]
	v_max_f32_e32 v114, 0, v120
	v_max_f32_e32 v116, 0, v116
	v_max_f32_e32 v115, 0, v121
	v_max_f32_e32 v117, 0, v117
	v_pk_mul_f32 v[118:119], v[118:119], v[118:119]
	v_pk_mul_f32 v[120:121], v[114:115], v[114:115]
	v_pk_mul_f32 v[124:125], v[116:117], v[116:117]
	v_pk_mul_f32 v[106:107], v[106:107], v[154:155] op_sel_hi:[1,0]
	v_cvt_pk_bf16_f32 v114, v118, v119
	v_cvt_pk_bf16_f32 v115, v120, v121
	v_cvt_pk_bf16_f32 v116, v122, v123
	v_cvt_pk_bf16_f32 v117, v124, v125
	v_pk_mul_f32 v[112:113], v[112:113], v[154:155] op_sel_hi:[1,0]
	v_pk_mul_f32 v[110:111], v[110:111], v[154:155] op_sel_hi:[1,0]
	v_pk_mul_f32 v[108:109], v[108:109], v[154:155] op_sel_hi:[1,0]
	v_max_f32_e32 v106, 0, v106
	v_max_f32_e32 v107, 0, v107
	global_store_dwordx4 v[160:161], v[114:117], off offset:256 sc1
	v_max_f32_e32 v110, 0, v110
	v_max_f32_e32 v111, 0, v111
	v_lshlrev_b64 v[114:115], 13, v[150:151]
	v_pk_mul_f32 v[116:117], v[106:107], v[106:107]
	v_max_f32_e32 v106, 0, v112
	v_max_f32_e32 v108, 0, v108
	v_max_f32_e32 v107, 0, v113
	v_max_f32_e32 v109, 0, v109
	v_lshl_add_u64 v[114:115], s[28:29], 0, v[114:115]
	v_pk_mul_f32 v[110:111], v[110:111], v[110:111]
	v_pk_mul_f32 v[112:113], v[106:107], v[106:107]
	v_pk_mul_f32 v[118:119], v[108:109], v[108:109]
	v_pk_mul_f32 v[98:99], v[98:99], v[154:155] op_sel_hi:[1,0]
	v_lshl_add_u64 v[114:115], v[114:115], 0, v[142:143]
	v_cvt_pk_bf16_f32 v106, v110, v111
	v_cvt_pk_bf16_f32 v107, v112, v113
	v_cvt_pk_bf16_f32 v108, v116, v117
	v_cvt_pk_bf16_f32 v109, v118, v119
	v_pk_mul_f32 v[104:105], v[104:105], v[154:155] op_sel_hi:[1,0]
	v_pk_mul_f32 v[102:103], v[102:103], v[154:155] op_sel_hi:[1,0]
	v_pk_mul_f32 v[100:101], v[100:101], v[154:155] op_sel_hi:[1,0]
	v_max_f32_e32 v98, 0, v98
	v_max_f32_e32 v99, 0, v99
	global_store_dwordx4 v[114:115], v[106:109], off sc1
	v_max_f32_e32 v102, 0, v102
	v_max_f32_e32 v103, 0, v103
	v_pk_mul_f32 v[106:107], v[98:99], v[98:99]
	v_max_f32_e32 v98, 0, v104
	v_max_f32_e32 v100, 0, v100
	v_max_f32_e32 v99, 0, v105
	v_max_f32_e32 v101, 0, v101
	v_pk_mul_f32 v[102:103], v[102:103], v[102:103]
	v_pk_mul_f32 v[104:105], v[98:99], v[98:99]
	v_pk_mul_f32 v[108:109], v[100:101], v[100:101]
	v_pk_mul_f32 v[90:91], v[90:91], v[156:157] op_sel_hi:[1,0]
	v_cvt_pk_bf16_f32 v98, v102, v103
	v_cvt_pk_bf16_f32 v99, v104, v105
	v_cvt_pk_bf16_f32 v100, v106, v107
	v_cvt_pk_bf16_f32 v101, v108, v109
	v_pk_mul_f32 v[96:97], v[96:97], v[156:157] op_sel_hi:[1,0]
	v_pk_mul_f32 v[94:95], v[94:95], v[156:157] op_sel_hi:[1,0]
	v_pk_mul_f32 v[92:93], v[92:93], v[156:157] op_sel_hi:[1,0]
	v_max_f32_e32 v90, 0, v90
	v_max_f32_e32 v91, 0, v91
	global_store_dwordx4 v[114:115], v[98:101], off offset:256 sc1
	v_max_f32_e32 v94, 0, v94
	v_max_f32_e32 v95, 0, v95
	v_lshlrev_b64 v[98:99], 13, v[148:149]
	v_pk_mul_f32 v[100:101], v[90:91], v[90:91]
	v_max_f32_e32 v90, 0, v96
	v_max_f32_e32 v92, 0, v92
	v_max_f32_e32 v91, 0, v97
	v_max_f32_e32 v93, 0, v93
	v_lshl_add_u64 v[98:99], s[28:29], 0, v[98:99]
	v_pk_mul_f32 v[94:95], v[94:95], v[94:95]
	v_pk_mul_f32 v[96:97], v[90:91], v[90:91]
	v_pk_mul_f32 v[102:103], v[92:93], v[92:93]
	v_pk_mul_f32 v[82:83], v[82:83], v[156:157] op_sel_hi:[1,0]
	v_lshl_add_u64 v[98:99], v[98:99], 0, v[142:143]
	v_cvt_pk_bf16_f32 v90, v94, v95
	v_cvt_pk_bf16_f32 v91, v96, v97
	v_cvt_pk_bf16_f32 v92, v100, v101
	v_cvt_pk_bf16_f32 v93, v102, v103
	v_pk_mul_f32 v[88:89], v[88:89], v[156:157] op_sel_hi:[1,0]
	v_pk_mul_f32 v[86:87], v[86:87], v[156:157] op_sel_hi:[1,0]
	v_pk_mul_f32 v[84:85], v[84:85], v[156:157] op_sel_hi:[1,0]
	v_max_f32_e32 v82, 0, v82
	v_max_f32_e32 v83, 0, v83
	global_store_dwordx4 v[98:99], v[90:93], off sc1
	v_max_f32_e32 v86, 0, v86
	v_max_f32_e32 v87, 0, v87
	v_pk_mul_f32 v[90:91], v[82:83], v[82:83]
	v_max_f32_e32 v82, 0, v88
	v_max_f32_e32 v84, 0, v84
	v_max_f32_e32 v83, 0, v89
	v_max_f32_e32 v85, 0, v85
	v_pk_mul_f32 v[86:87], v[86:87], v[86:87]
	v_pk_mul_f32 v[88:89], v[82:83], v[82:83]
	v_pk_mul_f32 v[92:93], v[84:85], v[84:85]
	v_pk_mul_f32 v[74:75], v[74:75], v[152:153] op_sel_hi:[1,0]
	v_cvt_pk_bf16_f32 v82, v86, v87
	v_cvt_pk_bf16_f32 v83, v88, v89
	v_cvt_pk_bf16_f32 v84, v90, v91
	v_cvt_pk_bf16_f32 v85, v92, v93
	v_pk_mul_f32 v[80:81], v[80:81], v[152:153] op_sel_hi:[1,0]
	v_pk_mul_f32 v[78:79], v[78:79], v[152:153] op_sel_hi:[1,0]
	v_pk_mul_f32 v[76:77], v[76:77], v[152:153] op_sel_hi:[1,0]
	v_max_f32_e32 v74, 0, v74
	v_max_f32_e32 v75, 0, v75
	global_store_dwordx4 v[98:99], v[82:85], off offset:256 sc1
	v_max_f32_e32 v78, 0, v78
	v_max_f32_e32 v79, 0, v79
	v_lshlrev_b64 v[82:83], 13, v[146:147]
	v_pk_mul_f32 v[84:85], v[74:75], v[74:75]
	v_max_f32_e32 v74, 0, v80
	v_max_f32_e32 v76, 0, v76
	v_max_f32_e32 v75, 0, v81
	v_max_f32_e32 v77, 0, v77
	v_lshl_add_u64 v[82:83], s[28:29], 0, v[82:83]
	v_pk_mul_f32 v[78:79], v[78:79], v[78:79]
	v_pk_mul_f32 v[80:81], v[74:75], v[74:75]
	v_pk_mul_f32 v[86:87], v[76:77], v[76:77]
	v_pk_mul_f32 v[66:67], v[66:67], v[152:153] op_sel_hi:[1,0]
	v_lshl_add_u64 v[82:83], v[82:83], 0, v[142:143]
	v_cvt_pk_bf16_f32 v74, v78, v79
	v_cvt_pk_bf16_f32 v75, v80, v81
	v_cvt_pk_bf16_f32 v76, v84, v85
	v_cvt_pk_bf16_f32 v77, v86, v87
	v_pk_mul_f32 v[72:73], v[72:73], v[152:153] op_sel_hi:[1,0]
	v_pk_mul_f32 v[70:71], v[70:71], v[152:153] op_sel_hi:[1,0]
	v_pk_mul_f32 v[68:69], v[68:69], v[152:153] op_sel_hi:[1,0]
	v_max_f32_e32 v66, 0, v66
	v_max_f32_e32 v67, 0, v67
	global_store_dwordx4 v[82:83], v[74:77], off sc1
	v_max_f32_e32 v70, 0, v70
	v_max_f32_e32 v71, 0, v71
	v_pk_mul_f32 v[74:75], v[66:67], v[66:67]
	v_max_f32_e32 v66, 0, v72
	v_max_f32_e32 v68, 0, v68
	v_max_f32_e32 v67, 0, v73
	v_max_f32_e32 v69, 0, v69
	v_pk_mul_f32 v[70:71], v[70:71], v[70:71]
	v_pk_mul_f32 v[72:73], v[66:67], v[66:67]
	v_pk_mul_f32 v[76:77], v[68:69], v[68:69]
	v_cvt_pk_bf16_f32 v66, v70, v71
	v_cvt_pk_bf16_f32 v67, v72, v73
	v_cvt_pk_bf16_f32 v68, v74, v75
	v_cvt_pk_bf16_f32 v69, v76, v77
	v_add_u32_e32 v74, 0x80, v144
	global_store_dwordx4 v[82:83], v[66:69], off offset:256 sc1
	v_ashrrev_i32_e32 v75, 31, v74
	s_andn2_b64 vcc, exec, s[46:47]
	v_add_u32_e32 v70, 0x90, v144
	v_add_u32_e32 v68, 0xa0, v144
	v_add_u32_e32 v66, 0xb0, v144
	s_cbranch_vccnz .LBB0_667
	v_ashrrev_i32_e32 v71, 31, v70
	v_lshlrev_b64 v[72:73], 6, v[74:75]
	v_lshlrev_b64 v[76:77], 6, v[70:71]
	v_lshl_add_u64 v[72:73], v[136:137], 0, v[72:73]
	v_lshl_add_u64 v[80:81], v[136:137], 0, v[76:77]
	v_ashrrev_i32_e32 v69, 31, v68
	v_ashrrev_i32_e32 v67, 31, v66
	global_load_dwordx4 v[76:79], v[72:73], off
	s_nop 0
	global_load_dwordx4 v[80:83], v[80:81], off
	v_lshlrev_b64 v[72:73], 6, v[68:69]
	v_lshlrev_b64 v[84:85], 6, v[66:67]
	v_lshl_add_u64 v[72:73], v[136:137], 0, v[72:73]
	v_lshl_add_u64 v[88:89], v[136:137], 0, v[84:85]
	global_load_dwordx4 v[84:87], v[72:73], off
	s_nop 0
	global_load_dwordx4 v[88:91], v[88:89], off
	v_cmp_lt_i32_e32 vcc, v218, v213
	s_waitcnt vmcnt(0)
	v_mov_b32_e32 v73, v80
	v_mov_b32_e32 v80, v77
	v_cndmask_b32_e32 v72, v211, v218, vcc
	v_cmp_lt_i32_e32 vcc, v219, v213
	v_lshlrev_b32_e32 v92, 2, v72
	v_mov_b32_e32 v77, v82
	v_cndmask_b32_e32 v72, v211, v219, vcc
	v_lshlrev_b32_e32 v93, 2, v72
	v_mov_b32_e32 v72, v76
	v_mov_b32_e32 v76, v78
	v_mov_b32_e32 v82, v79
	v_pk_add_f32 v[72:73], v[72:73], v[80:81]
	v_pk_add_f32 v[76:77], v[76:77], v[82:83]
	s_mov_b32 s38, 0x358637bd
	v_pk_add_f32 v[72:73], v[72:73], v[76:77]
	ds_bpermute_b32 v76, v92, v72
	ds_bpermute_b32 v77, v92, v73
	v_mov_b64_e32 v[78:79], s[38:39]
	s_mov_b32 s54, 0x3a800000
	s_mov_b32 s38, 0x45800000
	v_add_f32_e32 v82, v86, v87
	s_waitcnt lgkmcnt(0)
	v_pk_add_f32 v[72:73], v[72:73], v[76:77]
	ds_bpermute_b32 v76, v93, v72
	ds_bpermute_b32 v77, v93, v73
	s_waitcnt lgkmcnt(0)
	v_pk_add_f32 v[72:73], v[72:73], v[76:77]
	s_nop 0
	v_pk_fma_f32 v[72:73], v[72:73], s[54:55], v[78:79] op_sel_hi:[1,0,0]
	s_nop 0
	v_mul_f32_e32 v76, 0x4b800000, v72
	v_cmp_gt_f32_e64 s[44:45], s39, v72
	v_cmp_gt_f32_e32 vcc, s39, v73
	s_nop 0
	v_cndmask_b32_e64 v72, v72, v76, s[44:45]
	v_mul_f32_e32 v76, 0x4b800000, v73
	v_cndmask_b32_e32 v73, v73, v76, vcc
	v_rsq_f32_e32 v72, v72
	v_rsq_f32_e32 v73, v73
	s_nop 0
	v_pk_mul_f32 v[76:77], v[72:73], s[38:39] op_sel_hi:[1,0]
	s_nop 0
	v_cndmask_b32_e64 v80, v72, v76, s[44:45]
	v_add_f32_e32 v72, v84, v85
	v_mov_b32_e32 v84, v89
	v_mov_b32_e32 v85, v90
	v_mov_b32_e32 v89, v91
	v_pk_add_f32 v[84:85], v[84:85], v[88:89]
	v_cndmask_b32_e32 v76, v73, v77, vcc
	v_mov_b32_e32 v73, v84
	v_mov_b32_e32 v83, v85
	v_pk_add_f32 v[72:73], v[72:73], v[82:83]
	ds_bpermute_b32 v82, v92, v72
	ds_bpermute_b32 v83, v92, v73
	s_waitcnt lgkmcnt(0)
	v_pk_add_f32 v[72:73], v[72:73], v[82:83]
	ds_bpermute_b32 v82, v93, v72
	ds_bpermute_b32 v83, v93, v73
	s_waitcnt lgkmcnt(0)
	v_pk_add_f32 v[72:73], v[72:73], v[82:83]
	s_nop 0
	v_pk_fma_f32 v[72:73], v[72:73], s[54:55], v[78:79] op_sel_hi:[1,0,0]
	s_nop 0
	v_mul_f32_e32 v77, 0x4b800000, v72
	v_cmp_gt_f32_e64 s[44:45], s39, v72
	v_cmp_gt_f32_e32 vcc, s39, v73
	s_nop 0
	v_cndmask_b32_e64 v72, v72, v77, s[44:45]
	v_mul_f32_e32 v77, 0x4b800000, v73
	v_cndmask_b32_e32 v73, v73, v77, vcc
	v_rsq_f32_e32 v72, v72
	v_rsq_f32_e32 v73, v73
	s_nop 0
	v_pk_mul_f32 v[78:79], v[72:73], s[38:39] op_sel_hi:[1,0]
	s_nop 0
	v_cndmask_b32_e64 v78, v72, v78, s[44:45]
	v_cndmask_b32_e32 v72, v73, v79, vcc
	s_cbranch_execnz .LBB0_663

.LBB0_663:
	v_pk_mul_f32 v[58:59], v[58:59], v[80:81] op_sel_hi:[1,0]
	v_pk_mul_f32 v[64:65], v[64:65], v[80:81] op_sel_hi:[1,0]
	v_pk_mul_f32 v[62:63], v[62:63], v[80:81] op_sel_hi:[1,0]
	v_pk_mul_f32 v[60:61], v[60:61], v[80:81] op_sel_hi:[1,0]
	v_max_f32_e32 v58, 0, v58
	v_max_f32_e32 v59, 0, v59
	v_lshlrev_b64 v[74:75], 13, v[74:75]
	v_max_f32_e32 v62, 0, v62
	v_max_f32_e32 v63, 0, v63
	v_pk_mul_f32 v[82:83], v[58:59], v[58:59]
	v_max_f32_e32 v58, 0, v64
	v_max_f32_e32 v60, 0, v60
	v_max_f32_e32 v59, 0, v65
	v_max_f32_e32 v61, 0, v61
	v_lshl_add_u64 v[74:75], s[28:29], 0, v[74:75]
	v_pk_mul_f32 v[62:63], v[62:63], v[62:63]
	v_pk_mul_f32 v[64:65], v[58:59], v[58:59]
	v_pk_mul_f32 v[84:85], v[60:61], v[60:61]
	v_pk_mul_f32 v[50:51], v[50:51], v[80:81] op_sel_hi:[1,0]
	v_lshl_add_u64 v[74:75], v[74:75], 0, v[142:143]
	v_cvt_pk_bf16_f32 v58, v62, v63
	v_cvt_pk_bf16_f32 v59, v64, v65
	v_cvt_pk_bf16_f32 v60, v82, v83
	v_cvt_pk_bf16_f32 v61, v84, v85
	v_pk_mul_f32 v[56:57], v[56:57], v[80:81] op_sel_hi:[1,0]
	v_pk_mul_f32 v[54:55], v[54:55], v[80:81] op_sel_hi:[1,0]
	v_pk_mul_f32 v[52:53], v[52:53], v[80:81] op_sel_hi:[1,0]
	v_max_f32_e32 v50, 0, v50
	v_max_f32_e32 v51, 0, v51
	global_store_dwordx4 v[74:75], v[58:61], off sc1
	v_max_f32_e32 v54, 0, v54
	v_max_f32_e32 v55, 0, v55
	v_pk_mul_f32 v[58:59], v[50:51], v[50:51]
	v_max_f32_e32 v50, 0, v56
	v_max_f32_e32 v52, 0, v52
	v_max_f32_e32 v51, 0, v57
	v_max_f32_e32 v53, 0, v53
	v_pk_mul_f32 v[54:55], v[54:55], v[54:55]
	v_pk_mul_f32 v[56:57], v[50:51], v[50:51]
	v_pk_mul_f32 v[60:61], v[52:53], v[52:53]
	v_pk_mul_f32 v[42:43], v[42:43], v[76:77] op_sel_hi:[1,0]
	v_cvt_pk_bf16_f32 v50, v54, v55
	v_cvt_pk_bf16_f32 v51, v56, v57
	v_cvt_pk_bf16_f32 v52, v58, v59
	v_cvt_pk_bf16_f32 v53, v60, v61
	v_pk_mul_f32 v[48:49], v[48:49], v[76:77] op_sel_hi:[1,0]
	v_pk_mul_f32 v[46:47], v[46:47], v[76:77] op_sel_hi:[1,0]
	v_pk_mul_f32 v[44:45], v[44:45], v[76:77] op_sel_hi:[1,0]
	v_max_f32_e32 v42, 0, v42
	v_max_f32_e32 v43, 0, v43
	global_store_dwordx4 v[74:75], v[50:53], off offset:256 sc1
	v_max_f32_e32 v46, 0, v46
	v_max_f32_e32 v47, 0, v47
	v_lshlrev_b64 v[50:51], 13, v[70:71]
	v_pk_mul_f32 v[52:53], v[42:43], v[42:43]
	v_max_f32_e32 v42, 0, v48
	v_max_f32_e32 v44, 0, v44
	v_max_f32_e32 v43, 0, v49
	v_max_f32_e32 v45, 0, v45
	v_lshl_add_u64 v[50:51], s[28:29], 0, v[50:51]
	v_pk_mul_f32 v[46:47], v[46:47], v[46:47]
	v_pk_mul_f32 v[48:49], v[42:43], v[42:43]
	v_pk_mul_f32 v[54:55], v[44:45], v[44:45]
	v_pk_mul_f32 v[34:35], v[34:35], v[76:77] op_sel_hi:[1,0]
	v_lshl_add_u64 v[50:51], v[50:51], 0, v[142:143]
	v_cvt_pk_bf16_f32 v42, v46, v47
	v_cvt_pk_bf16_f32 v43, v48, v49
	v_cvt_pk_bf16_f32 v44, v52, v53
	v_cvt_pk_bf16_f32 v45, v54, v55
	v_pk_mul_f32 v[40:41], v[40:41], v[76:77] op_sel_hi:[1,0]
	v_pk_mul_f32 v[38:39], v[38:39], v[76:77] op_sel_hi:[1,0]
	v_pk_mul_f32 v[36:37], v[36:37], v[76:77] op_sel_hi:[1,0]
	v_max_f32_e32 v34, 0, v34
	v_max_f32_e32 v35, 0, v35
	global_store_dwordx4 v[50:51], v[42:45], off sc1
	v_max_f32_e32 v38, 0, v38
	v_max_f32_e32 v39, 0, v39
	v_pk_mul_f32 v[42:43], v[34:35], v[34:35]
	v_max_f32_e32 v34, 0, v40
	v_max_f32_e32 v36, 0, v36
	v_max_f32_e32 v35, 0, v41
	v_max_f32_e32 v37, 0, v37
	v_pk_mul_f32 v[38:39], v[38:39], v[38:39]
	v_pk_mul_f32 v[40:41], v[34:35], v[34:35]
	v_pk_mul_f32 v[44:45], v[36:37], v[36:37]
	v_pk_mul_f32 v[26:27], v[26:27], v[78:79] op_sel_hi:[1,0]
	v_cvt_pk_bf16_f32 v34, v38, v39
	v_cvt_pk_bf16_f32 v35, v40, v41
	v_cvt_pk_bf16_f32 v36, v42, v43
	v_cvt_pk_bf16_f32 v37, v44, v45
	v_pk_mul_f32 v[32:33], v[32:33], v[78:79] op_sel_hi:[1,0]
	v_pk_mul_f32 v[30:31], v[30:31], v[78:79] op_sel_hi:[1,0]
	v_pk_mul_f32 v[28:29], v[28:29], v[78:79] op_sel_hi:[1,0]
	v_max_f32_e32 v26, 0, v26
	v_max_f32_e32 v27, 0, v27
	global_store_dwordx4 v[50:51], v[34:37], off offset:256 sc1
	v_max_f32_e32 v30, 0, v30
	v_max_f32_e32 v31, 0, v31
	v_lshlrev_b64 v[34:35], 13, v[68:69]
	v_pk_mul_f32 v[36:37], v[26:27], v[26:27]
	v_max_f32_e32 v26, 0, v32
	v_max_f32_e32 v28, 0, v28
	v_max_f32_e32 v27, 0, v33
	v_max_f32_e32 v29, 0, v29
	v_lshl_add_u64 v[34:35], s[28:29], 0, v[34:35]
	v_pk_mul_f32 v[30:31], v[30:31], v[30:31]
	v_pk_mul_f32 v[32:33], v[26:27], v[26:27]
	v_pk_mul_f32 v[38:39], v[28:29], v[28:29]
	v_pk_mul_f32 v[18:19], v[18:19], v[78:79] op_sel_hi:[1,0]
	v_lshl_add_u64 v[34:35], v[34:35], 0, v[142:143]
	v_cvt_pk_bf16_f32 v26, v30, v31
	v_cvt_pk_bf16_f32 v27, v32, v33
	v_cvt_pk_bf16_f32 v28, v36, v37
	v_cvt_pk_bf16_f32 v29, v38, v39
	v_pk_mul_f32 v[24:25], v[24:25], v[78:79] op_sel_hi:[1,0]
	v_pk_mul_f32 v[22:23], v[22:23], v[78:79] op_sel_hi:[1,0]
	v_pk_mul_f32 v[20:21], v[20:21], v[78:79] op_sel_hi:[1,0]
	v_max_f32_e32 v18, 0, v18
	v_max_f32_e32 v19, 0, v19
	global_store_dwordx4 v[34:35], v[26:29], off sc1
	v_max_f32_e32 v22, 0, v22
	v_max_f32_e32 v23, 0, v23
	v_pk_mul_f32 v[26:27], v[18:19], v[18:19]
	v_max_f32_e32 v18, 0, v24
	v_max_f32_e32 v20, 0, v20
	v_max_f32_e32 v19, 0, v25
	v_max_f32_e32 v21, 0, v21
	v_pk_mul_f32 v[22:23], v[22:23], v[22:23]
	v_pk_mul_f32 v[24:25], v[18:19], v[18:19]
	v_pk_mul_f32 v[28:29], v[20:21], v[20:21]
	v_pk_mul_f32 v[10:11], v[10:11], v[72:73] op_sel_hi:[1,0]
	v_cvt_pk_bf16_f32 v18, v22, v23
	v_cvt_pk_bf16_f32 v19, v24, v25
	v_cvt_pk_bf16_f32 v20, v26, v27
	v_cvt_pk_bf16_f32 v21, v28, v29
	v_pk_mul_f32 v[16:17], v[16:17], v[72:73] op_sel_hi:[1,0]
	v_pk_mul_f32 v[14:15], v[14:15], v[72:73] op_sel_hi:[1,0]
	v_pk_mul_f32 v[12:13], v[12:13], v[72:73] op_sel_hi:[1,0]
	v_max_f32_e32 v10, 0, v10
	v_max_f32_e32 v11, 0, v11
	global_store_dwordx4 v[34:35], v[18:21], off offset:256 sc1
	v_max_f32_e32 v14, 0, v14
	v_max_f32_e32 v15, 0, v15
	v_lshlrev_b64 v[18:19], 13, v[66:67]
	v_pk_mul_f32 v[20:21], v[10:11], v[10:11]
	v_max_f32_e32 v10, 0, v16
	v_max_f32_e32 v12, 0, v12
	v_max_f32_e32 v11, 0, v17
	v_max_f32_e32 v13, 0, v13
	v_lshl_add_u64 v[18:19], s[28:29], 0, v[18:19]
	v_pk_mul_f32 v[14:15], v[14:15], v[14:15]
	v_pk_mul_f32 v[16:17], v[10:11], v[10:11]
	v_pk_mul_f32 v[22:23], v[12:13], v[12:13]
	v_pk_mul_f32 v[2:3], v[2:3], v[72:73] op_sel_hi:[1,0]
	v_lshl_add_u64 v[18:19], v[18:19], 0, v[142:143]
	v_cvt_pk_bf16_f32 v10, v14, v15
	v_cvt_pk_bf16_f32 v11, v16, v17
	v_cvt_pk_bf16_f32 v12, v20, v21
	v_cvt_pk_bf16_f32 v13, v22, v23
	v_pk_mul_f32 v[8:9], v[8:9], v[72:73] op_sel_hi:[1,0]
	v_pk_mul_f32 v[6:7], v[6:7], v[72:73] op_sel_hi:[1,0]
	v_pk_mul_f32 v[4:5], v[4:5], v[72:73] op_sel_hi:[1,0]
	v_max_f32_e32 v2, 0, v2
	v_max_f32_e32 v3, 0, v3
	global_store_dwordx4 v[18:19], v[10:13], off sc1
	v_max_f32_e32 v6, 0, v6
	v_max_f32_e32 v7, 0, v7
	v_pk_mul_f32 v[10:11], v[2:3], v[2:3]
	v_max_f32_e32 v2, 0, v8
	v_max_f32_e32 v4, 0, v4
	v_max_f32_e32 v3, 0, v9
	v_max_f32_e32 v5, 0, v5
	v_pk_mul_f32 v[6:7], v[6:7], v[6:7]
	v_pk_mul_f32 v[8:9], v[2:3], v[2:3]
	v_pk_mul_f32 v[12:13], v[4:5], v[4:5]
	v_cvt_pk_bf16_f32 v2, v6, v7
	v_cvt_pk_bf16_f32 v3, v8, v9
	v_cvt_pk_bf16_f32 v4, v10, v11
	v_cvt_pk_bf16_f32 v5, v12, v13
	s_andn2_b64 vcc, exec, s[42:43]
	s_mov_b64 s[42:43], -1
	global_store_dwordx4 v[18:19], v[2:5], off offset:256 sc1
	s_cbranch_vccnz .LBB0_646
	s_andn2_b64 vcc, exec, s[16:17]
	s_cbranch_vccnz .LBB0_645
	s_barrier
	s_branch .LBB0_645

.LBB0_674:
	v_readlane_b32 s16, v255, 34
	v_readlane_b32 s17, v255, 35
	s_load_dwordx2 s[16:17], s[16:17], 0xf0
	s_mul_i32 s31, s31, s26
	v_or_b32_e32 v19, s30, v4
	v_or_b32_e32 v21, 8, v19
	s_waitcnt vmcnt(0)
	ds_bpermute_b32 v32, v5, v3
	s_waitcnt lgkmcnt(0)
	s_add_u32 s22, s16, s28
	s_addc_u32 s23, s17, s29
	s_sub_i32 s9, s9, s31
	s_lshl_b32 s16, s9, 5
	s_ashr_i32 s17, s16, 31
	s_lshl_b64 s[28:29], s[16:17], 2
	s_add_u32 s10, s10, s28
	s_addc_u32 s11, s11, s29
	v_lshl_add_u64 v[30:31], s[10:11], 0, v[0:1]
	v_mad_i64_i32 v[22:23], s[10:11], v19, s5, 0
	v_lshl_add_u64 v[22:23], v[22:23], 2, v[30:31]
	global_load_dwordx4 v[22:25], v[22:23], off
	v_mad_i64_i32 v[26:27], s[10:11], v21, s5, 0
	v_lshl_add_u64 v[26:27], v[26:27], 2, v[30:31]
	global_load_dwordx4 v[26:29], v[26:27], off
	v_or_b32_e32 v21, 16, v19
	ds_bpermute_b32 v34, v7, v3
	v_mad_i64_i32 v[36:37], s[10:11], v21, s5, 0
	v_lshl_add_u64 v[36:37], v[36:37], 2, v[30:31]
	v_or_b32_e32 v21, 24, v19
	ds_bpermute_b32 v40, v9, v3
	ds_bpermute_b32 v48, v12, v3
	s_ashr_i32 s31, s30, 31
	s_waitcnt vmcnt(1)
	v_pk_mul_f32 v[38:39], v[22:23], v[32:33] op_sel_hi:[1,0]
	v_pk_mul_f32 v[32:33], v[24:25], v[32:33] op_sel_hi:[1,0]
	global_load_dwordx4 v[22:25], v[36:37], off
	s_waitcnt vmcnt(1) lgkmcnt(2)
	v_pk_mul_f32 v[36:37], v[26:27], v[34:35] op_sel_hi:[1,0]
	v_mad_i64_i32 v[26:27], s[10:11], v21, s5, 0
	v_lshl_add_u64 v[26:27], v[26:27], 2, v[30:31]
	v_pk_mul_f32 v[34:35], v[28:29], v[34:35] op_sel_hi:[1,0]
	global_load_dwordx4 v[26:29], v[26:27], off
	v_or_b32_e32 v21, 32, v19
	s_waitcnt vmcnt(1) lgkmcnt(1)
	v_pk_mul_f32 v[42:43], v[22:23], v[40:41] op_sel_hi:[1,0]
	ds_bpermute_b32 v22, v11, v3
	v_pk_mul_f32 v[40:41], v[24:25], v[40:41] op_sel_hi:[1,0]
	s_waitcnt vmcnt(0) lgkmcnt(0)
	v_pk_mul_f32 v[44:45], v[26:27], v[22:23] op_sel_hi:[1,0]
	v_pk_mul_f32 v[46:47], v[28:29], v[22:23] op_sel_hi:[1,0]
	v_mad_i64_i32 v[22:23], s[10:11], v21, s5, 0
	v_or_b32_e32 v21, 40, v19
	v_mad_i64_i32 v[24:25], s[10:11], v21, s5, 0
	v_lshl_add_u64 v[22:23], v[22:23], 2, v[30:31]
	v_lshl_add_u64 v[26:27], v[24:25], 2, v[30:31]
	global_load_dwordx4 v[22:25], v[22:23], off
	s_nop 0
	global_load_dwordx4 v[26:29], v[26:27], off
	v_add_u32_e32 v21, 0x420, v17
	ds_write2_b32 v21, v36, v37 offset1:1
	v_add_u32_e32 v21, 0x428, v17
	ds_write2_b32 v21, v34, v35 offset1:1
	v_add_u32_e32 v21, 0x840, v17
	ds_write2_b32 v21, v42, v43 offset1:1
	v_add_u32_e32 v21, 0x848, v17
	ds_write2_b32 v21, v40, v41 offset1:1
	v_or_b32_e32 v21, 48, v19
	v_or_b32_e32 v19, 56, v19
	ds_write2_b32 v17, v32, v33 offset0:2 offset1:3
	ds_bpermute_b32 v32, v15, v3
	ds_write2_b32 v17, v38, v39 offset1:1
	s_waitcnt vmcnt(1)
	v_pk_mul_f32 v[50:51], v[22:23], v[48:49] op_sel_hi:[1,0]
	ds_bpermute_b32 v22, v13, v3
	v_pk_mul_f32 v[48:49], v[24:25], v[48:49] op_sel_hi:[1,0]
	v_mad_i64_i32 v[24:25], s[10:11], v19, s5, 0
	v_add_u32_e32 v19, 0xc60, v17
	s_waitcnt vmcnt(0) lgkmcnt(0)
	v_pk_mul_f32 v[52:53], v[26:27], v[22:23] op_sel_hi:[1,0]
	v_pk_mul_f32 v[54:55], v[28:29], v[22:23] op_sel_hi:[1,0]
	v_mad_i64_i32 v[22:23], s[10:11], v21, s5, 0
	v_lshl_add_u64 v[22:23], v[22:23], 2, v[30:31]
	v_lshl_add_u64 v[26:27], v[24:25], 2, v[30:31]
	global_load_dwordx4 v[22:25], v[22:23], off
	ds_bpermute_b32 v30, v14, v3
	global_load_dwordx4 v[26:29], v[26:27], off
	ds_write2_b32 v19, v44, v45 offset1:1
	v_add_u32_e32 v19, 0xc68, v17
	ds_write2_b32 v19, v46, v47 offset1:1
	v_add_u32_e32 v19, 0x1080, v17
	v_add_u32_e32 v21, 0x1088, v17
	v_add_u32_e32 v31, 0x14a0, v17
	ds_write2_b32 v19, v50, v51 offset1:1
	v_add_u32_e32 v19, 0x14a8, v17
	ds_write2_b32 v21, v48, v49 offset1:1
	ds_write2_b32 v31, v52, v53 offset1:1
	ds_write2_b32 v19, v54, v55 offset1:1
	v_add_u32_e32 v19, 0x18c0, v17
	v_add_u32_e32 v3, 0x18c8, v17
	s_lshl_b64 s[10:11], s[30:31], 1
	s_add_u32 s10, s22, s10
	s_addc_u32 s11, s23, s11
	s_waitcnt vmcnt(1) lgkmcnt(6)
	v_pk_mul_f32 v[22:23], v[22:23], v[30:31] op_sel_hi:[1,0]
	ds_write2_b32 v19, v22, v23 offset1:1
	v_pk_mul_f32 v[22:23], v[24:25], v[30:31] op_sel_hi:[1,0]
	ds_write2_b32 v3, v22, v23 offset1:1
	s_waitcnt vmcnt(0)
	v_pk_mul_f32 v[22:23], v[26:27], v[32:33] op_sel_hi:[1,0]
	v_add_u32_e32 v3, 0x1ce0, v17
	ds_write2_b32 v3, v22, v23 offset1:1
	v_pk_mul_f32 v[22:23], v[28:29], v[32:33] op_sel_hi:[1,0]
	v_add_u32_e32 v3, 0x1ce8, v17
	ds_write2_b32 v3, v22, v23 offset1:1
	s_waitcnt lgkmcnt(0)
	ds_read2_b32 v[26:27], v16 offset0:33 offset1:41
	ds_read2_b32 v[28:29], v16 offset1:8
	ds_read2_b32 v[30:31], v16 offset0:66 offset1:74
	ds_read2_b32 v[32:33], v16 offset0:99 offset1:107
	ds_read2_b32 v[34:35], v16 offset0:132 offset1:140
	ds_read2_b32 v[36:37], v16 offset0:165 offset1:173
	ds_read2_b32 v[38:39], v16 offset0:198 offset1:206
	ds_read2_b32 v[40:41], v16 offset0:231 offset1:239
	v_mov_b32_e32 v3, v1
	v_or_b32_e32 v19, s16, v4
	v_mad_i64_i32 v[42:43], s[22:23], v19, s4, 0
	v_lshl_add_u64 v[44:45], s[10:11], 0, v[2:3]
	s_waitcnt lgkmcnt(6)
	v_cvt_pk_bf16_f32 v22, v28, v26
	s_waitcnt lgkmcnt(4)
	v_cvt_pk_bf16_f32 v23, v30, v32
	s_waitcnt lgkmcnt(2)
	v_cvt_pk_bf16_f32 v24, v34, v36
	s_waitcnt lgkmcnt(0)
	v_cvt_pk_bf16_f32 v25, v38, v40
	v_lshl_add_u64 v[42:43], v[42:43], 1, v[44:45]
	v_or_b32_e32 v3, s16, v6
	global_store_dwordx4 v[42:43], v[22:25], off sc1
	s_nop 1
	v_cvt_pk_bf16_f32 v22, v29, v27
	v_mad_i64_i32 v[26:27], s[10:11], v3, s4, 0
	v_cvt_pk_bf16_f32 v23, v31, v33
	v_cvt_pk_bf16_f32 v24, v35, v37
	v_cvt_pk_bf16_f32 v25, v39, v41
	v_lshl_add_u64 v[26:27], v[26:27], 1, v[44:45]
	ds_read2_b32 v[28:29], v16 offset0:16 offset1:24
	ds_read2_b32 v[30:31], v16 offset0:49 offset1:57
	ds_read2_b32 v[32:33], v16 offset0:82 offset1:90
	ds_read2_b32 v[34:35], v16 offset0:115 offset1:123
	ds_read2_b32 v[36:37], v16 offset0:148 offset1:156
	ds_read2_b32 v[38:39], v16 offset0:181 offset1:189
	global_store_dwordx4 v[26:27], v[22:25], off sc1
	ds_read2_b32 v[26:27], v16 offset0:214 offset1:222
	ds_read2_b32 v[40:41], v16 offset0:247 offset1:255
	v_or_b32_e32 v3, s16, v8
	v_mad_i64_i32 v[42:43], s[10:11], v3, s4, 0
	s_waitcnt lgkmcnt(6)
	v_cvt_pk_bf16_f32 v22, v28, v30
	s_waitcnt lgkmcnt(4)
	v_cvt_pk_bf16_f32 v23, v32, v34
	s_waitcnt lgkmcnt(2)
	v_cvt_pk_bf16_f32 v24, v36, v38
	s_waitcnt lgkmcnt(0)
	v_cvt_pk_bf16_f32 v25, v26, v40
	v_lshl_add_u64 v[42:43], v[42:43], 1, v[44:45]
	v_or_b32_e32 v3, s16, v10
	global_store_dwordx4 v[42:43], v[22:25], off sc1
	s_nop 1
	v_cvt_pk_bf16_f32 v25, v27, v41
	v_mad_i64_i32 v[26:27], s[4:5], v3, s4, 0
	v_cvt_pk_bf16_f32 v22, v29, v31
	v_cvt_pk_bf16_f32 v23, v33, v35
	v_cvt_pk_bf16_f32 v24, v37, v39
	v_lshl_add_u64 v[26:27], v[26:27], 1, v[44:45]
	global_store_dwordx4 v[26:27], v[22:25], off sc1
	v_readlane_b32 s4, v254, 49
	s_waitcnt lgkmcnt(0)
	s_add_i32 s1, s1, s4
	s_cmp_lt_i32 s1, s43
	v_readlane_b32 s5, v254, 50
	s_cbranch_scc0 .LBB0_759

.LBB0_782:
	v_readlane_b32 s4, v255, 32
	v_readlane_b32 s5, v255, 33
	s_add_i32 s4, s4, 1
	s_cmp_ge_i32 s4, s5
	v_readlane_b32 s10, v255, 20
	s_mov_b64 s[38:39], s[4:5]
	s_cselect_b64 s[4:5], -1, 0
	v_readlane_b32 s11, v255, 21
	s_or_b64 s[4:5], s[4:5], s[10:11]
	v_readlane_b32 s10, v255, 16
	v_readlane_b32 s11, v255, 17
	s_or_b64 s[4:5], s[4:5], s[10:11]
	s_andn2_b64 vcc, exec, s[4:5]
	s_cbranch_vccnz .LBB0_783
.Lpb_nobar:
	s_getpc_b64 s[98:99]

.LBB0_783:
	v_readlane_b32 s4, v255, 32
	v_readlane_b32 s5, v254, 58
	s_nop 1
	s_cmp_eq_u32 s5, 0x100
	s_cbranch_scc0 .Lpb_grid
	s_lshl_b32 s5, 1, s4
	s_and_b32 s5, s5, 0x13130
	s_cbranch_scc0 .Lpb_grid
	s_waitcnt vmcnt(0) lgkmcnt(0)
	s_barrier
	v_readlane_b32 s10, v251, 7
	s_nop 1
	s_cmp_lg_u32 s10, 0
	s_cbranch_scc1 .Lpb_wait
	s_mov_b64 s[44:45], exec
	s_mov_b64 exec, 1
	v_readlane_b32 s10, v254, 56
	v_readlane_b32 s11, v254, 57
	v_readlane_b32 s22, v254, 54
	s_nop 1
	s_load_dwordx2 s[16:17], s[10:11], 0xf0
	s_and_b32 s23, s22, 7
	s_lshl_b32 s23, s23, 3
	s_bfe_u32 s22, s22, 0x30003
	s_add_i32 s23, s23, s22
	s_lshl_b32 s23, s23, 8
	s_lshl_b32 s22, s4, 2
	s_add_i32 s23, s23, s22
	v_mov_b32_e32 v0, 1
	v_mov_b32_e32 v2, 0
	s_waitcnt lgkmcnt(0)
	s_add_u32 s16, s16, 0xee04000
	s_addc_u32 s17, s17, 0
	s_add_u32 s16, s16, s23
	s_addc_u32 s17, s17, 0
	global_atomic_add v2, v0, s[16:17]
	s_mov_b32 s22, 0
.Lpb_spin:
	global_load_dword v3, v2, s[16:17] sc1
	s_waitcnt vmcnt(0)
	v_readfirstlane_b32 s23, v3
	s_nop 1
	s_cmp_ge_u32 s23, 4
	s_cbranch_scc1 .Lpb_done
	s_sleep 1
	s_add_i32 s22, s22, 1
	s_cmp_lt_u32 s22, 0x40000
	s_cbranch_scc1 .Lpb_spin
.Lpb_done:
	buffer_inv sc1
	s_waitcnt vmcnt(0)
	s_mov_b64 exec, s[44:45]
.Lpb_wait:
	s_barrier
	s_branch .Lpb_nobar
